# in-proj epilogue loads each row sum-of-squares once per tile; diff attention loops fetch the next step's first K fragments right after the barrier (under the PV tail MFMAs)
# speedup vs baseline: 1.0589x; 1.0061x over previous
; #define A_LOAD(t, rk, rv) do { const size_t kb_ = (size_t)(t) * 64; \
;     _Pragma("unroll") for (int s = 0; s < NK; ++s) _Pragma("unroll") for (int i = 0; i < KI; ++i) rk[s][i] = *(const u32x4*)(J.k[s] + (kb_ + ksrow + 32 * i) * J.ldk + ksch * 8); \
;     _Pragma("unroll") for (int i = 0; i < VI; ++i) rv[i] = *(const u32x4*)(J.v + (kb_ + vkey0 + (STN / VCH) * i) * J.ldv + vc8); } while (0)
; template <int DV, int NK, int MODE, bool FIXM, int GRP>
; DI void attn_job(char* lds_wg, const AttnJob& J) {
;     ...
;   bf16x8 qf[4];
;   const bf16_t* qrow = J.q + (size_t)r * UW + 8 * h;
; #pragma unroll
;   for (int ds = 0; ds < 4; ++ds) qf[ds] = *(const bf16x8*)(qrow + 16 * ds);
;   f32x16 O[NDV];
; #pragma unroll
;   for (int d = 0; d < NDV; ++d)
; #pragma unroll
;     for (int i = 0; i < 16; ++i) O[d][i] = 0.f;
;   float m = J.m_init, l = (h == 0) ? J.l_init : 0.f;
;   f32x16 Osum;
; #pragma unroll
;   for (int i = 0; i < 16; ++i) Osum[i] = 0.f;
;   const bf16x8 ones = {0x3F80, 0x3F80, 0x3F80, 0x3F80, 0x3F80, 0x3F80, 0x3F80, 0x3F80};
;   constexpr int KI = 512 / STN;
;   const int ksrow = st_ >> 3, ksch = st_ & 7;
;   const int kpi = (ksrow & ~12) | ((ksrow & 4) << 1) | ((ksrow & 8) >> 1);
;   const int ksoff = kpi * 128 + ((ksch ^ ((kpi >> 1) & 7)) << 4);
;   constexpr int VCH = DV / 8;
;   constexpr int VI = (64 * VCH) / STN;
;   const int vkey0 = st_ / VCH, vc8 = (st_ % VCH) * 8;
;   u32x4 rk0[NK][KI], rv0[VI], rk1[NK][KI], rv1[VI];
;     ...
;   const int nt = J.tile_hi - J.tile_lo;
;   constexpr bool DEEP2 = FIXM || MODE != AM_DIFF;
;   constexpr bool ONESET = FIXM;
;   A_LOAD(J.tile_lo, rk0, rv0); A_WRITE(0, rk0, rv0); if (ONESET) A_LOAD(J.tile_lo + 1, rk0, rv0); else if (DEEP2) A_LOAD(J.tile_lo + 1, rk1, rv1); __syncthreads();
.LBB0_320:
	s_andn2_b64 vcc, exec, s[70:71]
	s_cbranch_vccnz .LBB0_292
	s_add_u32 s70, s68, 0xa00
	s_addc_u32 s71, s69, 0
	s_add_u32 s72, s68, 0xa80
	s_addc_u32 s73, s69, 0
	s_and_b64 vcc, exec, s[4:5]
	s_mov_b64 s[4:5], -1
	s_cbranch_vccnz .LBB0_338
	v_mov_b32 v30, v212
	v_mov_b64_e32 v[2:3], s[68:69]
	v_ashrrev_i32_e32 v0, 31, v30
	v_lshrrev_b32_e32 v0, 28, v0
	v_add_u32_e32 v0, v30, v0
	v_ashrrev_i32_e32 v32, 4, v0
	v_and_b32_e32 v0, -16, v0
	v_sub_u32_e32 v33, v30, v0
	v_lshlrev_b32_e32 v10, 3, v33
	v_ashrrev_i32_e32 v11, 31, v10
	v_lshlrev_b64 v[20:21], 1, v[10:11]
	v_lshl_add_u64 v[10:11], s[68:69], 0, v[20:21]
	v_ashrrev_i32_e32 v31, 3, v30
	v_lshlrev_b32_e32 v34, 4, v30
	v_mad_i64_i32 v[22:23], s[4:5], v32, s13, v[10:11]
	v_mad_i64_i32 v[2:3], s[4:5], v31, s13, v[2:3]
	v_and_b32_e32 v18, 0x70, v34
	v_mov_b32_e32 v19, v1
	v_add_co_u32_e32 v14, vcc, s22, v22
	v_lshl_add_u64 v[6:7], v[2:3], 0, v[18:19]
	s_nop 0
	v_addc_co_u32_e32 v15, vcc, 0, v23, vcc
	global_load_dwordx4 v[2:5], v[6:7], off offset:2560
	s_nop 0
	global_load_dwordx4 v[6:9], v[6:7], off offset:2688
	s_nop 0
	global_load_dwordx4 v[10:13], v[22:23], off offset:3584
	s_nop 0
	global_load_dwordx4 v[14:17], v[14:15], off offset:3584
	v_mov_b64_e32 v[24:25], s[96:97]
	v_and_b32_e32 v146, 31, v30
	v_bfe_u32 v130, v30, 5, 1
	v_lshlrev_b32_e32 v28, 1, v31
	v_lshrrev_b32_e32 v29, 1, v31
	v_mad_u64_u32 v[24:25], s[4:5], v146, s13, v[24:25]
	v_lshlrev_b32_e32 v0, 4, v130
	v_and_b32_e32 v36, -13, v31
	v_mad_i64_i32 v[26:27], s[4:5], v31, s13, v[166:167]
	v_and_b32_e32 v37, 8, v28
	v_and_b32_e32 v38, 4, v29
	v_lshl_add_u64 v[24:25], v[24:25], 0, v[0:1]
	v_lshl_add_u64 v[28:29], s[70:71], 0, v[26:27]
	v_lshl_add_u64 v[26:27], s[72:73], 0, v[26:27]
	v_or3_b32 v36, v37, v36, v38
	global_load_dwordx4 v[98:101], v[24:25], off offset:1536
	global_load_dwordx4 v[102:105], v[24:25], off offset:1568
	global_load_dwordx4 v[106:109], v[24:25], off offset:1600
	global_load_dwordx4 v[110:113], v[24:25], off offset:1632
	v_lshl_add_u64 v[24:25], v[28:29], 0, v[18:19]
	v_lshl_add_u64 v[18:19], v[26:27], 0, v[18:19]
	v_lshrrev_b32_e32 v27, 1, v36
	v_lshlrev_b32_e32 v26, 7, v36
	v_lshrrev_b32_e32 v29, 1, v32
	v_add_u32_e32 v36, 32, v32
	global_load_dwordx4 v[114:117], v[24:25], off
	global_load_dwordx4 v[118:121], v[18:19], off
	v_xor_b32_e32 v18, v27, v30
	v_ashrrev_i32_e32 v19, 2, v33
	v_and_b32_e32 v25, 0x7ffffc, v29
	v_lshrrev_b32_e32 v27, 1, v36
	v_lshlrev_b32_e32 v18, 4, v18
	v_add_lshl_u32 v140, v25, v19, 9
	v_and_b32_e32 v25, 0x7ffffc, v27
	v_and_or_b32 v141, v18, s12, v26
	v_add_co_u32_e32 v18, vcc, s34, v22
	v_add_lshl_u32 v143, v25, v19, 9
	s_nop 0
	v_addc_co_u32_e32 v19, vcc, 0, v23, vcc
	v_add_co_u32_e32 v22, vcc, s20, v22
	v_lshlrev_b32_e32 v24, 4, v33
	s_nop 0
	v_addc_co_u32_e32 v23, vcc, 0, v23, vcc
	global_load_dwordx4 v[122:125], v[18:19], off offset:3584
	global_load_dwordx4 v[126:129], v[22:23], off offset:3584
	v_lshlrev_b32_e32 v28, 6, v32
	v_and_b32_e32 v24, 48, v24
	v_and_or_b32 v142, v28, s6, v24
	v_or_b32_e32 v24, v142, v140
	v_or_b32_e32 v25, v142, v143
	v_lshrrev_b32_e32 v35, 5, v30
	v_readfirstlane_b32 s38, v30
	s_lshl_b32 s4, s38, 7
	s_and_b32 s4, s4, 0x2000
	v_readlane_b32 s44, v254, 33
	v_readlane_b32 s48, v254, 37
	v_readlane_b32 s49, v254, 38
	v_mov_b32_e32 v150, 0
	s_mov_b32 s41, 0
	s_lshr_b32 s39, s38, 6
	v_mov_b32_e32 v18, 0
	v_mov_b32_e32 v19, v150
	v_mov_b32_e32 v22, v150
	v_mov_b32_e32 v23, v150
	v_mov_b32_e32 v26, v150
	v_mov_b32_e32 v27, v150
	s_waitcnt vmcnt(11)
	ds_write_b128 v141, v[2:5]
	s_waitcnt vmcnt(10)
	ds_write_b128 v141, v[6:9] offset:8192
	s_waitcnt vmcnt(9)
	ds_write_b128 v24, v[10:13] offset:16384
	s_waitcnt vmcnt(8)
	ds_write_b128 v25, v[14:17] offset:16384
	v_lshlrev_b32_e32 v4, 2, v30
	v_and_b32_e32 v5, 16, v30
	v_and_or_b32 v4, v4, 12, v5
	v_lshlrev_b32_e32 v2, 11, v130
	v_and_b32_e32 v3, 0xc0, v34
	v_lshlrev_b32_e32 v4, 1, v4
	v_or3_b32 v144, v2, v3, v4
	v_bfe_u32 v2, v30, 1, 3
	v_bitop3_b32 v3, v35, v2, 1 bitop3:0x6c
	v_lshlrev_b32_e32 v7, 4, v3
	v_bitop3_b32 v3, v130, v2, 2 bitop3:0x36
	v_lshlrev_b32_e32 v8, 4, v3
	v_bitop3_b32 v3, v130, v2, 4 bitop3:0x36
	v_bitop3_b32 v2, v130, v2, 6 bitop3:0x36
	v_lshl_or_b32 v6, v146, 7, s4
	v_lshlrev_b32_e32 v9, 4, v3
	v_lshlrev_b32_e32 v10, 4, v2
	s_and_b32 s4, s87, 3
	v_mov_b64_e32 v[2:3], s[2:3]
	s_lshl_b32 s14, s4, 8
	v_mad_i64_i32 v[4:5], s[4:5], v32, s13, v[2:3]
	v_lshl_add_u64 v[4:5], v[4:5], 0, v[20:21]
	v_lshl_add_u64 v[132:133], s[48:49], 0, v[4:5]
	v_and_b32_e32 v4, 7, v30
	v_mad_i64_i32 v[2:3], s[4:5], v31, s13, v[2:3]
	v_lshlrev_b32_e32 v4, 4, v4
	v_mov_b32_e32 v5, v1
	v_lshl_add_u64 v[2:3], v[2:3], 0, v[4:5]
	v_lshl_add_u64 v[134:135], s[48:49], 0, v[2:3]
	v_add_u32_e32 v145, v6, v7
	v_add_u32_e32 v147, v6, v8
	v_add_u32_e32 v148, v6, v9
	v_add_u32_e32 v149, v6, v10
	v_mov_b32_e32 v2, 0
	v_mov_b32_e32 v3, v150
	v_mov_b32_e32 v4, v150
	v_mov_b32_e32 v5, v150
	v_mov_b32_e32 v6, v150
	v_mov_b32_e32 v7, v150
	v_mov_b32_e32 v8, v150
	v_mov_b32_e32 v9, v150
	v_mov_b32_e32 v10, v150
	v_mov_b32_e32 v11, v150
	v_mov_b32_e32 v12, v150
	v_mov_b32_e32 v13, v150
	v_mov_b32_e32 v14, v150
	v_mov_b32_e32 v15, v150
	v_mov_b32_e32 v16, v150
	v_mov_b32_e32 v17, v150
	v_mov_b32_e32 v20, v150
	v_mov_b32_e32 v21, v150
	v_mov_b32_e32 v24, v150
	v_mov_b32_e32 v25, v150
	v_mov_b32_e32 v28, v150
	v_mov_b32_e32 v29, v150
	v_mov_b32_e32 v30, v150
	v_mov_b32_e32 v31, v150
	v_mov_b32_e32 v32, v150
	v_mov_b32_e32 v33, v150
	v_mov_b32_e32 v34, 0
	v_mov_b32_e32 v35, v150
	v_mov_b32_e32 v36, v150
	v_mov_b32_e32 v37, v150
	v_mov_b32_e32 v38, v150
	v_mov_b32_e32 v39, v150
	v_mov_b32_e32 v40, v150
	v_mov_b32_e32 v41, v150
	v_mov_b32_e32 v42, v150
	v_mov_b32_e32 v43, v150
	v_mov_b32_e32 v44, v150
	v_mov_b32_e32 v45, v150
	v_mov_b32_e32 v46, v150
	v_mov_b32_e32 v47, v150
	v_mov_b32_e32 v48, v150
	v_mov_b32_e32 v49, v150
	v_mov_b32_e32 v50, 0
	v_mov_b32_e32 v51, v150
	v_mov_b32_e32 v52, v150
	v_mov_b32_e32 v53, v150
	v_mov_b32_e32 v54, v150
	v_mov_b32_e32 v55, v150
	v_mov_b32_e32 v56, v150
	v_mov_b32_e32 v57, v150
	v_mov_b32_e32 v58, v150
	v_mov_b32_e32 v59, v150
	v_mov_b32_e32 v60, v150
	v_mov_b32_e32 v61, v150
	v_mov_b32_e32 v62, v150
	v_mov_b32_e32 v63, v150
	v_mov_b32_e32 v64, v150
	v_mov_b32_e32 v65, v150
	s_waitcnt lgkmcnt(0)
	s_barrier
; template <int DV, int NK, int MODE, bool FIXM, int GRP>
; DI void attn_job(char* lds_wg, const AttnJob& J) {
;     ...
;   bf16x8 qf[4];
;   const bf16_t* qrow = J.q + (size_t)r * UW + 8 * h;
; #pragma unroll
;   for (int ds = 0; ds < 4; ++ds) qf[ds] = *(const bf16x8*)(qrow + 16 * ds);
;     ...
;         bf16x8 ka[4], kb[4];
; #pragma unroll
;         for (int ds = 0; ds < 4; ++ds) { const int co = ((2 * ds + h) ^ ((r >> 1) & 7)) << 4; ka[ds] = *(const bf16x8*)(Kl + co); kb[ds] = *(const bf16x8*)(Kl + 4096 + co); }
	v_readlane_b32 s45, v254, 34
	v_readlane_b32 s46, v254, 35
	v_readlane_b32 s47, v254, 36
	v_readlane_b32 s50, v254, 39
	v_readlane_b32 s51, v254, 40
	v_readlane_b32 s52, v254, 41
	v_readlane_b32 s53, v254, 42
	v_readlane_b32 s54, v254, 43
	v_readlane_b32 s55, v254, 44
	v_readlane_b32 s56, v254, 45
	v_readlane_b32 s57, v254, 46
	v_readlane_b32 s58, v254, 47
	v_readlane_b32 s59, v254, 48
	s_waitcnt vmcnt(4)
	v_lshlrev_b32_e32 v82, 16, v98
	v_and_b32_e32 v83, 0xffff0000, v98
	v_mul_f32_e32 v82, s7, v82
	v_mul_f32_e32 v83, s7, v83
	v_cvt_pk_bf16_f32 v98, v82, v83
	v_lshlrev_b32_e32 v82, 16, v99
	v_and_b32_e32 v83, 0xffff0000, v99
	v_mul_f32_e32 v82, s7, v82
	v_mul_f32_e32 v83, s7, v83
	v_cvt_pk_bf16_f32 v99, v82, v83
	v_lshlrev_b32_e32 v82, 16, v100
	v_and_b32_e32 v83, 0xffff0000, v100
	v_mul_f32_e32 v82, s7, v82
	v_mul_f32_e32 v83, s7, v83
	v_cvt_pk_bf16_f32 v100, v82, v83
	v_lshlrev_b32_e32 v82, 16, v101
	v_and_b32_e32 v83, 0xffff0000, v101
	v_mul_f32_e32 v82, s7, v82
	v_mul_f32_e32 v83, s7, v83
	v_cvt_pk_bf16_f32 v101, v82, v83
	v_lshlrev_b32_e32 v82, 16, v102
	v_and_b32_e32 v83, 0xffff0000, v102
	v_mul_f32_e32 v82, s7, v82
	v_mul_f32_e32 v83, s7, v83
	v_cvt_pk_bf16_f32 v102, v82, v83
	v_lshlrev_b32_e32 v82, 16, v103
	v_and_b32_e32 v83, 0xffff0000, v103
	v_mul_f32_e32 v82, s7, v82
	v_mul_f32_e32 v83, s7, v83
	v_cvt_pk_bf16_f32 v103, v82, v83
	v_lshlrev_b32_e32 v82, 16, v104
	v_and_b32_e32 v83, 0xffff0000, v104
	v_mul_f32_e32 v82, s7, v82
	v_mul_f32_e32 v83, s7, v83
	v_cvt_pk_bf16_f32 v104, v82, v83
	v_lshlrev_b32_e32 v82, 16, v105
	v_and_b32_e32 v83, 0xffff0000, v105
	v_mul_f32_e32 v82, s7, v82
	v_mul_f32_e32 v83, s7, v83
	v_cvt_pk_bf16_f32 v105, v82, v83
	v_lshlrev_b32_e32 v82, 16, v106
	v_and_b32_e32 v83, 0xffff0000, v106
	v_mul_f32_e32 v82, s7, v82
	v_mul_f32_e32 v83, s7, v83
	v_cvt_pk_bf16_f32 v106, v82, v83
	v_lshlrev_b32_e32 v82, 16, v107
	v_and_b32_e32 v83, 0xffff0000, v107
	v_mul_f32_e32 v82, s7, v82
	v_mul_f32_e32 v83, s7, v83
	v_cvt_pk_bf16_f32 v107, v82, v83
	v_lshlrev_b32_e32 v82, 16, v108
	v_and_b32_e32 v83, 0xffff0000, v108
	v_mul_f32_e32 v82, s7, v82
	v_mul_f32_e32 v83, s7, v83
	v_cvt_pk_bf16_f32 v108, v82, v83
	v_lshlrev_b32_e32 v82, 16, v109
	v_and_b32_e32 v83, 0xffff0000, v109
	v_mul_f32_e32 v82, s7, v82
	v_mul_f32_e32 v83, s7, v83
	v_cvt_pk_bf16_f32 v109, v82, v83
	v_lshlrev_b32_e32 v82, 16, v110
	v_and_b32_e32 v83, 0xffff0000, v110
	v_mul_f32_e32 v82, s7, v82
	v_mul_f32_e32 v83, s7, v83
	v_cvt_pk_bf16_f32 v110, v82, v83
	v_lshlrev_b32_e32 v82, 16, v111
	v_and_b32_e32 v83, 0xffff0000, v111
	v_mul_f32_e32 v82, s7, v82
	v_mul_f32_e32 v83, s7, v83
	v_cvt_pk_bf16_f32 v111, v82, v83
	v_lshlrev_b32_e32 v82, 16, v112
	v_and_b32_e32 v83, 0xffff0000, v112
	v_mul_f32_e32 v82, s7, v82
	v_mul_f32_e32 v83, s7, v83
	v_cvt_pk_bf16_f32 v112, v82, v83
	v_lshlrev_b32_e32 v82, 16, v113
	v_and_b32_e32 v83, 0xffff0000, v113
	v_mul_f32_e32 v82, s7, v82
	v_mul_f32_e32 v83, s7, v83
	v_cvt_pk_bf16_f32 v113, v82, v83
	ds_read_b128 v[234:237], v145
	ds_read_b128 v[238:241], v145 offset:4096
	ds_read_b128 v[242:245], v147
	ds_read_b128 v[246:249], v147 offset:4096

; template <int DV, int NK, int MODE, bool FIXM, int GRP>
; DI void attn_job(char* lds_wg, const AttnJob& J) {
;     ...
;       if (NDV == 2 || FIXM) {
;         bf16x8 ka[4], kb[4];
; #pragma unroll
;         for (int ds = 0; ds < 4; ++ds) { const int co = ((2 * ds + h) ^ ((r >> 1) & 7)) << 4; ka[ds] = *(const bf16x8*)(Kl + co); kb[ds] = *(const bf16x8*)(Kl + 4096 + co); }
; #pragma unroll
;         for (int ds = 0; ds < 4; ++ds) { sA = MFMA32(ka[ds], qf[ds], sA); sB = MFMA32(kb[ds], qf[ds], sB); }
;         __builtin_amdgcn_sched_group_barrier(0x100, 4, 0); __builtin_amdgcn_sched_group_barrier(0x008, 2, 0);
;         __builtin_amdgcn_sched_group_barrier(0x100, 2, 0); __builtin_amdgcn_sched_group_barrier(0x008, 2, 0);
;         __builtin_amdgcn_sched_group_barrier(0x100, 2, 0); __builtin_amdgcn_sched_group_barrier(0x008, 4, 0);
;       } else {
; #pragma unroll
;         for (int ds = 0; ds < 4; ++ds) {
;           const int co = ((2 * ds + h) ^ ((r >> 1) & 7)) << 4;
;           const bf16x8 ka = *(const bf16x8*)(Kl + co), kb = *(const bf16x8*)(Kl + 4096 + co);
;           sA = MFMA32(ka, qf[ds], sA); sB = MFMA32(kb, qf[ds], sB);
;         }
;       }
;       if (MODE == AM_SWA) {
;         const int qa = J.qpos0 + r, kbase = tile * 64 + 8 * h;
; #pragma unroll
;         for (int i = 0; i < 16; ++i) {
;           const int ka_ = kbase + 16 * (i >> 3) + (i & 7);
;           int d0 = qa - ka_; d0 = d0 < 0 ? -d0 : d0; if (d0 > 128) sA[i] = -INFINITY;
;           int d1 = qa - (ka_ + 32); d1 = d1 < 0 ? -d1 : d1; if (d1 > 128) sB[i] = -INFINITY;
;         }
;       }
;       if (FIXM) {
;         const float nm = -J.m_init;
; #pragma unroll
;         for (int i = 0; i < 16; ++i) { sA[i] = __builtin_amdgcn_exp2f(fmaf(sA[i], C, nm)); sB[i] = __builtin_amdgcn_exp2f(fmaf(sB[i], C, nm)); l += sA[i] + sB[i]; }
;     ...
;       bf16x8 pf[4];
;       { u32x4 w;
;         w.x = cvtpk(sA[0], sA[1]); w.y = cvtpk(sA[2], sA[3]); w.z = cvtpk(sA[4], sA[5]); w.w = cvtpk(sA[6], sA[7]); pf[0] = __builtin_bit_cast(bf16x8, w);
;         w.x = cvtpk(sA[8], sA[9]); w.y = cvtpk(sA[10], sA[11]); w.z = cvtpk(sA[12], sA[13]); w.w = cvtpk(sA[14], sA[15]); pf[1] = __builtin_bit_cast(bf16x8, w);
;         w.x = cvtpk(sB[0], sB[1]); w.y = cvtpk(sB[2], sB[3]); w.z = cvtpk(sB[4], sB[5]); w.w = cvtpk(sB[6], sB[7]); pf[2] = __builtin_bit_cast(bf16x8, w);
.LBB0_325:
	s_andn2_b64 vcc, exec, s[74:75]
	s_waitcnt lgkmcnt(7)
	v_mfma_f32_32x32x16_bf16 v[82:97], v[234:237], v[98:101], 0
	s_waitcnt lgkmcnt(6)
	v_mfma_f32_32x32x16_bf16 v[66:81], v[238:241], v[98:101], 0
	ds_read_b128 v[162:165], v148
	ds_read_b128 v[174:177], v148 offset:4096
	s_waitcnt lgkmcnt(7)
	v_mfma_f32_32x32x16_bf16 v[82:97], v[242:245], v[102:105], v[82:97]
	s_waitcnt lgkmcnt(6)
	v_mfma_f32_32x32x16_bf16 v[66:81], v[246:249], v[102:105], v[66:81]
	ds_read_b128 v[154:157], v149
	ds_read_b128 v[158:161], v149 offset:4096
	s_waitcnt lgkmcnt(3)
	v_mfma_f32_32x32x16_bf16 v[82:97], v[162:165], v[106:109], v[82:97]
	s_waitcnt lgkmcnt(1)
	v_mfma_f32_32x32x16_bf16 v[82:97], v[154:157], v[110:113], v[82:97]
	v_mfma_f32_32x32x16_bf16 v[66:81], v[174:177], v[106:109], v[66:81]
	s_nop 10
	v_exp_f32_e32 v153, v82
	v_exp_f32_e32 v154, v83
	v_exp_f32_e32 v155, v84
	v_exp_f32_e32 v156, v85
	s_waitcnt lgkmcnt(0)
	v_mfma_f32_32x32x16_bf16 v[66:81], v[158:161], v[110:113], v[66:81]
	v_exp_f32_e32 v158, v86
	v_exp_f32_e32 v157, v87
	v_exp_f32_e32 v159, v88
	v_exp_f32_e32 v160, v89
	ds_read_b64_tr_b16 v[86:87], v144 offset:16384
	ds_read_b64_tr_b16 v[88:89], v144 offset:16640
	ds_read_b64_tr_b16 v[174:175], v144 offset:16896
	ds_read_b64_tr_b16 v[176:177], v144 offset:17152
	ds_read_b64_tr_b16 v[178:179], v144 offset:17408
	ds_read_b64_tr_b16 v[180:181], v144 offset:17664
	ds_read_b64_tr_b16 v[182:183], v144 offset:17920
	ds_read_b64_tr_b16 v[184:185], v144 offset:18176
	v_cvt_pk_bf16_f32 v82, v153, v154
	v_cvt_pk_bf16_f32 v83, v155, v156
	v_cvt_pk_bf16_f32 v84, v158, v157
	v_cvt_pk_bf16_f32 v85, v159, v160
	ds_read_b64_tr_b16 v[186:187], v144 offset:20480
	ds_read_b64_tr_b16 v[188:189], v144 offset:20736
	ds_read_b64_tr_b16 v[190:191], v144 offset:20992
	ds_read_b64_tr_b16 v[192:193], v144 offset:21248
	ds_read_b64_tr_b16 v[194:195], v144 offset:21504
	ds_read_b64_tr_b16 v[196:197], v144 offset:21760
	ds_read_b64_tr_b16 v[198:199], v144 offset:22016
	ds_read_b64_tr_b16 v[200:201], v144 offset:22272
	s_waitcnt lgkmcnt(14)
	v_mfma_f32_32x32x16_bf16 v[50:65], v[86:89], v[82:85], v[50:65]
	v_exp_f32_e32 v168, v90
	v_exp_f32_e32 v162, v91
	v_exp_f32_e32 v163, v92
	v_exp_f32_e32 v169, v93
	s_waitcnt lgkmcnt(12)
	v_mfma_f32_32x32x16_bf16 v[34:49], v[174:177], v[82:85], v[34:49]
	v_exp_f32_e32 v164, v94
	v_exp_f32_e32 v165, v95
	v_exp_f32_e32 v170, v96
	v_exp_f32_e32 v161, v97
	s_waitcnt lgkmcnt(10)
	v_mfma_f32_32x32x16_bf16 v[18:33], v[178:181], v[82:85], v[18:33]
	v_exp_f32_e32 v176, v66
	v_exp_f32_e32 v177, v67
	v_exp_f32_e32 v178, v68
	s_waitcnt lgkmcnt(8)
	v_mfma_f32_32x32x16_bf16 v[2:17], v[182:185], v[82:85], v[2:17]
	v_cvt_pk_bf16_f32 v86, v168, v162
	v_cvt_pk_bf16_f32 v87, v163, v169
	v_cvt_pk_bf16_f32 v88, v164, v165
	v_cvt_pk_bf16_f32 v89, v170, v161
	ds_read_b64_tr_b16 v[82:83], v144 offset:24576
	ds_read_b64_tr_b16 v[84:85], v144 offset:24832
	ds_read_b64_tr_b16 v[90:91], v144 offset:25088
	ds_read_b64_tr_b16 v[92:93], v144 offset:25344
	ds_read_b64_tr_b16 v[94:95], v144 offset:25600
	ds_read_b64_tr_b16 v[96:97], v144 offset:25856
	ds_read_b64_tr_b16 v[202:203], v144 offset:26112
	ds_read_b64_tr_b16 v[204:205], v144 offset:26368
	v_exp_f32_e32 v179, v69
	s_waitcnt lgkmcnt(14)
	v_mfma_f32_32x32x16_bf16 v[50:65], v[186:189], v[86:89], v[50:65]
	v_exp_f32_e32 v180, v70
	v_exp_f32_e32 v173, v71
	v_exp_f32_e32 v174, v72
	v_exp_f32_e32 v175, v73
	s_waitcnt lgkmcnt(12)
	v_mfma_f32_32x32x16_bf16 v[34:49], v[190:193], v[86:89], v[34:49]
	v_exp_f32_e32 v186, v74
	v_exp_f32_e32 v182, v75
	v_cvt_pk_bf16_f32 v66, v176, v177
	v_cvt_pk_bf16_f32 v67, v178, v179
	s_waitcnt lgkmcnt(10)
	v_mfma_f32_32x32x16_bf16 v[18:33], v[194:197], v[86:89], v[18:33]
	v_cvt_pk_bf16_f32 v68, v180, v173
	v_cvt_pk_bf16_f32 v69, v174, v175
	v_exp_f32_e32 v183, v76
	v_exp_f32_e32 v187, v77
	v_exp_f32_e32 v184, v78
	s_waitcnt lgkmcnt(8)
	v_mfma_f32_32x32x16_bf16 v[2:17], v[198:201], v[86:89], v[2:17]
	ds_read_b64_tr_b16 v[70:71], v144 offset:28672
	ds_read_b64_tr_b16 v[72:73], v144 offset:28928
	ds_read_b64_tr_b16 v[86:87], v144 offset:29184
	ds_read_b64_tr_b16 v[88:89], v144 offset:29440
	ds_read_b64_tr_b16 v[190:191], v144 offset:29696
	ds_read_b64_tr_b16 v[192:193], v144 offset:29952
	ds_read_b64_tr_b16 v[194:195], v144 offset:30208
	ds_read_b64_tr_b16 v[196:197], v144 offset:30464
	s_waitcnt lgkmcnt(14)
	v_mfma_f32_32x32x16_bf16 v[50:65], v[82:85], v[66:69], v[50:65]
	v_exp_f32_e32 v185, v79
	v_exp_f32_e32 v188, v80
	s_waitcnt lgkmcnt(0)
	s_barrier
	ds_read_b128 v[234:237], v145 offset:32768
	ds_read_b128 v[238:241], v145 offset:36864
	ds_read_b128 v[242:245], v147 offset:32768
	ds_read_b128 v[246:249], v147 offset:36864
	v_mfma_f32_32x32x16_bf16 v[34:49], v[90:93], v[66:69], v[34:49]
	v_mfma_f32_32x32x16_bf16 v[18:33], v[94:97], v[66:69], v[18:33]
	v_mfma_f32_32x32x16_bf16 v[2:17], v[202:205], v[66:69], v[2:17]
	v_exp_f32_e32 v181, v81
	v_cvt_pk_bf16_f32 v66, v186, v182
	v_cvt_pk_bf16_f32 v67, v183, v187
	v_cvt_pk_bf16_f32 v68, v184, v185
	v_cvt_pk_bf16_f32 v69, v188, v181
	s_nop 1
	v_mfma_f32_32x32x16_bf16 v[50:65], v[70:73], v[66:69], v[50:65]
	v_mfma_f32_32x32x16_bf16 v[34:49], v[86:89], v[66:69], v[34:49]
	v_mfma_f32_32x32x16_bf16 v[18:33], v[190:193], v[66:69], v[18:33]
	v_mfma_f32_32x32x16_bf16 v[2:17], v[194:197], v[66:69], v[2:17]
	s_cbranch_vccnz .LBB0_327
	s_waitcnt vmcnt(3)
	ds_write_b128 v141, v[114:117]
	s_waitcnt vmcnt(2)
	ds_write_b128 v141, v[118:121] offset:8192
	s_waitcnt vmcnt(1)
	ds_write_b128 v151, v[122:125] offset:16384
	s_waitcnt vmcnt(0)
	ds_write_b128 v152, v[126:129] offset:16384

; template <int DV, int NK, int MODE, bool FIXM, int GRP>
; DI void attn_job(char* lds_wg, const AttnJob& J) {
;     ...
;       if (NDV == 2 || FIXM) {
;         bf16x8 ka[4], kb[4];
; #pragma unroll
;         for (int ds = 0; ds < 4; ++ds) { const int co = ((2 * ds + h) ^ ((r >> 1) & 7)) << 4; ka[ds] = *(const bf16x8*)(Kl + co); kb[ds] = *(const bf16x8*)(Kl + 4096 + co); }
; #pragma unroll
;         for (int ds = 0; ds < 4; ++ds) { sA = MFMA32(ka[ds], qf[ds], sA); sB = MFMA32(kb[ds], qf[ds], sB); }
;         __builtin_amdgcn_sched_group_barrier(0x100, 4, 0); __builtin_amdgcn_sched_group_barrier(0x008, 2, 0);
;         __builtin_amdgcn_sched_group_barrier(0x100, 2, 0); __builtin_amdgcn_sched_group_barrier(0x008, 2, 0);
;         __builtin_amdgcn_sched_group_barrier(0x100, 2, 0); __builtin_amdgcn_sched_group_barrier(0x008, 4, 0);
;       } else {
; #pragma unroll
;         for (int ds = 0; ds < 4; ++ds) {
;           const int co = ((2 * ds + h) ^ ((r >> 1) & 7)) << 4;
;           const bf16x8 ka = *(const bf16x8*)(Kl + co), kb = *(const bf16x8*)(Kl + 4096 + co);
;           sA = MFMA32(ka, qf[ds], sA); sB = MFMA32(kb, qf[ds], sB);
;         }
;       }
;       if (MODE == AM_SWA) {
;         const int qa = J.qpos0 + r, kbase = tile * 64 + 8 * h;
; #pragma unroll
;         for (int i = 0; i < 16; ++i) {
;           const int ka_ = kbase + 16 * (i >> 3) + (i & 7);
;           int d0 = qa - ka_; d0 = d0 < 0 ? -d0 : d0; if (d0 > 128) sA[i] = -INFINITY;
;           int d1 = qa - (ka_ + 32); d1 = d1 < 0 ? -d1 : d1; if (d1 > 128) sB[i] = -INFINITY;
;         }
;       }
;       if (FIXM) {
;         const float nm = -J.m_init;
; #pragma unroll
;         for (int i = 0; i < 16; ++i) { sA[i] = __builtin_amdgcn_exp2f(fmaf(sA[i], C, nm)); sB[i] = __builtin_amdgcn_exp2f(fmaf(sB[i], C, nm)); l += sA[i] + sB[i]; }
;     ...
;       bf16x8 pf[4];
;       { u32x4 w;
;         w.x = cvtpk(sA[0], sA[1]); w.y = cvtpk(sA[2], sA[3]); w.z = cvtpk(sA[4], sA[5]); w.w = cvtpk(sA[6], sA[7]); pf[0] = __builtin_bit_cast(bf16x8, w);
;         w.x = cvtpk(sA[8], sA[9]); w.y = cvtpk(sA[10], sA[11]); w.z = cvtpk(sA[12], sA[13]); w.w = cvtpk(sA[14], sA[15]); pf[1] = __builtin_bit_cast(bf16x8, w);
;         w.x = cvtpk(sB[0], sB[1]); w.y = cvtpk(sB[2], sB[3]); w.z = cvtpk(sB[4], sB[5]); w.w = cvtpk(sB[6], sB[7]); pf[2] = __builtin_bit_cast(bf16x8, w);
.LBB0_329:
	v_lshl_add_u64 v[132:133], v[132:133], 0, s[94:95]
	v_lshl_add_u64 v[134:135], v[134:135], 0, s[94:95]
	s_and_b64 vcc, exec, s[4:5]
	s_waitcnt lgkmcnt(3)
	v_mfma_f32_32x32x16_bf16 v[82:97], v[234:237], v[98:101], 0
	s_waitcnt lgkmcnt(2)
	v_mfma_f32_32x32x16_bf16 v[66:81], v[238:241], v[98:101], 0
	ds_read_b128 v[194:197], v148 offset:32768
	ds_read_b128 v[198:201], v148 offset:36864
	s_waitcnt lgkmcnt(3)
	v_mfma_f32_32x32x16_bf16 v[82:97], v[242:245], v[102:105], v[82:97]
	v_add_f32_e32 v136, v153, v176
	v_add_f32_e32 v136, v150, v136
	v_add_f32_e32 v137, v154, v177
	v_add_f32_e32 v136, v137, v136
	v_add_f32_e32 v137, v155, v178
	v_add_f32_e32 v136, v137, v136
	v_add_f32_e32 v137, v156, v179
	s_waitcnt lgkmcnt(2)
	v_mfma_f32_32x32x16_bf16 v[66:81], v[246:249], v[102:105], v[66:81]
	v_add_f32_e32 v136, v137, v136
	v_add_f32_e32 v137, v158, v180
	v_add_f32_e32 v154, v137, v136
	ds_read_b128 v[136:139], v149 offset:32768
	ds_read_b128 v[150:153], v149 offset:36864
	v_add_f32_e32 v155, v157, v173
	v_add_f32_e32 v154, v155, v154
	s_waitcnt lgkmcnt(3)
	v_mfma_f32_32x32x16_bf16 v[82:97], v[194:197], v[106:109], v[82:97]
	v_add_f32_e32 v155, v159, v174
	v_add_f32_e32 v154, v155, v154
	v_add_f32_e32 v155, v160, v175
	v_add_f32_e32 v154, v155, v154
	v_add_f32_e32 v155, v168, v186
	v_add_f32_e32 v154, v155, v154
	v_add_f32_e32 v155, v162, v182
	s_waitcnt lgkmcnt(2)
	v_mfma_f32_32x32x16_bf16 v[66:81], v[198:201], v[106:109], v[66:81]
	v_add_f32_e32 v154, v155, v154
	v_add_f32_e32 v155, v163, v183
	v_add_f32_e32 v154, v155, v154
	v_add_f32_e32 v155, v169, v187
	v_add_f32_e32 v154, v155, v154
	s_waitcnt lgkmcnt(1)
	v_mfma_f32_32x32x16_bf16 v[82:97], v[136:139], v[110:113], v[82:97]
	v_add_f32_e32 v136, v164, v184
	v_add_f32_e32 v136, v136, v154
	v_add_f32_e32 v137, v165, v185
	v_add_f32_e32 v136, v137, v136
	v_add_f32_e32 v137, v170, v188
	s_nop 6
	s_waitcnt lgkmcnt(0)
	v_mfma_f32_32x32x16_bf16 v[66:81], v[150:153], v[110:113], v[66:81]
	v_exp_f32_e32 v82, v82
	v_exp_f32_e32 v83, v83
	ds_read_b64_tr_b16 v[138:139], v144 offset:50432
	ds_read_b64_tr_b16 v[150:151], v144 offset:50688
	ds_read_b64_tr_b16 v[152:153], v144 offset:50944
	ds_read_b64_tr_b16 v[154:155], v144 offset:53248
	s_nop 4
	v_exp_f32_e32 v170, v66
	v_exp_f32_e32 v173, v67
	v_add_f32_e32 v66, v137, v136
	v_add_f32_e32 v136, v161, v181
	v_exp_f32_e32 v67, v84
	v_exp_f32_e32 v181, v68
	v_add_f32_e32 v66, v136, v66
	v_add_f32_e32 v136, v82, v170
	v_add_f32_e32 v66, v66, v136
	v_add_f32_e32 v68, v83, v173
	v_add_f32_e32 v66, v68, v66
	v_add_f32_e32 v68, v67, v181
	v_add_f32_e32 v169, v68, v66
	v_exp_f32_e32 v179, v85
	v_exp_f32_e32 v183, v69
	v_exp_f32_e32 v185, v86
	v_exp_f32_e32 v187, v70
	v_exp_f32_e32 v70, v87
	v_exp_f32_e32 v188, v88
	v_exp_f32_e32 v168, v89
	v_cvt_pk_bf16_f32 v66, v82, v83
	ds_read_b64_tr_b16 v[82:83], v144 offset:49152
	ds_read_b64_tr_b16 v[84:85], v144 offset:49408
	v_exp_f32_e32 v178, v71
	ds_read_b64_tr_b16 v[86:87], v144 offset:49664
	ds_read_b64_tr_b16 v[88:89], v144 offset:49920
	v_exp_f32_e32 v189, v90
	ds_read_b64_tr_b16 v[136:137], v144 offset:50176
	v_exp_f32_e32 v180, v91
	v_exp_f32_e32 v190, v92
	v_exp_f32_e32 v182, v93
	v_exp_f32_e32 v191, v94
	v_exp_f32_e32 v184, v95
	v_cvt_pk_bf16_f32 v67, v67, v179
	v_cvt_pk_bf16_f32 v68, v185, v70
	v_cvt_pk_bf16_f32 v69, v188, v168
	ds_read_b64_tr_b16 v[156:157], v144 offset:53504
	v_exp_f32_e32 v192, v96
	ds_read_b64_tr_b16 v[158:159], v144 offset:53760
	ds_read_b64_tr_b16 v[160:161], v144 offset:54016
	ds_read_b64_tr_b16 v[162:163], v144 offset:54272
	ds_read_b64_tr_b16 v[164:165], v144 offset:54528
	ds_read_b64_tr_b16 v[174:175], v144 offset:54784
	ds_read_b64_tr_b16 v[176:177], v144 offset:55040
	s_waitcnt lgkmcnt(10)
	v_mfma_f32_32x32x16_bf16 v[50:65], v[82:85], v[66:69], v[50:65]
	v_exp_f32_e32 v186, v97
	v_add_f32_e32 v71, v179, v183
	v_add_f32_e32 v179, v71, v169
	v_add_f32_e32 v71, v185, v187
	v_pk_add_f32 v[70:71], v[70:71], v[178:179]
	v_cvt_pk_bf16_f32 v82, v189, v180
	v_cvt_pk_bf16_f32 v83, v190, v182
	s_waitcnt lgkmcnt(8)
	v_mfma_f32_32x32x16_bf16 v[34:49], v[86:89], v[66:69], v[34:49]
	v_cvt_pk_bf16_f32 v84, v191, v184
	v_cvt_pk_bf16_f32 v85, v192, v186
	s_waitcnt lgkmcnt(7)
	v_mfma_f32_32x32x16_bf16 v[18:33], v[136:139], v[66:69], v[18:33]
	v_add_f32_e64 v136, v70, v70
	v_add_f32_e64 v137, v70, v71
	v_exp_f32_e32 v138, v72
	v_exp_f32_e32 v136, v73
	v_cvt_pk_bf16_f32 v72, v187, v178
	v_add_f32_e32 v169, v188, v138
	v_mfma_f32_32x32x16_bf16 v[2:17], v[150:153], v[66:69], v[2:17]
	ds_read_b64_tr_b16 v[66:67], v144 offset:57344
	ds_read_b64_tr_b16 v[68:69], v144 offset:57600
	ds_read_b64_tr_b16 v[86:87], v144 offset:57856
	ds_read_b64_tr_b16 v[88:89], v144 offset:58112
	ds_read_b64_tr_b16 v[90:91], v144 offset:58368
	ds_read_b64_tr_b16 v[92:93], v144 offset:58624
	ds_read_b64_tr_b16 v[94:95], v144 offset:58880
	ds_read_b64_tr_b16 v[96:97], v144 offset:59136
	s_waitcnt lgkmcnt(14)
	v_mfma_f32_32x32x16_bf16 v[50:65], v[154:157], v[82:85], v[50:65]
	v_add_f32_e64 v70, v168, v136
	v_add_f32_e64 v71, v169, v137
	v_cvt_pk_bf16_f32 v73, v138, v136
	s_waitcnt lgkmcnt(12)
	v_mfma_f32_32x32x16_bf16 v[34:49], v[158:161], v[82:85], v[34:49]
	v_add_f32_e64 v158, v70, v70
	v_add_f32_e64 v159, v70, v71
	v_exp_f32_e32 v160, v74
	v_exp_f32_e32 v158, v75
	v_cvt_pk_bf16_f32 v70, v170, v173
	v_cvt_pk_bf16_f32 v71, v181, v183
	v_add_f32_e32 v181, v189, v160
	s_waitcnt lgkmcnt(10)
	v_mfma_f32_32x32x16_bf16 v[18:33], v[162:165], v[82:85], v[18:33]
	s_waitcnt lgkmcnt(8)
	v_mfma_f32_32x32x16_bf16 v[2:17], v[174:177], v[82:85], v[2:17]
	ds_read_b64_tr_b16 v[82:83], v144 offset:61440
	ds_read_b64_tr_b16 v[84:85], v144 offset:61696
	ds_read_b64_tr_b16 v[136:137], v144 offset:61952
	ds_read_b64_tr_b16 v[138:139], v144 offset:62208
	ds_read_b64_tr_b16 v[150:151], v144 offset:62464
	ds_read_b64_tr_b16 v[152:153], v144 offset:62720
	ds_read_b64_tr_b16 v[154:155], v144 offset:62976
	ds_read_b64_tr_b16 v[156:157], v144 offset:63232
	s_waitcnt lgkmcnt(14)
	v_mfma_f32_32x32x16_bf16 v[50:65], v[66:69], v[70:73], v[50:65]
	v_add_f32_e64 v66, v180, v158
	v_add_f32_e64 v67, v181, v159
	s_waitcnt lgkmcnt(0)
	v_add_f32_e64 v68, v66, v66
	v_add_f32_e64 v69, v66, v67
	v_exp_f32_e32 v159, v76
	v_exp_f32_e32 v68, v77
	v_mfma_f32_32x32x16_bf16 v[34:49], v[86:89], v[70:73], v[34:49]
	v_add_f32_e32 v183, v190, v159
	s_barrier
; DI int crow(int i, int h) { return (i & 3) + 8 * (i >> 2) + 4 * h; }
; #define MFMA32(a, b, c) __builtin_amdgcn_mfma_f32_32x32x16_bf16((a), (b), (c), 0, 0, 0)
; template <int DV, int MODE>
; DI void attn_finalize(char* lds, const AttnJob& J, f32x16 (&O)[DV / 32], const float lt, const int wid, const int r, const int h) {
;     ...
;     float* sc = (float*)(lds + 32768) + (wid >> 1) * (DV * 32);
;     if (wid & 1) {
;       const float f = inv * J.lam;
; #pragma unroll
;       for (int d = 0; d < NDV; ++d)
; #pragma unroll
;         for (int i = 0; i < 16; ++i) sc[(32 * d + crow(i, h)) * 32 + r] = O[d][i] * f;
;     }
; template <int DV, int NK, int MODE, bool FIXM, int GRP>
; DI void attn_job(char* lds_wg, const AttnJob& J) {
;     ...
;         for (int ks = 0; ks < 4; ++ks) {
; #pragma unroll
;           for (int d = 0; d < NDV; ++d) O[d] = MFMA32(vf[ks][d], pf[ks], O[d]);
;         }
;         __builtin_amdgcn_sched_group_barrier(0x100, 4 * NDV, 0); __builtin_amdgcn_sched_group_barrier(0x008, NDV, 0);
;         __builtin_amdgcn_sched_group_barrier(0x100, 2 * NDV, 0); __builtin_amdgcn_sched_group_barrier(0x008, NDV, 0);
;         __builtin_amdgcn_sched_group_barrier(0x100, 2 * NDV, 0); __builtin_amdgcn_sched_group_barrier(0x008, 2 * NDV, 0);
	ds_read_b128 v[234:237], v145
	ds_read_b128 v[238:241], v145 offset:4096
	ds_read_b128 v[242:245], v147
	ds_read_b128 v[246:249], v147 offset:4096
	v_add_f32_e64 v66, v182, v68
	v_add_f32_e64 v67, v183, v69
	v_add_f32_e64 v74, v66, v66
	v_add_f32_e64 v75, v66, v67
	v_exp_f32_e32 v69, v78
	v_exp_f32_e32 v74, v79
	v_mfma_f32_32x32x16_bf16 v[18:33], v[90:93], v[70:73], v[18:33]
	v_add_f32_e32 v185, v191, v69
	v_add_f32_e64 v66, v184, v74
	v_add_f32_e64 v67, v185, v75
	v_add_f32_e64 v76, v66, v66
	v_add_f32_e64 v77, v66, v67
	v_cvt_pk_bf16_f32 v67, v159, v68
	v_cvt_pk_bf16_f32 v68, v69, v74
	v_mfma_f32_32x32x16_bf16 v[2:17], v[94:97], v[70:73], v[2:17]
	v_exp_f32_e32 v70, v80
	v_exp_f32_e32 v76, v81
	v_cvt_pk_bf16_f32 v66, v160, v158
	v_add_f32_e32 v187, v192, v70
	v_cvt_pk_bf16_f32 v69, v70, v76
	v_pk_add_f32 v[70:71], v[186:187], v[76:77]
	s_nop 0
	v_mfma_f32_32x32x16_bf16 v[50:65], v[82:85], v[66:69], v[50:65]
	v_mfma_f32_32x32x16_bf16 v[34:49], v[136:139], v[66:69], v[34:49]
	v_mfma_f32_32x32x16_bf16 v[18:33], v[150:153], v[66:69], v[18:33]
	v_add_f32_e32 v150, v70, v71
	v_mfma_f32_32x32x16_bf16 v[2:17], v[154:157], v[66:69], v[2:17]
	s_cbranch_vccnz .LBB0_331
	s_mov_b32 s41, s40
	s_branch .LBB0_323
.LBB0_331:
	s_waitcnt lgkmcnt(0)
	s_and_b64 vcc, exec, s[24:25]
	s_cbranch_vccz .LBB0_337
	v_mov_b32_e32 v66, v150
	s_nop 1
	v_permlane32_swap_b32_e32 v150, v66
	v_add_f32_e32 v66, v150, v66
	v_div_scale_f32 v67, s[4:5], v66, v66, 1.0
	v_rcp_f32_e32 v68, v67
	s_lshl_b32 s4, s39, 13
	s_and_b32 s4, s4, 0x4000
	s_or_b32 s14, s4, 0x18000
	v_fma_f32 v69, -v67, v68, 1.0
	v_fmac_f32_e32 v68, v69, v68
	v_div_scale_f32 v69, vcc, 1.0, v66, 1.0
	v_mul_f32_e32 v70, v69, v68
	v_fma_f32 v71, -v67, v70, v69
	v_fmac_f32_e32 v70, v71, v68
	v_fma_f32 v67, -v67, v70, v69
	v_div_fmas_f32 v67, v67, v68, v70
	s_bitcmp0_b32 s38, 6
	v_div_fixup_f32 v72, v67, v66, 1.0
	s_cselect_b64 s[4:5], -1, 0
	v_lshlrev_b32_e32 v66, 9, v130
	v_lshlrev_b32_e32 v67, 2, v146
	s_and_b64 vcc, exec, s[4:5]
	v_add3_u32 v66, s14, v66, v67
	s_cbranch_vccnz .LBB0_334
	v_mul_f32_e32 v67, v171, v72
	v_mul_f32_e32 v68, v50, v67
	v_mul_f32_e32 v69, v51, v67
	ds_write2_b32 v66, v68, v69 offset1:32
	v_mul_f32_e32 v68, v52, v67
	v_mul_f32_e32 v69, v53, v67
	ds_write2_b32 v66, v68, v69 offset0:64 offset1:96
	v_mul_f32_e32 v68, v54, v67
	v_mul_f32_e32 v69, v55, v67
	v_add_u32_e32 v70, 0x400, v66
	ds_write2_b32 v70, v68, v69 offset1:32
	v_mul_f32_e32 v68, v56, v67
	v_mul_f32_e32 v69, v57, v67
	ds_write2_b32 v70, v68, v69 offset0:64 offset1:96
	v_mul_f32_e32 v68, v58, v67
	v_mul_f32_e32 v69, v59, v67
	v_add_u32_e32 v70, 0x800, v66
	ds_write2_b32 v70, v68, v69 offset1:32
	v_mul_f32_e32 v68, v60, v67
	v_mul_f32_e32 v69, v61, v67
	ds_write2_b32 v70, v68, v69 offset0:64 offset1:96
	v_mul_f32_e32 v68, v62, v67
	v_mul_f32_e32 v69, v63, v67
	v_add_u32_e32 v70, 0xc00, v66
	ds_write2_b32 v70, v68, v69 offset1:32
	v_mul_f32_e32 v68, v64, v67
	v_mul_f32_e32 v69, v65, v67
	ds_write2_b32 v70, v68, v69 offset0:64 offset1:96
	v_mul_f32_e32 v68, v34, v67
	v_mul_f32_e32 v69, v35, v67
	v_add_u32_e32 v70, 0x1000, v66
	ds_write2_b32 v70, v68, v69 offset1:32
	v_mul_f32_e32 v68, v36, v67
	v_mul_f32_e32 v69, v37, v67
	ds_write2_b32 v70, v68, v69 offset0:64 offset1:96
	v_mul_f32_e32 v68, v38, v67
	v_mul_f32_e32 v69, v39, v67
	v_add_u32_e32 v70, 0x1400, v66
	ds_write2_b32 v70, v68, v69 offset1:32
	v_mul_f32_e32 v68, v40, v67
	v_mul_f32_e32 v69, v41, v67
	ds_write2_b32 v70, v68, v69 offset0:64 offset1:96
	v_mul_f32_e32 v68, v42, v67
	v_mul_f32_e32 v69, v43, v67
	v_add_u32_e32 v70, 0x1800, v66
	ds_write2_b32 v70, v68, v69 offset1:32
	v_mul_f32_e32 v68, v44, v67
	v_mul_f32_e32 v69, v45, v67
	ds_write2_b32 v70, v68, v69 offset0:64 offset1:96
	v_mul_f32_e32 v68, v46, v67
	v_mul_f32_e32 v69, v47, v67
	v_add_u32_e32 v70, 0x1c00, v66
	ds_write2_b32 v70, v68, v69 offset1:32
	v_mul_f32_e32 v68, v48, v67
	v_mul_f32_e32 v69, v49, v67
	ds_write2_b32 v70, v68, v69 offset0:64 offset1:96
	v_mul_f32_e32 v68, v18, v67
	v_mul_f32_e32 v69, v19, v67
	v_add_u32_e32 v70, 0x2000, v66
	ds_write2_b32 v70, v68, v69 offset1:32
	v_mul_f32_e32 v68, v20, v67
	v_mul_f32_e32 v69, v21, v67
	ds_write2_b32 v70, v68, v69 offset0:64 offset1:96
	v_mul_f32_e32 v68, v22, v67
	v_mul_f32_e32 v69, v23, v67
	v_add_u32_e32 v70, 0x2400, v66
	ds_write2_b32 v70, v68, v69 offset1:32
	v_mul_f32_e32 v68, v24, v67
	v_mul_f32_e32 v69, v25, v67
	ds_write2_b32 v70, v68, v69 offset0:64 offset1:96
	v_mul_f32_e32 v68, v26, v67
	v_mul_f32_e32 v69, v27, v67
	v_add_u32_e32 v70, 0x2800, v66
	ds_write2_b32 v70, v68, v69 offset1:32
	v_mul_f32_e32 v68, v28, v67
	v_mul_f32_e32 v69, v29, v67
	ds_write2_b32 v70, v68, v69 offset0:64 offset1:96
	v_mul_f32_e32 v68, v30, v67
	v_mul_f32_e32 v69, v31, v67
	v_add_u32_e32 v70, 0x2c00, v66
	ds_write2_b32 v70, v68, v69 offset1:32
	v_mul_f32_e32 v68, v32, v67
	v_mul_f32_e32 v69, v33, v67
	ds_write2_b32 v70, v68, v69 offset0:64 offset1:96
	v_mul_f32_e32 v68, v2, v67
	v_mul_f32_e32 v69, v3, v67
	v_add_u32_e32 v70, 0x3000, v66
	ds_write2_b32 v70, v68, v69 offset1:32
	v_mul_f32_e32 v68, v4, v67
	v_mul_f32_e32 v69, v5, v67
	ds_write2_b32 v70, v68, v69 offset0:64 offset1:96
	v_mul_f32_e32 v68, v6, v67
	v_mul_f32_e32 v69, v7, v67
	v_add_u32_e32 v70, 0x3400, v66
	ds_write2_b32 v70, v68, v69 offset1:32
	v_mul_f32_e32 v68, v8, v67
	v_mul_f32_e32 v69, v9, v67
	ds_write2_b32 v70, v68, v69 offset0:64 offset1:96
	v_mul_f32_e32 v68, v10, v67
	v_mul_f32_e32 v69, v11, v67
	v_add_u32_e32 v70, 0x3800, v66
	ds_write2_b32 v70, v68, v69 offset1:32
	v_mul_f32_e32 v68, v12, v67
	v_mul_f32_e32 v69, v13, v67
	ds_write2_b32 v70, v68, v69 offset0:64 offset1:96
	v_mul_f32_e32 v68, v14, v67
	v_mul_f32_e32 v69, v15, v67
	v_add_u32_e32 v70, 0x3c00, v66
	ds_write2_b32 v70, v68, v69 offset1:32
	v_mul_f32_e32 v68, v16, v67
	v_mul_f32_e32 v67, v17, v67
	ds_write2_b32 v70, v68, v67 offset0:64 offset1:96

; #define A_LOAD(t, rk, rv) do { const size_t kb_ = (size_t)(t) * 64; \
;     _Pragma("unroll") for (int s = 0; s < NK; ++s) _Pragma("unroll") for (int i = 0; i < KI; ++i) rk[s][i] = *(const u32x4*)(J.k[s] + (kb_ + ksrow + 32 * i) * J.ldk + ksch * 8); \
;     _Pragma("unroll") for (int i = 0; i < VI; ++i) rv[i] = *(const u32x4*)(J.v + (kb_ + vkey0 + (STN / VCH) * i) * J.ldv + vc8); } while (0)
; template <int DV, int NK, int MODE, bool FIXM, int GRP>
; DI void attn_job(char* lds_wg, const AttnJob& J) {
;     ...
;   bf16x8 qf[4];
;   const bf16_t* qrow = J.q + (size_t)r * UW + 8 * h;
; #pragma unroll
;   for (int ds = 0; ds < 4; ++ds) qf[ds] = *(const bf16x8*)(qrow + 16 * ds);
;   f32x16 O[NDV];
; #pragma unroll
;   for (int d = 0; d < NDV; ++d)
; #pragma unroll
;     for (int i = 0; i < 16; ++i) O[d][i] = 0.f;
;   float m = J.m_init, l = (h == 0) ? J.l_init : 0.f;
;   f32x16 Osum;
; #pragma unroll
;   for (int i = 0; i < 16; ++i) Osum[i] = 0.f;
;   const bf16x8 ones = {0x3F80, 0x3F80, 0x3F80, 0x3F80, 0x3F80, 0x3F80, 0x3F80, 0x3F80};
;   constexpr int KI = 512 / STN;
;   const int ksrow = st_ >> 3, ksch = st_ & 7;
;   const int kpi = (ksrow & ~12) | ((ksrow & 4) << 1) | ((ksrow & 8) >> 1);
;   const int ksoff = kpi * 128 + ((ksch ^ ((kpi >> 1) & 7)) << 4);
;   constexpr int VCH = DV / 8;
;   constexpr int VI = (64 * VCH) / STN;
;   const int vkey0 = st_ / VCH, vc8 = (st_ % VCH) * 8;
;   u32x4 rk0[NK][KI], rv0[VI], rk1[NK][KI], rv1[VI];
;     ...
;   const int nt = J.tile_hi - J.tile_lo;
;   constexpr bool DEEP2 = FIXM || MODE != AM_DIFF;
;   constexpr bool ONESET = FIXM;
;   A_LOAD(J.tile_lo, rk0, rv0); A_WRITE(0, rk0, rv0); if (ONESET) A_LOAD(J.tile_lo + 1, rk0, rv0); else if (DEEP2) A_LOAD(J.tile_lo + 1, rk1, rv1); __syncthreads();
.LBB0_338:
	s_and_b64 vcc, exec, s[4:5]
	s_cbranch_vccz .LBB0_292
	v_mov_b32 v30, v212
	s_nop 5
	v_mov_b64_e32 v[2:3], s[68:69]
	v_ashrrev_i32_e32 v0, 31, v30
	v_lshrrev_b32_e32 v0, 28, v0
	v_add_u32_e32 v0, v30, v0
	v_ashrrev_i32_e32 v32, 4, v0
	v_and_b32_e32 v0, -16, v0
	v_sub_u32_e32 v33, v30, v0
	v_lshlrev_b32_e32 v10, 3, v33
	v_ashrrev_i32_e32 v11, 31, v10
	v_lshlrev_b64 v[20:21], 1, v[10:11]
	v_lshl_add_u64 v[10:11], s[68:69], 0, v[20:21]
	v_ashrrev_i32_e32 v31, 3, v30
	v_lshlrev_b32_e32 v34, 4, v30
	v_mad_i64_i32 v[22:23], s[4:5], v32, s13, v[10:11]
	v_mad_i64_i32 v[2:3], s[4:5], v31, s13, v[2:3]
	v_and_b32_e32 v18, 0x70, v34
	v_mov_b32_e32 v19, v1
	v_add_co_u32_e32 v14, vcc, s22, v22
	v_lshl_add_u64 v[6:7], v[2:3], 0, v[18:19]
	s_nop 0
	v_addc_co_u32_e32 v15, vcc, 0, v23, vcc
	global_load_dwordx4 v[2:5], v[6:7], off offset:2560
	s_nop 0
	global_load_dwordx4 v[6:9], v[6:7], off offset:2688
	s_nop 0
	global_load_dwordx4 v[10:13], v[22:23], off offset:3584
	s_nop 0
	global_load_dwordx4 v[14:17], v[14:15], off offset:3584
	v_mov_b64_e32 v[24:25], s[96:97]
	v_and_b32_e32 v146, 31, v30
	v_bfe_u32 v130, v30, 5, 1
	v_lshlrev_b32_e32 v28, 1, v31
	v_lshrrev_b32_e32 v29, 1, v31
	v_mad_u64_u32 v[24:25], s[4:5], v146, s13, v[24:25]
	v_lshlrev_b32_e32 v0, 4, v130
	v_and_b32_e32 v36, -13, v31
	v_mad_i64_i32 v[26:27], s[4:5], v31, s13, v[166:167]
	v_and_b32_e32 v37, 8, v28
	v_and_b32_e32 v38, 4, v29
	v_lshl_add_u64 v[24:25], v[24:25], 0, v[0:1]
	v_lshl_add_u64 v[28:29], s[70:71], 0, v[26:27]
	v_lshl_add_u64 v[26:27], s[72:73], 0, v[26:27]
	v_or3_b32 v36, v37, v36, v38
	global_load_dwordx4 v[98:101], v[24:25], off offset:1536
	global_load_dwordx4 v[102:105], v[24:25], off offset:1568
	global_load_dwordx4 v[106:109], v[24:25], off offset:1600
	global_load_dwordx4 v[110:113], v[24:25], off offset:1632
	v_lshl_add_u64 v[24:25], v[28:29], 0, v[18:19]
	v_lshl_add_u64 v[18:19], v[26:27], 0, v[18:19]
	v_lshrrev_b32_e32 v27, 1, v36
	v_lshlrev_b32_e32 v26, 7, v36
	v_lshrrev_b32_e32 v29, 1, v32
	v_add_u32_e32 v36, 32, v32
	global_load_dwordx4 v[114:117], v[24:25], off
	global_load_dwordx4 v[118:121], v[18:19], off
	v_xor_b32_e32 v18, v27, v30
	v_ashrrev_i32_e32 v19, 2, v33
	v_and_b32_e32 v25, 0x7ffffc, v29
	v_lshrrev_b32_e32 v27, 1, v36
	v_lshlrev_b32_e32 v18, 4, v18
	v_add_lshl_u32 v140, v25, v19, 9
	v_and_b32_e32 v25, 0x7ffffc, v27
	v_and_or_b32 v141, v18, s12, v26
	v_add_co_u32_e32 v18, vcc, s34, v22
	v_add_lshl_u32 v143, v25, v19, 9
	s_nop 0
	v_addc_co_u32_e32 v19, vcc, 0, v23, vcc
	v_add_co_u32_e32 v22, vcc, s20, v22
	v_lshlrev_b32_e32 v24, 4, v33
	s_nop 0
	v_addc_co_u32_e32 v23, vcc, 0, v23, vcc
	global_load_dwordx4 v[122:125], v[18:19], off offset:3584
	global_load_dwordx4 v[126:129], v[22:23], off offset:3584
	v_lshlrev_b32_e32 v28, 6, v32
	v_and_b32_e32 v24, 48, v24
	v_and_or_b32 v142, v28, s6, v24
	v_or_b32_e32 v24, v142, v140
	v_or_b32_e32 v25, v142, v143
	v_lshrrev_b32_e32 v35, 5, v30
	v_readlane_b32 s44, v254, 33
	v_readfirstlane_b32 s38, v30
	v_readlane_b32 s48, v254, 37
	v_readlane_b32 s49, v254, 38
	s_lshl_b32 s4, s38, 7
	s_and_b32 s4, s4, 0x2000
	v_mov_b32_e32 v150, 0
	s_mov_b32 s41, 0
	s_lshr_b32 s39, s38, 6
	v_mov_b32_e32 v18, 0
	v_mov_b32_e32 v19, v150
	v_mov_b32_e32 v22, v150
	v_mov_b32_e32 v23, v150
	v_mov_b32_e32 v26, v150
	v_mov_b32_e32 v27, v150
	s_waitcnt vmcnt(11)
	ds_write_b128 v141, v[2:5]
	s_waitcnt vmcnt(10)
	ds_write_b128 v141, v[6:9] offset:8192
	s_waitcnt vmcnt(9)
	ds_write_b128 v24, v[10:13] offset:16384
	s_waitcnt vmcnt(8)
	ds_write_b128 v25, v[14:17] offset:16384
	v_lshlrev_b32_e32 v4, 2, v30
	v_and_b32_e32 v5, 16, v30
	v_and_or_b32 v4, v4, 12, v5
	v_lshlrev_b32_e32 v2, 11, v130
	v_and_b32_e32 v3, 0xc0, v34
	v_lshlrev_b32_e32 v4, 1, v4
	v_or3_b32 v144, v2, v3, v4
	v_bfe_u32 v2, v30, 1, 3
	v_bitop3_b32 v3, v35, v2, 1 bitop3:0x6c
	v_lshlrev_b32_e32 v7, 4, v3
	v_bitop3_b32 v3, v130, v2, 2 bitop3:0x36
	v_lshlrev_b32_e32 v8, 4, v3
	v_bitop3_b32 v3, v130, v2, 4 bitop3:0x36
	v_bitop3_b32 v2, v130, v2, 6 bitop3:0x36
	v_lshlrev_b32_e32 v9, 4, v3
	v_lshlrev_b32_e32 v10, 4, v2
	v_mov_b64_e32 v[2:3], s[2:3]
	v_mad_i64_i32 v[4:5], s[2:3], v32, s13, v[2:3]
	v_lshl_add_u64 v[4:5], v[4:5], 0, v[20:21]
	v_lshl_add_u64 v[132:133], s[48:49], 0, v[4:5]
	v_and_b32_e32 v4, 7, v30
	v_mad_i64_i32 v[2:3], s[2:3], v31, s13, v[2:3]
	v_lshlrev_b32_e32 v4, 4, v4
	v_mov_b32_e32 v5, v1
	v_lshl_or_b32 v6, v146, 7, s4
	s_and_b32 s4, s87, 3
	v_lshl_add_u64 v[2:3], v[2:3], 0, v[4:5]
	s_lshl_b32 s14, s4, 8
	v_lshl_add_u64 v[134:135], s[48:49], 0, v[2:3]
	v_add_u32_e32 v145, v6, v7
	v_add_u32_e32 v147, v6, v8
	v_add_u32_e32 v148, v6, v9
	v_add_u32_e32 v149, v6, v10
	v_mov_b32_e32 v2, 0
	v_mov_b32_e32 v3, v150
	v_mov_b32_e32 v4, v150
	v_mov_b32_e32 v5, v150
	v_mov_b32_e32 v6, v150
	v_mov_b32_e32 v7, v150
	v_mov_b32_e32 v8, v150
	v_mov_b32_e32 v9, v150
	v_mov_b32_e32 v10, v150
	v_mov_b32_e32 v11, v150
	v_mov_b32_e32 v12, v150
	v_mov_b32_e32 v13, v150
	v_mov_b32_e32 v14, v150
	v_mov_b32_e32 v15, v150
	v_mov_b32_e32 v16, v150
	v_mov_b32_e32 v17, v150
	v_mov_b32_e32 v20, v150
	v_mov_b32_e32 v21, v150
	v_mov_b32_e32 v24, v150
	v_mov_b32_e32 v25, v150
	v_mov_b32_e32 v28, v150
	v_mov_b32_e32 v29, v150
	v_mov_b32_e32 v30, v150
	v_mov_b32_e32 v31, v150
	v_mov_b32_e32 v32, v150
	v_mov_b32_e32 v33, v150
	v_mov_b32_e32 v34, 0
	v_mov_b32_e32 v35, v150
	v_mov_b32_e32 v36, v150
	v_mov_b32_e32 v37, v150
	v_mov_b32_e32 v38, v150
	v_mov_b32_e32 v39, v150
	v_mov_b32_e32 v40, v150
	v_mov_b32_e32 v41, v150
	v_mov_b32_e32 v42, v150
	v_mov_b32_e32 v43, v150
	v_mov_b32_e32 v44, v150
	v_mov_b32_e32 v45, v150
	v_mov_b32_e32 v46, v150
	v_mov_b32_e32 v47, v150
	v_mov_b32_e32 v48, v150
	v_mov_b32_e32 v49, v150
	v_mov_b32_e32 v50, 0
	v_mov_b32_e32 v51, v150
	v_mov_b32_e32 v52, v150
	v_mov_b32_e32 v53, v150
	v_mov_b32_e32 v54, v150
	v_mov_b32_e32 v55, v150
	v_mov_b32_e32 v56, v150
	v_mov_b32_e32 v57, v150
	v_mov_b32_e32 v58, v150
	v_mov_b32_e32 v59, v150
	v_mov_b32_e32 v60, v150
	v_mov_b32_e32 v61, v150
	v_mov_b32_e32 v62, v150
	v_mov_b32_e32 v63, v150
	v_mov_b32_e32 v64, v150
	v_mov_b32_e32 v65, v150
	s_waitcnt lgkmcnt(0)
	s_barrier
; template <int DV, int NK, int MODE, bool FIXM, int GRP>
; DI void attn_job(char* lds_wg, const AttnJob& J) {
;     ...
;   bf16x8 qf[4];
;   const bf16_t* qrow = J.q + (size_t)r * UW + 8 * h;
; #pragma unroll
;   for (int ds = 0; ds < 4; ++ds) qf[ds] = *(const bf16x8*)(qrow + 16 * ds);
;     ...
;         bf16x8 ka[4], kb[4];
; #pragma unroll
;         for (int ds = 0; ds < 4; ++ds) { const int co = ((2 * ds + h) ^ ((r >> 1) & 7)) << 4; ka[ds] = *(const bf16x8*)(Kl + co); kb[ds] = *(const bf16x8*)(Kl + 4096 + co); }
	v_readlane_b32 s45, v254, 34
	v_readlane_b32 s46, v254, 35
	v_readlane_b32 s47, v254, 36
	v_readlane_b32 s50, v254, 39
	v_readlane_b32 s51, v254, 40
	v_readlane_b32 s52, v254, 41
	v_readlane_b32 s53, v254, 42
	v_readlane_b32 s54, v254, 43
	v_readlane_b32 s55, v254, 44
	v_readlane_b32 s56, v254, 45
	v_readlane_b32 s57, v254, 46
	v_readlane_b32 s58, v254, 47
	v_readlane_b32 s59, v254, 48
	s_waitcnt vmcnt(4)
	v_lshlrev_b32_e32 v82, 16, v98
	v_and_b32_e32 v83, 0xffff0000, v98
	v_mul_f32_e32 v82, s7, v82
	v_mul_f32_e32 v83, s7, v83
	v_cvt_pk_bf16_f32 v98, v82, v83
	v_lshlrev_b32_e32 v82, 16, v99
	v_and_b32_e32 v83, 0xffff0000, v99
	v_mul_f32_e32 v82, s7, v82
	v_mul_f32_e32 v83, s7, v83
	v_cvt_pk_bf16_f32 v99, v82, v83
	v_lshlrev_b32_e32 v82, 16, v100
	v_and_b32_e32 v83, 0xffff0000, v100
	v_mul_f32_e32 v82, s7, v82
	v_mul_f32_e32 v83, s7, v83
	v_cvt_pk_bf16_f32 v100, v82, v83
	v_lshlrev_b32_e32 v82, 16, v101
	v_and_b32_e32 v83, 0xffff0000, v101
	v_mul_f32_e32 v82, s7, v82
	v_mul_f32_e32 v83, s7, v83
	v_cvt_pk_bf16_f32 v101, v82, v83
	v_lshlrev_b32_e32 v82, 16, v102
	v_and_b32_e32 v83, 0xffff0000, v102
	v_mul_f32_e32 v82, s7, v82
	v_mul_f32_e32 v83, s7, v83
	v_cvt_pk_bf16_f32 v102, v82, v83
	v_lshlrev_b32_e32 v82, 16, v103
	v_and_b32_e32 v83, 0xffff0000, v103
	v_mul_f32_e32 v82, s7, v82
	v_mul_f32_e32 v83, s7, v83
	v_cvt_pk_bf16_f32 v103, v82, v83
	v_lshlrev_b32_e32 v82, 16, v104
	v_and_b32_e32 v83, 0xffff0000, v104
	v_mul_f32_e32 v82, s7, v82
	v_mul_f32_e32 v83, s7, v83
	v_cvt_pk_bf16_f32 v104, v82, v83
	v_lshlrev_b32_e32 v82, 16, v105
	v_and_b32_e32 v83, 0xffff0000, v105
	v_mul_f32_e32 v82, s7, v82
	v_mul_f32_e32 v83, s7, v83
	v_cvt_pk_bf16_f32 v105, v82, v83
	v_lshlrev_b32_e32 v82, 16, v106
	v_and_b32_e32 v83, 0xffff0000, v106
	v_mul_f32_e32 v82, s7, v82
	v_mul_f32_e32 v83, s7, v83
	v_cvt_pk_bf16_f32 v106, v82, v83
	v_lshlrev_b32_e32 v82, 16, v107
	v_and_b32_e32 v83, 0xffff0000, v107
	v_mul_f32_e32 v82, s7, v82
	v_mul_f32_e32 v83, s7, v83
	v_cvt_pk_bf16_f32 v107, v82, v83
	v_lshlrev_b32_e32 v82, 16, v108
	v_and_b32_e32 v83, 0xffff0000, v108
	v_mul_f32_e32 v82, s7, v82
	v_mul_f32_e32 v83, s7, v83
	v_cvt_pk_bf16_f32 v108, v82, v83
	v_lshlrev_b32_e32 v82, 16, v109
	v_and_b32_e32 v83, 0xffff0000, v109
	v_mul_f32_e32 v82, s7, v82
	v_mul_f32_e32 v83, s7, v83
	v_cvt_pk_bf16_f32 v109, v82, v83
	v_lshlrev_b32_e32 v82, 16, v110
	v_and_b32_e32 v83, 0xffff0000, v110
	v_mul_f32_e32 v82, s7, v82
	v_mul_f32_e32 v83, s7, v83
	v_cvt_pk_bf16_f32 v110, v82, v83
	v_lshlrev_b32_e32 v82, 16, v111
	v_and_b32_e32 v83, 0xffff0000, v111
	v_mul_f32_e32 v82, s7, v82
	v_mul_f32_e32 v83, s7, v83
	v_cvt_pk_bf16_f32 v111, v82, v83
	v_lshlrev_b32_e32 v82, 16, v112
	v_and_b32_e32 v83, 0xffff0000, v112
	v_mul_f32_e32 v82, s7, v82
	v_mul_f32_e32 v83, s7, v83
	v_cvt_pk_bf16_f32 v112, v82, v83
	v_lshlrev_b32_e32 v82, 16, v113
	v_and_b32_e32 v83, 0xffff0000, v113
	v_mul_f32_e32 v82, s7, v82
	v_mul_f32_e32 v83, s7, v83
	v_cvt_pk_bf16_f32 v113, v82, v83
	ds_read_b128 v[234:237], v145
	ds_read_b128 v[238:241], v145 offset:4096
	ds_read_b128 v[242:245], v147
	ds_read_b128 v[246:249], v147 offset:4096

; template <int DV, int NK, int MODE, bool FIXM, int GRP>
; DI void attn_job(char* lds_wg, const AttnJob& J) {
;     ...
;       if (NDV == 2 || FIXM) {
;         bf16x8 ka[4], kb[4];
; #pragma unroll
;         for (int ds = 0; ds < 4; ++ds) { const int co = ((2 * ds + h) ^ ((r >> 1) & 7)) << 4; ka[ds] = *(const bf16x8*)(Kl + co); kb[ds] = *(const bf16x8*)(Kl + 4096 + co); }
; #pragma unroll
;         for (int ds = 0; ds < 4; ++ds) { sA = MFMA32(ka[ds], qf[ds], sA); sB = MFMA32(kb[ds], qf[ds], sB); }
;         __builtin_amdgcn_sched_group_barrier(0x100, 4, 0); __builtin_amdgcn_sched_group_barrier(0x008, 2, 0);
;         __builtin_amdgcn_sched_group_barrier(0x100, 2, 0); __builtin_amdgcn_sched_group_barrier(0x008, 2, 0);
;         __builtin_amdgcn_sched_group_barrier(0x100, 2, 0); __builtin_amdgcn_sched_group_barrier(0x008, 4, 0);
;       } else {
; #pragma unroll
;         for (int ds = 0; ds < 4; ++ds) {
;           const int co = ((2 * ds + h) ^ ((r >> 1) & 7)) << 4;
;           const bf16x8 ka = *(const bf16x8*)(Kl + co), kb = *(const bf16x8*)(Kl + 4096 + co);
;           sA = MFMA32(ka, qf[ds], sA); sB = MFMA32(kb, qf[ds], sB);
;         }
;       }
;       if (MODE == AM_SWA) {
;         const int qa = J.qpos0 + r, kbase = tile * 64 + 8 * h;
; #pragma unroll
;         for (int i = 0; i < 16; ++i) {
;           const int ka_ = kbase + 16 * (i >> 3) + (i & 7);
;           int d0 = qa - ka_; d0 = d0 < 0 ? -d0 : d0; if (d0 > 128) sA[i] = -INFINITY;
;           int d1 = qa - (ka_ + 32); d1 = d1 < 0 ? -d1 : d1; if (d1 > 128) sB[i] = -INFINITY;
;         }
;       }
;       if (FIXM) {
;         const float nm = -J.m_init;
; #pragma unroll
;         for (int i = 0; i < 16; ++i) { sA[i] = __builtin_amdgcn_exp2f(fmaf(sA[i], C, nm)); sB[i] = __builtin_amdgcn_exp2f(fmaf(sB[i], C, nm)); l += sA[i] + sB[i]; }
;     ...
;       bf16x8 pf[4];
;       { u32x4 w;
;         w.x = cvtpk(sA[0], sA[1]); w.y = cvtpk(sA[2], sA[3]); w.z = cvtpk(sA[4], sA[5]); w.w = cvtpk(sA[6], sA[7]); pf[0] = __builtin_bit_cast(bf16x8, w);
;         w.x = cvtpk(sA[8], sA[9]); w.y = cvtpk(sA[10], sA[11]); w.z = cvtpk(sA[12], sA[13]); w.w = cvtpk(sA[14], sA[15]); pf[1] = __builtin_bit_cast(bf16x8, w);
;         w.x = cvtpk(sB[0], sB[1]); w.y = cvtpk(sB[2], sB[3]); w.z = cvtpk(sB[4], sB[5]); w.w = cvtpk(sB[6], sB[7]); pf[2] = __builtin_bit_cast(bf16x8, w);
.LBB0_342:
	s_andn2_b64 vcc, exec, s[4:5]
	s_waitcnt lgkmcnt(7)
	v_mfma_f32_32x32x16_bf16 v[82:97], v[234:237], v[98:101], 0
	s_waitcnt lgkmcnt(6)
	v_mfma_f32_32x32x16_bf16 v[66:81], v[238:241], v[98:101], 0
	ds_read_b128 v[162:165], v148
	ds_read_b128 v[174:177], v148 offset:4096
	s_waitcnt lgkmcnt(7)
	v_mfma_f32_32x32x16_bf16 v[82:97], v[242:245], v[102:105], v[82:97]
	s_waitcnt lgkmcnt(6)
	v_mfma_f32_32x32x16_bf16 v[66:81], v[246:249], v[102:105], v[66:81]
	ds_read_b128 v[154:157], v149
	ds_read_b128 v[158:161], v149 offset:4096
	s_waitcnt lgkmcnt(3)
	v_mfma_f32_32x32x16_bf16 v[82:97], v[162:165], v[106:109], v[82:97]
	s_waitcnt lgkmcnt(1)
	v_mfma_f32_32x32x16_bf16 v[82:97], v[154:157], v[110:113], v[82:97]
	v_mfma_f32_32x32x16_bf16 v[66:81], v[174:177], v[106:109], v[66:81]
	s_nop 10
	v_exp_f32_e32 v153, v82
	v_exp_f32_e32 v154, v83
	v_exp_f32_e32 v155, v84
	v_exp_f32_e32 v156, v85
	s_waitcnt lgkmcnt(0)
	v_mfma_f32_32x32x16_bf16 v[66:81], v[158:161], v[110:113], v[66:81]
	v_exp_f32_e32 v158, v86
	v_exp_f32_e32 v157, v87
	v_exp_f32_e32 v159, v88
	v_exp_f32_e32 v160, v89
	ds_read_b64_tr_b16 v[86:87], v144 offset:16384
	ds_read_b64_tr_b16 v[88:89], v144 offset:16640
	ds_read_b64_tr_b16 v[174:175], v144 offset:16896
	ds_read_b64_tr_b16 v[176:177], v144 offset:17152
	ds_read_b64_tr_b16 v[178:179], v144 offset:17408
	ds_read_b64_tr_b16 v[180:181], v144 offset:17664
	ds_read_b64_tr_b16 v[182:183], v144 offset:17920
	ds_read_b64_tr_b16 v[184:185], v144 offset:18176
	v_cvt_pk_bf16_f32 v82, v153, v154
	v_cvt_pk_bf16_f32 v83, v155, v156
	v_cvt_pk_bf16_f32 v84, v158, v157
	v_cvt_pk_bf16_f32 v85, v159, v160
	ds_read_b64_tr_b16 v[186:187], v144 offset:20480
	ds_read_b64_tr_b16 v[188:189], v144 offset:20736
	ds_read_b64_tr_b16 v[190:191], v144 offset:20992
	ds_read_b64_tr_b16 v[192:193], v144 offset:21248
	ds_read_b64_tr_b16 v[194:195], v144 offset:21504
	ds_read_b64_tr_b16 v[196:197], v144 offset:21760
	ds_read_b64_tr_b16 v[198:199], v144 offset:22016
	ds_read_b64_tr_b16 v[200:201], v144 offset:22272
	s_waitcnt lgkmcnt(14)
	v_mfma_f32_32x32x16_bf16 v[50:65], v[86:89], v[82:85], v[50:65]
	v_exp_f32_e32 v168, v90
	v_exp_f32_e32 v162, v91
	v_exp_f32_e32 v163, v92
	v_exp_f32_e32 v169, v93
	s_waitcnt lgkmcnt(12)
	v_mfma_f32_32x32x16_bf16 v[34:49], v[174:177], v[82:85], v[34:49]
	v_exp_f32_e32 v164, v94
	v_exp_f32_e32 v165, v95
	v_exp_f32_e32 v170, v96
	v_exp_f32_e32 v161, v97
	s_waitcnt lgkmcnt(10)
	v_mfma_f32_32x32x16_bf16 v[18:33], v[178:181], v[82:85], v[18:33]
	v_exp_f32_e32 v176, v66
	v_exp_f32_e32 v177, v67
	v_exp_f32_e32 v178, v68
	s_waitcnt lgkmcnt(8)
	v_mfma_f32_32x32x16_bf16 v[2:17], v[182:185], v[82:85], v[2:17]
	v_cvt_pk_bf16_f32 v86, v168, v162
	v_cvt_pk_bf16_f32 v87, v163, v169
	v_cvt_pk_bf16_f32 v88, v164, v165
	v_cvt_pk_bf16_f32 v89, v170, v161
	ds_read_b64_tr_b16 v[82:83], v144 offset:24576
	ds_read_b64_tr_b16 v[84:85], v144 offset:24832
	ds_read_b64_tr_b16 v[90:91], v144 offset:25088
	ds_read_b64_tr_b16 v[92:93], v144 offset:25344
	ds_read_b64_tr_b16 v[94:95], v144 offset:25600
	ds_read_b64_tr_b16 v[96:97], v144 offset:25856
	ds_read_b64_tr_b16 v[202:203], v144 offset:26112
	ds_read_b64_tr_b16 v[204:205], v144 offset:26368
	v_exp_f32_e32 v179, v69
	s_waitcnt lgkmcnt(14)
	v_mfma_f32_32x32x16_bf16 v[50:65], v[186:189], v[86:89], v[50:65]
	v_exp_f32_e32 v180, v70
	v_exp_f32_e32 v173, v71
	v_exp_f32_e32 v174, v72
	v_exp_f32_e32 v175, v73
	s_waitcnt lgkmcnt(12)
	v_mfma_f32_32x32x16_bf16 v[34:49], v[190:193], v[86:89], v[34:49]
	v_exp_f32_e32 v186, v74
	v_exp_f32_e32 v182, v75
	v_cvt_pk_bf16_f32 v66, v176, v177
	v_cvt_pk_bf16_f32 v67, v178, v179
	s_waitcnt lgkmcnt(10)
	v_mfma_f32_32x32x16_bf16 v[18:33], v[194:197], v[86:89], v[18:33]
	v_cvt_pk_bf16_f32 v68, v180, v173
	v_cvt_pk_bf16_f32 v69, v174, v175
	v_exp_f32_e32 v183, v76
	v_exp_f32_e32 v187, v77
	v_exp_f32_e32 v184, v78
	s_waitcnt lgkmcnt(8)
	v_mfma_f32_32x32x16_bf16 v[2:17], v[198:201], v[86:89], v[2:17]
	ds_read_b64_tr_b16 v[70:71], v144 offset:28672
	ds_read_b64_tr_b16 v[72:73], v144 offset:28928
	ds_read_b64_tr_b16 v[86:87], v144 offset:29184
	ds_read_b64_tr_b16 v[88:89], v144 offset:29440
	ds_read_b64_tr_b16 v[190:191], v144 offset:29696
	ds_read_b64_tr_b16 v[192:193], v144 offset:29952
	ds_read_b64_tr_b16 v[194:195], v144 offset:30208
	ds_read_b64_tr_b16 v[196:197], v144 offset:30464
	s_waitcnt lgkmcnt(14)
	v_mfma_f32_32x32x16_bf16 v[50:65], v[82:85], v[66:69], v[50:65]
	v_exp_f32_e32 v185, v79
	v_exp_f32_e32 v188, v80
	s_waitcnt lgkmcnt(0)
	s_barrier
	ds_read_b128 v[234:237], v145 offset:32768
	ds_read_b128 v[238:241], v145 offset:36864
	ds_read_b128 v[242:245], v147 offset:32768
	ds_read_b128 v[246:249], v147 offset:36864
	v_mfma_f32_32x32x16_bf16 v[34:49], v[90:93], v[66:69], v[34:49]
	v_mfma_f32_32x32x16_bf16 v[18:33], v[94:97], v[66:69], v[18:33]
	v_mfma_f32_32x32x16_bf16 v[2:17], v[202:205], v[66:69], v[2:17]
	v_exp_f32_e32 v181, v81
	v_cvt_pk_bf16_f32 v66, v186, v182
	v_cvt_pk_bf16_f32 v67, v183, v187
	v_cvt_pk_bf16_f32 v68, v184, v185
	v_cvt_pk_bf16_f32 v69, v188, v181
	s_nop 1
	v_mfma_f32_32x32x16_bf16 v[50:65], v[70:73], v[66:69], v[50:65]
	v_mfma_f32_32x32x16_bf16 v[34:49], v[86:89], v[66:69], v[34:49]
	v_mfma_f32_32x32x16_bf16 v[18:33], v[190:193], v[66:69], v[18:33]
	v_mfma_f32_32x32x16_bf16 v[2:17], v[194:197], v[66:69], v[2:17]
	s_cbranch_vccnz .LBB0_344
	s_waitcnt vmcnt(3)
	ds_write_b128 v141, v[114:117]
	s_waitcnt vmcnt(2)
	ds_write_b128 v141, v[118:121] offset:8192
	s_waitcnt vmcnt(1)
	ds_write_b128 v151, v[122:125] offset:16384
	s_waitcnt vmcnt(0)
	ds_write_b128 v152, v[126:129] offset:16384

; template <int DV, int NK, int MODE, bool FIXM, int GRP>
; DI void attn_job(char* lds_wg, const AttnJob& J) {
;     ...
;       if (NDV == 2 || FIXM) {
;         bf16x8 ka[4], kb[4];
; #pragma unroll
;         for (int ds = 0; ds < 4; ++ds) { const int co = ((2 * ds + h) ^ ((r >> 1) & 7)) << 4; ka[ds] = *(const bf16x8*)(Kl + co); kb[ds] = *(const bf16x8*)(Kl + 4096 + co); }
; #pragma unroll
;         for (int ds = 0; ds < 4; ++ds) { sA = MFMA32(ka[ds], qf[ds], sA); sB = MFMA32(kb[ds], qf[ds], sB); }
;         __builtin_amdgcn_sched_group_barrier(0x100, 4, 0); __builtin_amdgcn_sched_group_barrier(0x008, 2, 0);
;         __builtin_amdgcn_sched_group_barrier(0x100, 2, 0); __builtin_amdgcn_sched_group_barrier(0x008, 2, 0);
;         __builtin_amdgcn_sched_group_barrier(0x100, 2, 0); __builtin_amdgcn_sched_group_barrier(0x008, 4, 0);
;       } else {
; #pragma unroll
;         for (int ds = 0; ds < 4; ++ds) {
;           const int co = ((2 * ds + h) ^ ((r >> 1) & 7)) << 4;
;           const bf16x8 ka = *(const bf16x8*)(Kl + co), kb = *(const bf16x8*)(Kl + 4096 + co);
;           sA = MFMA32(ka, qf[ds], sA); sB = MFMA32(kb, qf[ds], sB);
;         }
;       }
;       if (MODE == AM_SWA) {
;         const int qa = J.qpos0 + r, kbase = tile * 64 + 8 * h;
; #pragma unroll
;         for (int i = 0; i < 16; ++i) {
;           const int ka_ = kbase + 16 * (i >> 3) + (i & 7);
;           int d0 = qa - ka_; d0 = d0 < 0 ? -d0 : d0; if (d0 > 128) sA[i] = -INFINITY;
;           int d1 = qa - (ka_ + 32); d1 = d1 < 0 ? -d1 : d1; if (d1 > 128) sB[i] = -INFINITY;
;         }
;       }
;       if (FIXM) {
;         const float nm = -J.m_init;
; #pragma unroll
;         for (int i = 0; i < 16; ++i) { sA[i] = __builtin_amdgcn_exp2f(fmaf(sA[i], C, nm)); sB[i] = __builtin_amdgcn_exp2f(fmaf(sB[i], C, nm)); l += sA[i] + sB[i]; }
;     ...
;       bf16x8 pf[4];
;       { u32x4 w;
;         w.x = cvtpk(sA[0], sA[1]); w.y = cvtpk(sA[2], sA[3]); w.z = cvtpk(sA[4], sA[5]); w.w = cvtpk(sA[6], sA[7]); pf[0] = __builtin_bit_cast(bf16x8, w);
;         w.x = cvtpk(sA[8], sA[9]); w.y = cvtpk(sA[10], sA[11]); w.z = cvtpk(sA[12], sA[13]); w.w = cvtpk(sA[14], sA[15]); pf[1] = __builtin_bit_cast(bf16x8, w);
;         w.x = cvtpk(sB[0], sB[1]); w.y = cvtpk(sB[2], sB[3]); w.z = cvtpk(sB[4], sB[5]); w.w = cvtpk(sB[6], sB[7]); pf[2] = __builtin_bit_cast(bf16x8, w);
.LBB0_346:
	v_lshl_add_u64 v[132:133], v[132:133], 0, s[94:95]
	v_lshl_add_u64 v[134:135], v[134:135], 0, s[94:95]
	s_and_b64 vcc, exec, s[2:3]
	s_waitcnt lgkmcnt(3)
	v_mfma_f32_32x32x16_bf16 v[82:97], v[234:237], v[98:101], 0
	s_waitcnt lgkmcnt(2)
	v_mfma_f32_32x32x16_bf16 v[66:81], v[238:241], v[98:101], 0
	ds_read_b128 v[194:197], v148 offset:32768
	ds_read_b128 v[198:201], v148 offset:36864
	s_waitcnt lgkmcnt(3)
	v_mfma_f32_32x32x16_bf16 v[82:97], v[242:245], v[102:105], v[82:97]
	v_add_f32_e32 v136, v153, v176
	v_add_f32_e32 v136, v150, v136
	v_add_f32_e32 v137, v154, v177
	v_add_f32_e32 v136, v137, v136
	v_add_f32_e32 v137, v155, v178
	v_add_f32_e32 v136, v137, v136
	v_add_f32_e32 v137, v156, v179
	s_waitcnt lgkmcnt(2)
	v_mfma_f32_32x32x16_bf16 v[66:81], v[246:249], v[102:105], v[66:81]
	v_add_f32_e32 v136, v137, v136
	v_add_f32_e32 v137, v158, v180
	v_add_f32_e32 v154, v137, v136
	ds_read_b128 v[136:139], v149 offset:32768
	ds_read_b128 v[150:153], v149 offset:36864
	v_add_f32_e32 v155, v157, v173
	v_add_f32_e32 v154, v155, v154
	s_waitcnt lgkmcnt(3)
	v_mfma_f32_32x32x16_bf16 v[82:97], v[194:197], v[106:109], v[82:97]
	v_add_f32_e32 v155, v159, v174
	v_add_f32_e32 v154, v155, v154
	v_add_f32_e32 v155, v160, v175
	v_add_f32_e32 v154, v155, v154
	v_add_f32_e32 v155, v168, v186
	v_add_f32_e32 v154, v155, v154
	v_add_f32_e32 v155, v162, v182
	s_waitcnt lgkmcnt(2)
	v_mfma_f32_32x32x16_bf16 v[66:81], v[198:201], v[106:109], v[66:81]
	v_add_f32_e32 v154, v155, v154
	v_add_f32_e32 v155, v163, v183
	v_add_f32_e32 v154, v155, v154
	v_add_f32_e32 v155, v169, v187
	v_add_f32_e32 v154, v155, v154
	s_waitcnt lgkmcnt(1)
	v_mfma_f32_32x32x16_bf16 v[82:97], v[136:139], v[110:113], v[82:97]
	v_add_f32_e32 v136, v164, v184
	v_add_f32_e32 v136, v136, v154
	v_add_f32_e32 v137, v165, v185
	v_add_f32_e32 v136, v137, v136
	v_add_f32_e32 v137, v170, v188
	s_nop 6
	s_waitcnt lgkmcnt(0)
	v_mfma_f32_32x32x16_bf16 v[66:81], v[150:153], v[110:113], v[66:81]
	v_exp_f32_e32 v82, v82
	v_exp_f32_e32 v83, v83
	ds_read_b64_tr_b16 v[138:139], v144 offset:50432
	ds_read_b64_tr_b16 v[150:151], v144 offset:50688
	ds_read_b64_tr_b16 v[152:153], v144 offset:50944
	ds_read_b64_tr_b16 v[154:155], v144 offset:53248
	s_nop 4
	v_exp_f32_e32 v170, v66
	v_exp_f32_e32 v173, v67
	v_add_f32_e32 v66, v137, v136
	v_add_f32_e32 v136, v161, v181
	v_exp_f32_e32 v67, v84
	v_exp_f32_e32 v181, v68
	v_add_f32_e32 v66, v136, v66
	v_add_f32_e32 v136, v82, v170
	v_add_f32_e32 v66, v66, v136
	v_add_f32_e32 v68, v83, v173
	v_add_f32_e32 v66, v68, v66
	v_add_f32_e32 v68, v67, v181
	v_add_f32_e32 v169, v68, v66
	v_exp_f32_e32 v179, v85
	v_exp_f32_e32 v183, v69
	v_exp_f32_e32 v185, v86
	v_exp_f32_e32 v187, v70
	v_exp_f32_e32 v70, v87
	v_exp_f32_e32 v188, v88
	v_exp_f32_e32 v168, v89
	v_cvt_pk_bf16_f32 v66, v82, v83
	ds_read_b64_tr_b16 v[82:83], v144 offset:49152
	ds_read_b64_tr_b16 v[84:85], v144 offset:49408
	v_exp_f32_e32 v178, v71
	ds_read_b64_tr_b16 v[86:87], v144 offset:49664
	ds_read_b64_tr_b16 v[88:89], v144 offset:49920
	v_exp_f32_e32 v189, v90
	ds_read_b64_tr_b16 v[136:137], v144 offset:50176
	v_exp_f32_e32 v180, v91
	v_exp_f32_e32 v190, v92
	v_exp_f32_e32 v182, v93
	v_exp_f32_e32 v191, v94
	v_exp_f32_e32 v184, v95
	v_cvt_pk_bf16_f32 v67, v67, v179
	v_cvt_pk_bf16_f32 v68, v185, v70
	v_cvt_pk_bf16_f32 v69, v188, v168
	ds_read_b64_tr_b16 v[156:157], v144 offset:53504
	v_exp_f32_e32 v192, v96
	ds_read_b64_tr_b16 v[158:159], v144 offset:53760
	ds_read_b64_tr_b16 v[160:161], v144 offset:54016
	ds_read_b64_tr_b16 v[162:163], v144 offset:54272
	ds_read_b64_tr_b16 v[164:165], v144 offset:54528
	ds_read_b64_tr_b16 v[174:175], v144 offset:54784
	ds_read_b64_tr_b16 v[176:177], v144 offset:55040
	s_waitcnt lgkmcnt(10)
	v_mfma_f32_32x32x16_bf16 v[50:65], v[82:85], v[66:69], v[50:65]
	v_exp_f32_e32 v186, v97
	v_add_f32_e32 v71, v179, v183
	v_add_f32_e32 v179, v71, v169
	v_add_f32_e32 v71, v185, v187
	v_pk_add_f32 v[70:71], v[70:71], v[178:179]
	v_cvt_pk_bf16_f32 v82, v189, v180
	v_cvt_pk_bf16_f32 v83, v190, v182
	s_waitcnt lgkmcnt(8)
	v_mfma_f32_32x32x16_bf16 v[34:49], v[86:89], v[66:69], v[34:49]
	v_cvt_pk_bf16_f32 v84, v191, v184
	v_cvt_pk_bf16_f32 v85, v192, v186
	s_waitcnt lgkmcnt(7)
	v_mfma_f32_32x32x16_bf16 v[18:33], v[136:139], v[66:69], v[18:33]
	v_add_f32_e64 v136, v70, v70
	v_add_f32_e64 v137, v70, v71
	v_exp_f32_e32 v138, v72
	v_exp_f32_e32 v136, v73
	v_cvt_pk_bf16_f32 v72, v187, v178
	v_add_f32_e32 v169, v188, v138
	v_mfma_f32_32x32x16_bf16 v[2:17], v[150:153], v[66:69], v[2:17]
	ds_read_b64_tr_b16 v[66:67], v144 offset:57344
	ds_read_b64_tr_b16 v[68:69], v144 offset:57600
	ds_read_b64_tr_b16 v[86:87], v144 offset:57856
	ds_read_b64_tr_b16 v[88:89], v144 offset:58112
	ds_read_b64_tr_b16 v[90:91], v144 offset:58368
	ds_read_b64_tr_b16 v[92:93], v144 offset:58624
	ds_read_b64_tr_b16 v[94:95], v144 offset:58880
	ds_read_b64_tr_b16 v[96:97], v144 offset:59136
	s_waitcnt lgkmcnt(14)
	v_mfma_f32_32x32x16_bf16 v[50:65], v[154:157], v[82:85], v[50:65]
	v_add_f32_e64 v70, v168, v136
	v_add_f32_e64 v71, v169, v137
	v_cvt_pk_bf16_f32 v73, v138, v136
	s_waitcnt lgkmcnt(12)
	v_mfma_f32_32x32x16_bf16 v[34:49], v[158:161], v[82:85], v[34:49]
	v_add_f32_e64 v158, v70, v70
	v_add_f32_e64 v159, v70, v71
	v_exp_f32_e32 v160, v74
	v_exp_f32_e32 v158, v75
	v_cvt_pk_bf16_f32 v70, v170, v173
	v_cvt_pk_bf16_f32 v71, v181, v183
	v_add_f32_e32 v181, v189, v160
	s_waitcnt lgkmcnt(10)
	v_mfma_f32_32x32x16_bf16 v[18:33], v[162:165], v[82:85], v[18:33]
	s_waitcnt lgkmcnt(8)
	v_mfma_f32_32x32x16_bf16 v[2:17], v[174:177], v[82:85], v[2:17]
	ds_read_b64_tr_b16 v[82:83], v144 offset:61440
	ds_read_b64_tr_b16 v[84:85], v144 offset:61696
	ds_read_b64_tr_b16 v[136:137], v144 offset:61952
	ds_read_b64_tr_b16 v[138:139], v144 offset:62208
	ds_read_b64_tr_b16 v[150:151], v144 offset:62464
	ds_read_b64_tr_b16 v[152:153], v144 offset:62720
	ds_read_b64_tr_b16 v[154:155], v144 offset:62976
	ds_read_b64_tr_b16 v[156:157], v144 offset:63232
	s_waitcnt lgkmcnt(14)
	v_mfma_f32_32x32x16_bf16 v[50:65], v[66:69], v[70:73], v[50:65]
	v_add_f32_e64 v66, v180, v158
	v_add_f32_e64 v67, v181, v159
	s_waitcnt lgkmcnt(0)
	v_add_f32_e64 v68, v66, v66
	v_add_f32_e64 v69, v66, v67
	v_exp_f32_e32 v159, v76
	v_exp_f32_e32 v68, v77
	v_mfma_f32_32x32x16_bf16 v[34:49], v[86:89], v[70:73], v[34:49]
	v_add_f32_e32 v183, v190, v159
	s_barrier
; DI int crow(int i, int h) { return (i & 3) + 8 * (i >> 2) + 4 * h; }
; #define MFMA32(a, b, c) __builtin_amdgcn_mfma_f32_32x32x16_bf16((a), (b), (c), 0, 0, 0)
; template <int DV, int MODE>
; DI void attn_finalize(char* lds, const AttnJob& J, f32x16 (&O)[DV / 32], const float lt, const int wid, const int r, const int h) {
;     ...
;     float* sc = (float*)(lds + 32768) + (wid >> 1) * (DV * 32);
;     if (wid & 1) {
;       const float f = inv * J.lam;
; #pragma unroll
;       for (int d = 0; d < NDV; ++d)
; #pragma unroll
;         for (int i = 0; i < 16; ++i) sc[(32 * d + crow(i, h)) * 32 + r] = O[d][i] * f;
;     }
; template <int DV, int NK, int MODE, bool FIXM, int GRP>
; DI void attn_job(char* lds_wg, const AttnJob& J) {
;     ...
;         for (int ks = 0; ks < 4; ++ks) {
; #pragma unroll
;           for (int d = 0; d < NDV; ++d) O[d] = MFMA32(vf[ks][d], pf[ks], O[d]);
;         }
;         __builtin_amdgcn_sched_group_barrier(0x100, 4 * NDV, 0); __builtin_amdgcn_sched_group_barrier(0x008, NDV, 0);
;         __builtin_amdgcn_sched_group_barrier(0x100, 2 * NDV, 0); __builtin_amdgcn_sched_group_barrier(0x008, NDV, 0);
;         __builtin_amdgcn_sched_group_barrier(0x100, 2 * NDV, 0); __builtin_amdgcn_sched_group_barrier(0x008, 2 * NDV, 0);
	ds_read_b128 v[234:237], v145
	ds_read_b128 v[238:241], v145 offset:4096
	ds_read_b128 v[242:245], v147
	ds_read_b128 v[246:249], v147 offset:4096
	v_add_f32_e64 v66, v182, v68
	v_add_f32_e64 v67, v183, v69
	v_add_f32_e64 v74, v66, v66
	v_add_f32_e64 v75, v66, v67
	v_exp_f32_e32 v69, v78
	v_exp_f32_e32 v74, v79
	v_mfma_f32_32x32x16_bf16 v[18:33], v[90:93], v[70:73], v[18:33]
	v_add_f32_e32 v185, v191, v69
	v_add_f32_e64 v66, v184, v74
	v_add_f32_e64 v67, v185, v75
	v_add_f32_e64 v76, v66, v66
	v_add_f32_e64 v77, v66, v67
	v_cvt_pk_bf16_f32 v67, v159, v68
	v_cvt_pk_bf16_f32 v68, v69, v74
	v_mfma_f32_32x32x16_bf16 v[2:17], v[94:97], v[70:73], v[2:17]
	v_exp_f32_e32 v70, v80
	v_exp_f32_e32 v76, v81
	v_cvt_pk_bf16_f32 v66, v160, v158
	v_add_f32_e32 v187, v192, v70
	v_cvt_pk_bf16_f32 v69, v70, v76
	v_pk_add_f32 v[70:71], v[186:187], v[76:77]
	s_nop 0
	v_mfma_f32_32x32x16_bf16 v[50:65], v[82:85], v[66:69], v[50:65]
	v_mfma_f32_32x32x16_bf16 v[34:49], v[136:139], v[66:69], v[34:49]
	v_mfma_f32_32x32x16_bf16 v[18:33], v[150:153], v[66:69], v[18:33]
	v_add_f32_e32 v150, v70, v71
	v_mfma_f32_32x32x16_bf16 v[2:17], v[154:157], v[66:69], v[2:17]
	s_cbranch_vccnz .LBB0_348
	s_mov_b32 s41, s40
	s_branch .LBB0_340
.LBB0_348:
	s_waitcnt lgkmcnt(0)
	s_and_b64 vcc, exec, s[24:25]
	s_cbranch_vccz .LBB0_292
	v_mov_b32_e32 v66, v150
	s_nop 1
	v_permlane32_swap_b32_e32 v150, v66
	v_add_f32_e32 v66, v150, v66
	v_div_scale_f32 v67, s[2:3], v66, v66, 1.0
	v_rcp_f32_e32 v68, v67
	s_lshl_b32 s2, s39, 13
	s_and_b32 s2, s2, 0x4000
	s_or_b32 s4, s2, 0x10000
	v_fma_f32 v69, -v67, v68, 1.0
	v_fmac_f32_e32 v68, v69, v68
	v_div_scale_f32 v69, vcc, 1.0, v66, 1.0
	v_mul_f32_e32 v70, v69, v68
	v_fma_f32 v71, -v67, v70, v69
	v_fmac_f32_e32 v70, v71, v68
	v_fma_f32 v67, -v67, v70, v69
	v_div_fmas_f32 v67, v67, v68, v70
	s_bitcmp0_b32 s38, 6
	v_div_fixup_f32 v72, v67, v66, 1.0
	s_cselect_b64 s[2:3], -1, 0
	v_lshlrev_b32_e32 v66, 9, v130
	v_lshlrev_b32_e32 v67, 2, v146
	s_and_b64 vcc, exec, s[2:3]
	v_add3_u32 v66, s4, v66, v67
	s_cbranch_vccnz .LBB0_351
	v_mul_f32_e32 v67, v171, v72
	v_mul_f32_e32 v68, v50, v67
	v_mul_f32_e32 v69, v51, v67
	ds_write2_b32 v66, v68, v69 offset1:32
	v_mul_f32_e32 v68, v52, v67
	v_mul_f32_e32 v69, v53, v67
	ds_write2_b32 v66, v68, v69 offset0:64 offset1:96
	v_mul_f32_e32 v68, v54, v67
	v_mul_f32_e32 v69, v55, v67
	v_add_u32_e32 v70, 0x400, v66
	ds_write2_b32 v70, v68, v69 offset1:32
	v_mul_f32_e32 v68, v56, v67
	v_mul_f32_e32 v69, v57, v67
	ds_write2_b32 v70, v68, v69 offset0:64 offset1:96
	v_mul_f32_e32 v68, v58, v67
	v_mul_f32_e32 v69, v59, v67
	v_add_u32_e32 v70, 0x800, v66
	ds_write2_b32 v70, v68, v69 offset1:32
	v_mul_f32_e32 v68, v60, v67
	v_mul_f32_e32 v69, v61, v67
	ds_write2_b32 v70, v68, v69 offset0:64 offset1:96
	v_mul_f32_e32 v68, v62, v67
	v_mul_f32_e32 v69, v63, v67
	v_add_u32_e32 v70, 0xc00, v66
	ds_write2_b32 v70, v68, v69 offset1:32
	v_mul_f32_e32 v68, v64, v67
	v_mul_f32_e32 v69, v65, v67
	ds_write2_b32 v70, v68, v69 offset0:64 offset1:96
	v_mul_f32_e32 v68, v34, v67
	v_mul_f32_e32 v69, v35, v67
	v_add_u32_e32 v70, 0x1000, v66
	ds_write2_b32 v70, v68, v69 offset1:32
	v_mul_f32_e32 v68, v36, v67
	v_mul_f32_e32 v69, v37, v67
	ds_write2_b32 v70, v68, v69 offset0:64 offset1:96
	v_mul_f32_e32 v68, v38, v67
	v_mul_f32_e32 v69, v39, v67
	v_add_u32_e32 v70, 0x1400, v66
	ds_write2_b32 v70, v68, v69 offset1:32
	v_mul_f32_e32 v68, v40, v67
	v_mul_f32_e32 v69, v41, v67
	ds_write2_b32 v70, v68, v69 offset0:64 offset1:96
	v_mul_f32_e32 v68, v42, v67
	v_mul_f32_e32 v69, v43, v67
	v_add_u32_e32 v70, 0x1800, v66
	ds_write2_b32 v70, v68, v69 offset1:32
	v_mul_f32_e32 v68, v44, v67
	v_mul_f32_e32 v69, v45, v67
	ds_write2_b32 v70, v68, v69 offset0:64 offset1:96
	v_mul_f32_e32 v68, v46, v67
	v_mul_f32_e32 v69, v47, v67
	v_add_u32_e32 v70, 0x1c00, v66
	ds_write2_b32 v70, v68, v69 offset1:32
	v_mul_f32_e32 v68, v48, v67
	v_mul_f32_e32 v69, v49, v67
	ds_write2_b32 v70, v68, v69 offset0:64 offset1:96
	v_mul_f32_e32 v68, v18, v67
	v_mul_f32_e32 v69, v19, v67
	v_add_u32_e32 v70, 0x2000, v66
	ds_write2_b32 v70, v68, v69 offset1:32
	v_mul_f32_e32 v68, v20, v67
	v_mul_f32_e32 v69, v21, v67
	ds_write2_b32 v70, v68, v69 offset0:64 offset1:96
	v_mul_f32_e32 v68, v22, v67
	v_mul_f32_e32 v69, v23, v67
	v_add_u32_e32 v70, 0x2400, v66
	ds_write2_b32 v70, v68, v69 offset1:32
	v_mul_f32_e32 v68, v24, v67
	v_mul_f32_e32 v69, v25, v67
	ds_write2_b32 v70, v68, v69 offset0:64 offset1:96
	v_mul_f32_e32 v68, v26, v67
	v_mul_f32_e32 v69, v27, v67
	v_add_u32_e32 v70, 0x2800, v66
	ds_write2_b32 v70, v68, v69 offset1:32
	v_mul_f32_e32 v68, v28, v67
	v_mul_f32_e32 v69, v29, v67
	ds_write2_b32 v70, v68, v69 offset0:64 offset1:96
	v_mul_f32_e32 v68, v30, v67
	v_mul_f32_e32 v69, v31, v67
	v_add_u32_e32 v70, 0x2c00, v66
	ds_write2_b32 v70, v68, v69 offset1:32
	v_mul_f32_e32 v68, v32, v67
	v_mul_f32_e32 v69, v33, v67
	ds_write2_b32 v70, v68, v69 offset0:64 offset1:96
	v_mul_f32_e32 v68, v2, v67
	v_mul_f32_e32 v69, v3, v67
	v_add_u32_e32 v70, 0x3000, v66
	ds_write2_b32 v70, v68, v69 offset1:32
	v_mul_f32_e32 v68, v4, v67
	v_mul_f32_e32 v69, v5, v67
	ds_write2_b32 v70, v68, v69 offset0:64 offset1:96
	v_mul_f32_e32 v68, v6, v67
	v_mul_f32_e32 v69, v7, v67
	v_add_u32_e32 v70, 0x3400, v66
	ds_write2_b32 v70, v68, v69 offset1:32
	v_mul_f32_e32 v68, v8, v67
	v_mul_f32_e32 v69, v9, v67
	ds_write2_b32 v70, v68, v69 offset0:64 offset1:96
	v_mul_f32_e32 v68, v10, v67
	v_mul_f32_e32 v69, v11, v67
	v_add_u32_e32 v70, 0x3800, v66
	ds_write2_b32 v70, v68, v69 offset1:32
	v_mul_f32_e32 v68, v12, v67
	v_mul_f32_e32 v69, v13, v67
	ds_write2_b32 v70, v68, v69 offset0:64 offset1:96
	v_mul_f32_e32 v68, v14, v67
	v_mul_f32_e32 v69, v15, v67
	v_add_u32_e32 v70, 0x3c00, v66
	ds_write2_b32 v70, v68, v69 offset1:32
	v_mul_f32_e32 v68, v16, v67
	v_mul_f32_e32 v67, v17, v67
	ds_write2_b32 v70, v68, v67 offset0:64 offset1:96

; DI unsigned cvtpk(float lo, float hi) { f32x2 v = {lo, hi}; bf16x2_t b = __builtin_convertvector(v, bf16x2_t); return __builtin_bit_cast(unsigned, b); }
; DI void head_store(f32x16 v0, f32x16 v1, float rs, int mode, const float* gain, const Params& p, int pos, bf16_t* obase, int ldo, char* stg_wg) {
;     ...
; #pragma unroll
;   for (int g4 = 0; g4 < 4; ++g4) {
;     u32x2 w0, w1; w0.x = cvtpk(v0[4 * g4], v0[4 * g4 + 1]); w0.y = cvtpk(v0[4 * g4 + 2], v0[4 * g4 + 3]);
;     w1.x = cvtpk(v1[4 * g4], v1[4 * g4 + 1]); w1.y = cvtpk(v1[4 * g4 + 2], v1[4 * g4 + 3]);
;     *(u32x2*)(stg + r * 128 + ((g4 ^ (r & 7)) << 4) + h * 8) = w0;
;     *(u32x2*)(stg + r * 128 + (((4 + g4) ^ (r & 7)) << 4) + h * 8) = w1;
;   }
; #pragma unroll
;   for (int j = 0; j < 4; ++j) {
;     const int row = (lane >> 3) + 8 * j, ch = lane & 7;
;     const u32x4 w = *(const u32x4*)(stg + row * 128 + ((ch ^ (row & 7)) << 4));
;     *(u32x4*)(obase + (size_t)row * ldo + ch * 8) = w;
;   }
.LBB0_515:
	v_lshlrev_b32_e32 v0, 6, v68
	v_and_b32_e32 v0, 0xfffff000, v0
	v_add_u32_e32 v3, 0x20000, v0
	v_lshlrev_b32_e32 v0, 7, v68
	v_and_b32_e32 v0, 0xf80, v0
	v_and_b32_e32 v8, 7, v68
	v_lshlrev_b32_e32 v4, 3, v69
	v_or3_b32 v9, v3, v0, v4
	v_lshlrev_b32_e32 v0, 4, v8
	v_cvt_pk_bf16_f32 v4, v18, v19
	v_cvt_pk_bf16_f32 v5, v20, v21
	v_or_b32_e32 v8, v9, v0
	ds_write_b64 v8, v[4:5]
	v_xor_b32_e32 v4, 64, v0
	v_cvt_pk_bf16_f32 v6, v60, v61
	v_cvt_pk_bf16_f32 v7, v58, v59
	v_or_b32_e32 v4, v9, v4
	v_xor_b32_e32 v8, 16, v0
	ds_write_b64 v4, v[6:7]
	v_cvt_pk_bf16_f32 v4, v46, v47
	v_cvt_pk_bf16_f32 v5, v54, v55
	v_or_b32_e32 v8, v9, v8
	ds_write_b64 v8, v[4:5]
	v_xor_b32_e32 v4, 0x50, v0
	v_cvt_pk_bf16_f32 v6, v62, v63
	v_cvt_pk_bf16_f32 v7, v64, v65
	v_or_b32_e32 v4, v9, v4
	v_xor_b32_e32 v8, 32, v0
	ds_write_b64 v4, v[6:7]
	v_cvt_pk_bf16_f32 v4, v26, v27
	v_cvt_pk_bf16_f32 v5, v28, v29
	v_or_b32_e32 v8, v9, v8
	ds_write_b64 v8, v[4:5]
	v_xor_b32_e32 v4, 0x60, v0
	v_cvt_pk_bf16_f32 v6, v36, v37
	v_cvt_pk_bf16_f32 v7, v24, v25
	v_or_b32_e32 v4, v9, v4
	v_xor_b32_e32 v8, 48, v0
	v_and_b32_e32 v2, 63, v68
	ds_write_b64 v4, v[6:7]
	v_cvt_pk_bf16_f32 v4, v30, v31
	v_cvt_pk_bf16_f32 v5, v32, v33
	v_or_b32_e32 v8, v9, v8
	ds_write_b64 v8, v[4:5]
	v_xor_b32_e32 v4, 0x70, v0
	v_lshrrev_b32_e32 v8, 3, v2
	v_cvt_pk_bf16_f32 v6, v50, v51
	v_cvt_pk_bf16_f32 v7, v66, v67
	v_or_b32_e32 v4, v9, v4
	v_bitop3_b32 v2, v8, v68, 7 bitop3:0x78
	ds_write_b64 v4, v[6:7]
	v_lshlrev_b32_e32 v2, 4, v2
	v_lshl_add_u64 v[6:7], s[0:1], 0, v[0:1]
	v_lshlrev_b32_e32 v0, 7, v8
	v_or3_b32 v14, v3, v2, v0
	ds_read_b128 v[2:5], v14
	v_mul_u32_u24_e32 v0, 0xf00, v8
	v_lshlrev_b32_e32 v0, 1, v0
	v_lshl_add_u64 v[10:11], v[6:7], 0, v[0:1]
	ds_read_b128 v[6:9], v14 offset:1024
	s_waitcnt lgkmcnt(1)
	global_store_dwordx4 v[10:11], v[2:5], off offset:128
	v_mov_b64_e32 v[178:179], v[174:175]
	v_mov_b64_e32 v[176:177], v[172:173]
	v_add_co_u32_e32 v2, vcc, 0xf000, v10
	s_mov_b32 s38, s11
	s_nop 0
	v_addc_co_u32_e32 v3, vcc, 0, v11, vcc
	s_waitcnt lgkmcnt(0)
	global_store_dwordx4 v[2:3], v[6:9], off offset:128
	ds_read_b128 v[2:5], v14 offset:2048
	ds_read_b128 v[6:9], v14 offset:3072
	v_add_co_u32_e32 v12, vcc, 0x1e000, v10
	s_mov_b32 s39, s33
	s_nop 0
	v_addc_co_u32_e32 v13, vcc, 0, v11, vcc
	s_waitcnt lgkmcnt(1)
	global_store_dwordx4 v[12:13], v[2:5], off offset:128
	s_nop 1
	v_add_co_u32_e32 v2, vcc, 0x2d000, v10
	s_nop 1
	v_addc_co_u32_e32 v3, vcc, 0, v11, vcc
	s_andn2_b64 vcc, exec, s[30:31]
	s_waitcnt lgkmcnt(0)
	global_store_dwordx4 v[2:3], v[6:9], off offset:128
	v_mov_b64_e32 v[166:167], 0x78000
	v_mov_b32_e32 v214, 0x1000
	s_cbranch_vccz .LBB0_506

; DI float swapsum(float v) { auto rr = __builtin_amdgcn_permlane32_swap(__float_as_uint(v), __float_as_uint(v), false, false); return __uint_as_float(rr[0]) + __uint_as_float(rr[1]); }
; DI void head_store(f32x16 v0, f32x16 v1, float rs, int mode, const float* gain, const Params& p, int pos, bf16_t* obase, int ldo, char* stg_wg) {
;     ...
;   v0 *= rs; v1 *= rs;
;   if (mode) {
;     float ss = 0.f;
; #pragma unroll
;     for (int i = 0; i < 16; ++i) ss += v0[i] * v0[i] + v1[i] * v1[i];
;     ss = swapsum(ss);
;     const float inv = rsqrtf(ss * (1.f / 64.f) + EPSF);
; #pragma unroll
;     for (int g4 = 0; g4 < 4; ++g4) {
;       const f32x4 ga = *(const f32x4*)(gain + 8 * g4 + 4 * h), gb = *(const f32x4*)(gain + 32 + 8 * g4 + 4 * h);
; #pragma unroll
;       for (int j = 0; j < 4; ++j) { v0[4 * g4 + j] *= inv * ga[j]; v1[4 * g4 + j] *= inv * gb[j]; }
;     }
; template <int EPI>
; DI void gemm_phase(char* lds, const Params& p, const GemmDesc g, int layer) {
;     ...
;         const int n_h = n_w + 64 * hu; const float* gain; const int mode = in_mode(p, layer, n_h, gain);
; #pragma unroll
;         for (int mi = 0; mi < 2; ++mi) {
;           const int t = mt * 256 + wm * 64 + mi * 32 + r;
;           int S, seq0, pos, sq; tok_info(t, S, seq0, pos, sq);
;           const float rs = rsqrtf(p.rstd[(layer & 1) * NTOK + t] * (1.f / DM) + EPSF);
.LBB0_550:
	s_lshl_b32 s0, s39, 8
	s_add_i32 s0, s0, s10
	v_or_b32_e32 v0, s0, v162
	v_add_u32_e32 v176, s26, v0
	v_readlane_b32 s40, v254, 49
	v_ashrrev_i32_e32 v177, 31, v176
	v_readlane_b32 s42, v254, 51
	v_readlane_b32 s43, v254, 52
	s_mov_b32 s1, 0x10000
	v_cmp_gt_i32_e32 vcc, s1, v0
	v_lshl_add_u64 v[176:177], v[176:177], 2, s[42:43]
	global_load_dword v0, v[176:177], off
	global_load_dword v214, v[176:177], off offset:128
	v_cndmask_b32_e32 v163, v220, v221, vcc
	v_bitop3_b32 v163, v163, s0, v162 bitop3:0xe0
	v_mov_b32 v232, v212
	v_readlane_b32 s41, v254, 50
	v_bfe_u32 v233, v232, 5, 1
	s_waitcnt vmcnt(0)
	v_mov_b32_e32 v166, v0
	v_fmamk_f32 v0, v0, 0x3a800000, v213
	v_cmp_gt_f32_e32 vcc, s37, v0
	v_mul_f32_e32 v178, 0x4b800000, v0
	s_nop 0
	v_cndmask_b32_e32 v0, v0, v178, vcc
	v_rsq_f32_e32 v0, v0
	s_nop 0
	v_mul_f32_e32 v178, 0x45800000, v0
	v_cndmask_b32_e32 v0, v0, v178, vcc
	v_pk_mul_f32 v[128:129], v[128:129], v[0:1] op_sel_hi:[1,0]
	v_pk_mul_f32 v[126:127], v[126:127], v[0:1] op_sel_hi:[1,0]
	v_pk_mul_f32 v[124:125], v[124:125], v[0:1] op_sel_hi:[1,0]
	v_pk_mul_f32 v[122:123], v[122:123], v[0:1] op_sel_hi:[1,0]
	v_pk_mul_f32 v[120:121], v[120:121], v[0:1] op_sel_hi:[1,0]
	v_pk_mul_f32 v[118:119], v[118:119], v[0:1] op_sel_hi:[1,0]
	v_pk_mul_f32 v[116:117], v[116:117], v[0:1] op_sel_hi:[1,0]
	v_pk_mul_f32 v[114:115], v[114:115], v[0:1] op_sel_hi:[1,0]
	v_pk_mul_f32 v[208:209], v[112:113], v[0:1] op_sel_hi:[1,0]
	v_pk_mul_f32 v[110:111], v[110:111], v[0:1] op_sel_hi:[1,0]
	v_pk_mul_f32 v[108:109], v[108:109], v[0:1] op_sel_hi:[1,0]
	v_pk_mul_f32 v[106:107], v[106:107], v[0:1] op_sel_hi:[1,0]
	v_pk_mul_f32 v[202:203], v[104:105], v[0:1] op_sel_hi:[1,0]
	v_pk_mul_f32 v[186:187], v[102:103], v[0:1] op_sel_hi:[1,0]
	v_pk_mul_f32 v[102:103], v[100:101], v[0:1] op_sel_hi:[1,0]
	v_pk_mul_f32 v[112:113], v[98:99], v[0:1] op_sel_hi:[1,0]
	s_and_b64 vcc, exec, s[92:93]
	s_cbranch_vccnz .LBB0_558
	v_mul_f32_e32 v0, v112, v112
	v_mul_f32_e32 v98, v113, v113
	v_fmac_f32_e32 v0, v114, v114
	v_fmac_f32_e32 v98, v115, v115
	v_add_f32_e32 v0, v0, v98
	v_mul_f32_e32 v98, v102, v102
	v_fmac_f32_e32 v98, v116, v116
	v_add_f32_e32 v0, v98, v0
	v_mul_f32_e32 v98, v103, v103
	v_fmac_f32_e32 v98, v117, v117
	v_add_f32_e32 v0, v98, v0
	v_mul_f32_e32 v98, v186, v186
	v_fmac_f32_e32 v98, v118, v118
	v_add_f32_e32 v0, v98, v0
	v_mul_f32_e32 v98, v187, v187
	v_fmac_f32_e32 v98, v119, v119
	v_add_f32_e32 v0, v98, v0
	v_mul_f32_e32 v98, v202, v202
	v_fmac_f32_e32 v98, v120, v120
	v_add_f32_e32 v0, v98, v0
	v_mul_f32_e32 v98, v203, v203
	v_fmac_f32_e32 v98, v121, v121
	v_add_f32_e32 v0, v98, v0
	v_mul_f32_e32 v98, v106, v106
	v_fmac_f32_e32 v98, v122, v122
	v_add_f32_e32 v0, v98, v0
	v_mul_f32_e32 v98, v107, v107
	v_fmac_f32_e32 v98, v123, v123
	v_add_f32_e32 v0, v98, v0
	v_pk_mul_f32 v[98:99], v[108:109], v[108:109]
	v_pk_mul_f32 v[100:101], v[110:111], v[110:111]
	v_pk_fma_f32 v[98:99], v[124:125], v[124:125], v[98:99]
	v_pk_fma_f32 v[100:101], v[126:127], v[126:127], v[100:101]
	v_add_f32_e32 v0, v98, v0
	v_add_f32_e32 v0, v99, v0
	v_pk_mul_f32 v[104:105], v[208:209], v[208:209]
	v_add_f32_e32 v0, v100, v0
	v_pk_fma_f32 v[104:105], v[128:129], v[128:129], v[104:105]
	v_add_f32_e32 v0, v101, v0
	v_add_f32_e32 v0, v104, v0
	v_add_f32_e32 v0, v105, v0
	v_mov_b32_e32 v98, v0
	s_nop 1
	v_permlane32_swap_b32_e32 v0, v98
	v_add_f32_e32 v0, v0, v98
	v_fmamk_f32 v0, v0, 0x3c800000, v213
	v_cmp_gt_f32_e32 vcc, s37, v0
	v_mul_f32_e32 v98, 0x4b800000, v0
	v_lshlrev_b32_e32 v190, 4, v233
	v_cndmask_b32_e32 v0, v0, v98, vcc
	v_rsq_f32_e32 v0, v0
	v_lshlrev_b32_e32 v234, 2, v233
	s_mov_b64 s[88:89], -1
	s_cmp_gt_i32 s38, 2
	v_mul_f32_e32 v98, 0x45800000, v0
	v_cndmask_b32_e32 v0, v0, v98, vcc
	global_load_dwordx4 v[98:101], v190, s[16:17]
	global_load_dwordx4 v[178:181], v190, s[16:17] offset:128
	s_waitcnt vmcnt(1)
	v_pk_mul_f32 v[98:99], v[98:99], v[0:1] op_sel_hi:[1,0]
	s_nop 0
	v_pk_mul_f32 v[182:183], v[114:115], v[98:99]
	s_waitcnt vmcnt(0)
	v_pk_mul_f32 v[98:99], v[178:179], v[0:1] op_sel_hi:[1,0]
	v_pk_mul_f32 v[100:101], v[100:101], v[0:1] op_sel_hi:[1,0]
	v_pk_mul_f32 v[98:99], v[112:113], v[98:99]
	v_pk_mul_f32 v[188:189], v[116:117], v[100:101]
	v_pk_mul_f32 v[100:101], v[180:181], v[0:1] op_sel_hi:[1,0]
	global_load_dwordx4 v[112:115], v190, s[16:17] offset:32
	global_load_dwordx4 v[178:181], v190, s[16:17] offset:160
	v_pk_mul_f32 v[100:101], v[102:103], v[100:101]
	s_waitcnt vmcnt(1)
	v_pk_mul_f32 v[102:103], v[112:113], v[0:1] op_sel_hi:[1,0]
	s_nop 0
	v_pk_mul_f32 v[192:193], v[118:119], v[102:103]
	s_waitcnt vmcnt(0)
	v_pk_mul_f32 v[102:103], v[178:179], v[0:1] op_sel_hi:[1,0]
	s_nop 0
	v_pk_mul_f32 v[104:105], v[186:187], v[102:103]
	v_pk_mul_f32 v[102:103], v[114:115], v[0:1] op_sel_hi:[1,0]
	global_load_dwordx4 v[112:115], v190, s[16:17] offset:64
	global_load_dwordx4 v[116:119], v190, s[16:17] offset:192
	v_pk_mul_f32 v[194:195], v[120:121], v[102:103]
	v_pk_mul_f32 v[102:103], v[180:181], v[0:1] op_sel_hi:[1,0]
	s_nop 0
	v_pk_mul_f32 v[178:179], v[202:203], v[102:103]
	s_waitcnt vmcnt(1)
	v_pk_mul_f32 v[102:103], v[112:113], v[0:1] op_sel_hi:[1,0]
	s_nop 0
	v_pk_mul_f32 v[204:205], v[122:123], v[102:103]
	s_waitcnt vmcnt(0)
	v_pk_mul_f32 v[102:103], v[116:117], v[0:1] op_sel_hi:[1,0]
	s_nop 0
	v_pk_mul_f32 v[180:181], v[106:107], v[102:103]
	v_pk_mul_f32 v[102:103], v[114:115], v[0:1] op_sel_hi:[1,0]
	s_nop 0
	v_pk_mul_f32 v[206:207], v[124:125], v[102:103]
	v_pk_mul_f32 v[102:103], v[118:119], v[0:1] op_sel_hi:[1,0]
	s_nop 0
	v_pk_mul_f32 v[184:185], v[108:109], v[102:103]
	global_load_dwordx4 v[106:109], v190, s[16:17] offset:96
	global_load_dwordx4 v[112:115], v190, s[16:17] offset:224
	s_waitcnt vmcnt(1)
	v_pk_mul_f32 v[102:103], v[106:107], v[0:1] op_sel_hi:[1,0]
	s_nop 0
	v_pk_mul_f32 v[210:211], v[126:127], v[102:103]
	s_waitcnt vmcnt(0)
	v_pk_mul_f32 v[102:103], v[112:113], v[0:1] op_sel_hi:[1,0]
	s_nop 0
	v_pk_mul_f32 v[190:191], v[110:111], v[102:103]
	v_mul_f32_e32 v102, v108, v0
	v_mul_f32_e32 v196, v128, v102
	v_mul_f32_e32 v102, v114, v0
	v_mov_b32_e32 v108, v115
	v_mul_f32_e32 v198, v208, v102
	v_pk_mul_f32 v[102:103], v[108:109], v[0:1] op_sel_hi:[1,0]
	v_mov_b32_e32 v128, v209
	v_pk_mul_f32 v[200:201], v[128:129], v[102:103]
	s_cbranch_scc0 .LBB0_553
; DI void head_store(f32x16 v0, f32x16 v1, float rs, int mode, const float* gain, const Params& p, int pos, bf16_t* obase, int ldo, char* stg_wg) {
;     ...
;     if (mode == 2) {
; #pragma unroll
;       for (int g4 = 0; g4 < 4; ++g4) {
;         const f32x4 c = *(const f32x4*)(p.tab1c + pos * 32 + 8 * g4 + 4 * h), s = *(const f32x4*)(p.tab1s + pos * 32 + 8 * g4 + 4 * h);
; #pragma unroll
;         for (int j = 0; j < 4; ++j) { const int i = 4 * g4 + j; const float x1 = v0[i], x2 = v1[i]; v0[i] = x1 * c[j] - x2 * s[j]; v1[i] = x2 * c[j] + x1 * s[j]; }
;       }
	v_and_b32_e32 v0, 0x1fc0, v163
	v_lshl_add_u64 v[102:103], s[80:81], 0, v[0:1]
	v_lshlrev_b32_e32 v106, 2, v234
	v_mov_b32_e32 v107, v1
	v_lshl_add_u64 v[110:111], v[102:103], 0, v[106:107]
	v_lshl_add_u64 v[102:103], s[82:83], 0, v[0:1]
	v_lshlrev_b32_e32 v0, 6, v163
	v_and_b32_e32 v0, 0x7c0, v0
	v_lshl_add_u64 v[120:121], v[102:103], 0, v[106:107]
	v_lshl_add_u64 v[102:103], s[80:81], 0, v[0:1]
	v_lshl_add_u64 v[186:187], v[102:103], 0, v[106:107]
	v_lshl_add_u64 v[102:103], s[82:83], 0, v[0:1]
	v_lshl_add_u64 v[202:203], v[102:103], 0, v[106:107]
	global_load_dwordx4 v[106:109], v[110:111], off
	global_load_dwordx4 v[116:119], v[120:121], off
	global_load_dwordx4 v[124:127], v[186:187], off
	global_load_dwordx4 v[236:239], v[202:203], off
	v_mov_b32_e32 v197, v201
	v_mov_b32_e32 v199, v200
	s_mov_b64 s[88:89], 0
	s_waitcnt vmcnt(2)
	v_pk_mul_f32 v[102:103], v[204:205], v[116:117]
	s_nop 0
	v_pk_fma_f32 v[114:115], v[182:183], v[106:107], v[102:103] neg_lo:[0,0,1] neg_hi:[0,0,1]
	v_pk_mul_f32 v[102:103], v[182:183], v[116:117]
	s_nop 0
	v_pk_fma_f32 v[122:123], v[204:205], v[106:107], v[102:103]
	s_waitcnt vmcnt(0)
	v_pk_mul_f32 v[102:103], v[180:181], v[236:237]
	s_nop 0
	v_pk_fma_f32 v[112:113], v[98:99], v[124:125], v[102:103] neg_lo:[0,0,1] neg_hi:[0,0,1]
	v_pk_mul_f32 v[102:103], v[98:99], v[236:237]
	s_nop 0
	v_pk_fma_f32 v[106:107], v[180:181], v[124:125], v[102:103]
	v_pk_mul_f32 v[102:103], v[206:207], v[118:119]
	s_nop 0
	v_pk_fma_f32 v[116:117], v[188:189], v[108:109], v[102:103] neg_lo:[0,0,1] neg_hi:[0,0,1]
	v_pk_mul_f32 v[102:103], v[188:189], v[118:119]
	s_nop 0
	v_pk_fma_f32 v[124:125], v[206:207], v[108:109], v[102:103]
	v_pk_mul_f32 v[102:103], v[184:185], v[238:239]
	v_pk_mul_f32 v[108:109], v[100:101], v[238:239]
	v_pk_fma_f32 v[102:103], v[100:101], v[126:127], v[102:103] neg_lo:[0,0,1] neg_hi:[0,0,1]
	v_pk_fma_f32 v[108:109], v[184:185], v[126:127], v[108:109]
	global_load_dwordx4 v[126:129], v[110:111], off offset:32
	global_load_dwordx4 v[236:239], v[120:121], off offset:32
	global_load_dwordx4 v[240:243], v[186:187], off offset:32
	global_load_dwordx4 v[244:247], v[202:203], off offset:32
	s_waitcnt vmcnt(3)
	v_mul_f32_e32 v202, v196, v128
	s_waitcnt vmcnt(2)
	v_pk_mul_f32 v[110:111], v[210:211], v[236:237]
	v_mul_f32_e32 v208, v194, v238
	v_pk_fma_f32 v[118:119], v[192:193], v[126:127], v[110:111] neg_lo:[0,0,1] neg_hi:[0,0,1]
	v_pk_mul_f32 v[110:111], v[192:193], v[236:237]
	v_pk_mul_f32 v[120:121], v[196:197], v[238:239]
	v_pk_fma_f32 v[126:127], v[210:211], v[126:127], v[110:111]
	s_waitcnt vmcnt(0)
	v_pk_mul_f32 v[110:111], v[190:191], v[244:245]
	v_mov_b32_e32 v238, v129
	v_pk_fma_f32 v[186:187], v[104:105], v[240:241], v[110:111] neg_lo:[0,0,1] neg_hi:[0,0,1]
	v_pk_mul_f32 v[110:111], v[104:105], v[244:245]
	v_mov_b32_e32 v244, v201
	v_mov_b32_e32 v245, v195
	v_pk_fma_f32 v[120:121], v[194:195], v[128:129], v[120:121] neg_lo:[0,0,1] neg_hi:[0,0,1]
	v_pk_mul_f32 v[128:129], v[244:245], v[238:239]
	v_pk_fma_f32 v[110:111], v[190:191], v[240:241], v[110:111]
	v_mov_b32_e32 v203, v128
	v_mov_b32_e32 v209, v129
	v_mul_f32_e32 v240, v178, v246
	v_pk_add_f32 v[128:129], v[202:203], v[208:209]
	v_pk_mul_f32 v[202:203], v[198:199], v[246:247]
	v_mov_b32_e32 v208, v200
	v_mov_b32_e32 v209, v179
	v_mov_b32_e32 v246, v243
	v_pk_mul_f32 v[208:209], v[208:209], v[246:247]
	v_mul_f32_e32 v236, v198, v242
	v_mov_b32_e32 v237, v208
	v_mov_b32_e32 v241, v209
	v_pk_fma_f32 v[202:203], v[178:179], v[242:243], v[202:203] neg_lo:[0,0,1] neg_hi:[0,0,1]
	v_pk_add_f32 v[208:209], v[236:237], v[240:241]

; DI unsigned cvtpk(float lo, float hi) { f32x2 v = {lo, hi}; bf16x2_t b = __builtin_convertvector(v, bf16x2_t); return __builtin_bit_cast(unsigned, b); }
; DI void head_store(f32x16 v0, f32x16 v1, float rs, int mode, const float* gain, const Params& p, int pos, bf16_t* obase, int ldo, char* stg_wg) {
;     ...
; #pragma unroll
;   for (int g4 = 0; g4 < 4; ++g4) {
;     u32x2 w0, w1; w0.x = cvtpk(v0[4 * g4], v0[4 * g4 + 1]); w0.y = cvtpk(v0[4 * g4 + 2], v0[4 * g4 + 3]);
;     w1.x = cvtpk(v1[4 * g4], v1[4 * g4 + 1]); w1.y = cvtpk(v1[4 * g4 + 2], v1[4 * g4 + 3]);
;     *(u32x2*)(stg + r * 128 + ((g4 ^ (r & 7)) << 4) + h * 8) = w0;
;     *(u32x2*)(stg + r * 128 + (((4 + g4) ^ (r & 7)) << 4) + h * 8) = w1;
;   }
; #pragma unroll
;   for (int j = 0; j < 4; ++j) {
;     const int row = (lane >> 3) + 8 * j, ch = lane & 7;
;     const u32x4 w = *(const u32x4*)(stg + row * 128 + ((ch ^ (row & 7)) << 4));
;     *(u32x4*)(obase + (size_t)row * ldo + ch * 8) = w;
;   }
; template <int EPI>
; DI void gemm_phase(char* lds, const Params& p, const GemmDesc g, int layer) {
;     ...
;           const int t = mt * 256 + wm * 64 + mi * 32 + r;
;           int S, seq0, pos, sq; tok_info(t, S, seq0, pos, sq);
;           const float rs = rsqrtf(p.rstd[(layer & 1) * NTOK + t] * (1.f / DM) + EPSF);
;           head_store(acc[mi][2 * hu], acc[mi][2 * hu + 1], rs, mode, gain, p, pos, p.u + (size_t)(t - r) * UW + n_h, UW, lds + 131072);
.LBB0_558:
	v_lshlrev_b32_e32 v0, 6, v232
	v_and_b32_e32 v0, 0xfffff000, v0
	v_add_u32_e32 v99, 0x20000, v0
	v_lshlrev_b32_e32 v0, 7, v232
	v_and_b32_e32 v0, 0xf80, v0
	v_and_b32_e32 v178, 7, v232
	v_lshlrev_b32_e32 v100, 3, v233
	v_or3_b32 v179, v99, v0, v100
	v_lshlrev_b32_e32 v0, 4, v178
	v_cvt_pk_bf16_f32 v100, v114, v115
	v_cvt_pk_bf16_f32 v101, v116, v117
	v_cvt_pk_bf16_f32 v105, v102, v103
	v_or_b32_e32 v102, v179, v0
	ds_write_b64 v102, v[100:101]
	v_xor_b32_e32 v100, 64, v0
	v_cvt_pk_bf16_f32 v104, v112, v113
	v_or_b32_e32 v100, v179, v100
	ds_write_b64 v100, v[104:105]
	v_xor_b32_e32 v104, 16, v0
	v_cvt_pk_bf16_f32 v100, v118, v119
	v_cvt_pk_bf16_f32 v101, v120, v121
	v_or_b32_e32 v104, v179, v104
	ds_write_b64 v104, v[100:101]
	v_xor_b32_e32 v100, 0x50, v0
	v_cvt_pk_bf16_f32 v102, v186, v187
	v_cvt_pk_bf16_f32 v103, v202, v203
	v_or_b32_e32 v100, v179, v100
	v_xor_b32_e32 v104, 32, v0
	v_readlane_b32 s44, v254, 33
	ds_write_b64 v100, v[102:103]
	v_cvt_pk_bf16_f32 v100, v122, v123
	v_cvt_pk_bf16_f32 v101, v124, v125
	v_or_b32_e32 v104, v179, v104
	s_xor_b64 s[90:91], s[92:93], -1
	s_ashr_i32 s97, s96, 31
	s_ashr_i32 s1, s0, 31
	s_mul_i32 s40, s0, 0x1e00
	v_readlane_b32 s48, v254, 37
	ds_write_b64 v104, v[100:101]
	v_xor_b32_e32 v100, 0x60, v0
	s_mul_hi_i32 s39, s0, 0x1e00
	v_readlane_b32 s49, v254, 38
	s_add_u32 s40, s48, s40
	v_cvt_pk_bf16_f32 v102, v106, v107
	v_cvt_pk_bf16_f32 v103, v108, v109
	v_or_b32_e32 v100, v179, v100
	v_xor_b32_e32 v104, 48, v0
	v_and_b32_e32 v98, 63, v232
	s_addc_u32 s39, s49, s39
	s_lshl_b64 s[88:89], s[96:97], 1
	ds_write_b64 v100, v[102:103]
	v_cvt_pk_bf16_f32 v100, v126, v127
	v_cvt_pk_bf16_f32 v101, v128, v129
	v_or_b32_e32 v104, v179, v104
	s_add_u32 s92, s40, s88
	ds_write_b64 v104, v[100:101]
	v_xor_b32_e32 v100, 0x70, v0
	v_lshrrev_b32_e32 v104, 3, v98
	s_addc_u32 s93, s39, s89
	v_cvt_pk_bf16_f32 v102, v110, v111
	v_cvt_pk_bf16_f32 v103, v208, v209
	v_or_b32_e32 v100, v179, v100
	v_bitop3_b32 v98, v104, v232, 7 bitop3:0x78
	ds_write_b64 v100, v[102:103]
	v_lshlrev_b32_e32 v98, 4, v98
	v_lshl_add_u64 v[102:103], s[92:93], 0, v[0:1]
	v_lshlrev_b32_e32 v0, 7, v104
	v_or3_b32 v110, v99, v98, v0
	ds_read_b128 v[98:101], v110
	v_mul_u32_u24_e32 v0, 0xf00, v104
	v_lshlrev_b32_e32 v0, 1, v0
	v_lshl_add_u64 v[106:107], v[102:103], 0, v[0:1]
	ds_read_b128 v[102:105], v110 offset:1024
	s_mov_b32 s39, 0xf000
	s_waitcnt lgkmcnt(1)
	global_store_dwordx4 v[106:107], v[98:101], off
	v_readlane_b32 s40, v254, 49
	v_readlane_b32 s42, v254, 51
	v_add_co_u32_e32 v98, vcc, s39, v106
	s_mov_b32 s39, 0x1e000
	s_nop 0
	v_addc_co_u32_e32 v99, vcc, 0, v107, vcc
	s_waitcnt lgkmcnt(0)
	global_store_dwordx4 v[98:99], v[102:105], off
	ds_read_b128 v[98:101], v110 offset:2048
	ds_read_b128 v[102:105], v110 offset:3072
	v_add_co_u32_e32 v108, vcc, s39, v106
	s_mov_b32 s39, 0x2d000
	s_nop 0
	v_addc_co_u32_e32 v109, vcc, 0, v107, vcc
	s_waitcnt lgkmcnt(1)
	global_store_dwordx4 v[108:109], v[98:101], off
	v_readlane_b32 s43, v254, 52
	v_readlane_b32 s45, v254, 34
	v_add_co_u32_e32 v98, vcc, s39, v106
	s_or_b32 s39, s0, 32
	s_nop 0
	v_addc_co_u32_e32 v99, vcc, 0, v107, vcc
	s_waitcnt lgkmcnt(0)
	global_store_dwordx4 v[98:99], v[102:105], off
	v_lshl_add_u64 v[98:99], s[0:1], 0, v[170:171]
	v_lshl_add_u64 v[98:99], v[98:99], 2, s[42:43]
	v_mov_b32_e32 v0, v214
	v_or_b32_e32 v100, s39, v162
	s_mov_b32 s0, 0x10000
	v_cmp_gt_i32_e64 s[0:1], s0, v100
	v_mov_b32 v183, v212
	v_readlane_b32 s46, v254, 35
	v_bfe_u32 v184, v183, 5, 1
	v_cndmask_b32_e64 v100, v218, v219, s[0:1]
	v_bitop3_b32 v182, v100, s39, v162 bitop3:0xe0
	v_readlane_b32 s47, v254, 36
	v_readlane_b32 s50, v254, 39
	v_readlane_b32 s51, v254, 40
	v_readlane_b32 s52, v254, 41
	v_readlane_b32 s53, v254, 42
	v_readlane_b32 s54, v254, 43
	v_readlane_b32 s55, v254, 44
	v_readlane_b32 s56, v254, 45
	v_readlane_b32 s57, v254, 46
	v_readlane_b32 s58, v254, 47
	v_readlane_b32 s59, v254, 48
	v_readlane_b32 s41, v254, 50
	s_waitcnt vmcnt(4)
	v_fmamk_f32 v0, v0, 0x3a800000, v213
	v_mul_f32_e32 v101, 0x4b800000, v0
	v_cmp_gt_f32_e32 vcc, s37, v0
	s_nop 1
	v_cndmask_b32_e32 v0, v0, v101, vcc
	v_rsq_f32_e32 v0, v0
	s_nop 0
	v_mul_f32_e32 v100, 0x45800000, v0
	v_cndmask_b32_e32 v0, v0, v100, vcc
	v_pk_mul_f32 v[96:97], v[96:97], v[0:1] op_sel_hi:[1,0]
	v_pk_mul_f32 v[94:95], v[94:95], v[0:1] op_sel_hi:[1,0]
	v_pk_mul_f32 v[92:93], v[92:93], v[0:1] op_sel_hi:[1,0]
	v_pk_mul_f32 v[90:91], v[90:91], v[0:1] op_sel_hi:[1,0]
	v_pk_mul_f32 v[88:89], v[88:89], v[0:1] op_sel_hi:[1,0]
	v_pk_mul_f32 v[86:87], v[86:87], v[0:1] op_sel_hi:[1,0]
	v_pk_mul_f32 v[84:85], v[84:85], v[0:1] op_sel_hi:[1,0]
	v_pk_mul_f32 v[82:83], v[82:83], v[0:1] op_sel_hi:[1,0]
	v_pk_mul_f32 v[180:181], v[80:81], v[0:1] op_sel_hi:[1,0]
	v_pk_mul_f32 v[78:79], v[78:79], v[0:1] op_sel_hi:[1,0]
	v_pk_mul_f32 v[76:77], v[76:77], v[0:1] op_sel_hi:[1,0]
	v_pk_mul_f32 v[74:75], v[74:75], v[0:1] op_sel_hi:[1,0]
	v_pk_mul_f32 v[116:117], v[72:73], v[0:1] op_sel_hi:[1,0]
	v_pk_mul_f32 v[70:71], v[70:71], v[0:1] op_sel_hi:[1,0]
	v_pk_mul_f32 v[68:69], v[68:69], v[0:1] op_sel_hi:[1,0]
	s_andn2_b64 vcc, exec, s[90:91]
	v_pk_mul_f32 v[66:67], v[66:67], v[0:1] op_sel_hi:[1,0]
	s_cbranch_vccnz .LBB0_566
; DI float swapsum(float v) { auto rr = __builtin_amdgcn_permlane32_swap(__float_as_uint(v), __float_as_uint(v), false, false); return __uint_as_float(rr[0]) + __uint_as_float(rr[1]); }
; DI void head_store(f32x16 v0, f32x16 v1, float rs, int mode, const float* gain, const Params& p, int pos, bf16_t* obase, int ldo, char* stg_wg) {
;     ...
;   if (mode) {
;     float ss = 0.f;
; #pragma unroll
;     for (int i = 0; i < 16; ++i) ss += v0[i] * v0[i] + v1[i] * v1[i];
;     ss = swapsum(ss);
;     const float inv = rsqrtf(ss * (1.f / 64.f) + EPSF);
; #pragma unroll
;     for (int g4 = 0; g4 < 4; ++g4) {
;       const f32x4 ga = *(const f32x4*)(gain + 8 * g4 + 4 * h), gb = *(const f32x4*)(gain + 32 + 8 * g4 + 4 * h);
; #pragma unroll
;       for (int j = 0; j < 4; ++j) { v0[4 * g4 + j] *= inv * ga[j]; v1[4 * g4 + j] *= inv * gb[j]; }
;     }
	v_mul_f32_e32 v0, v66, v66
	v_mul_f32_e32 v72, v67, v67
	v_fmac_f32_e32 v0, v82, v82
	v_fmac_f32_e32 v72, v83, v83
	v_add_f32_e32 v0, v0, v72
	v_mul_f32_e32 v72, v68, v68
	v_fmac_f32_e32 v72, v84, v84
	v_add_f32_e32 v0, v72, v0
	v_mul_f32_e32 v72, v69, v69
	v_fmac_f32_e32 v72, v85, v85
	v_add_f32_e32 v0, v72, v0
	v_mul_f32_e32 v72, v70, v70
	v_fmac_f32_e32 v72, v86, v86
	v_add_f32_e32 v0, v72, v0
	v_mul_f32_e32 v72, v71, v71
	v_fmac_f32_e32 v72, v87, v87
	v_add_f32_e32 v0, v72, v0
	v_mul_f32_e32 v72, v116, v116
	v_fmac_f32_e32 v72, v88, v88
	v_add_f32_e32 v0, v72, v0
	v_mul_f32_e32 v72, v117, v117
	v_fmac_f32_e32 v72, v89, v89
	v_add_f32_e32 v0, v72, v0
	v_mul_f32_e32 v72, v74, v74
	v_fmac_f32_e32 v72, v90, v90
	v_add_f32_e32 v0, v72, v0
	v_mul_f32_e32 v72, v75, v75
	v_fmac_f32_e32 v72, v91, v91
	v_add_f32_e32 v0, v72, v0
	v_pk_mul_f32 v[72:73], v[76:77], v[76:77]
	v_pk_mul_f32 v[80:81], v[78:79], v[78:79]
	v_pk_fma_f32 v[72:73], v[92:93], v[92:93], v[72:73]
	v_pk_fma_f32 v[80:81], v[94:95], v[94:95], v[80:81]
	v_add_f32_e32 v0, v72, v0
	v_add_f32_e32 v0, v73, v0
	v_pk_mul_f32 v[100:101], v[180:181], v[180:181]
	v_add_f32_e32 v0, v80, v0
	v_pk_fma_f32 v[100:101], v[96:97], v[96:97], v[100:101]
	v_add_f32_e32 v0, v81, v0
	v_add_f32_e32 v0, v100, v0
	v_lshlrev_b32_e32 v73, 4, v184
	v_add_f32_e32 v0, v101, v0
	global_load_dwordx4 v[100:103], v73, s[16:17]
	global_load_dwordx4 v[104:107], v73, s[16:17] offset:128
	global_load_dwordx4 v[108:111], v73, s[16:17] offset:32
	global_load_dwordx4 v[112:115], v73, s[16:17] offset:160
	global_load_dwordx4 v[118:121], v73, s[16:17] offset:64
	global_load_dwordx4 v[122:125], v73, s[16:17] offset:192
	global_load_dwordx4 v[186:189], v73, s[16:17] offset:96
	global_load_dwordx4 v[126:129], v73, s[16:17] offset:224
	v_mov_b32_e32 v72, v0
	s_nop 1
	v_permlane32_swap_b32_e32 v0, v72
	v_add_f32_e32 v0, v0, v72
	v_fmamk_f32 v0, v0, 0x3c800000, v213
	v_mul_f32_e32 v72, 0x4b800000, v0
	v_cmp_gt_f32_e32 vcc, s37, v0
	v_lshlrev_b32_e32 v185, 2, v184
	s_cmp_gt_i32 s38, 2
	v_cndmask_b32_e32 v0, v0, v72, vcc
	v_rsq_f32_e32 v0, v0
	s_mov_b64 s[0:1], -1
	v_mul_f32_e32 v72, 0x45800000, v0
	v_cndmask_b32_e32 v0, v0, v72, vcc
	s_waitcnt vmcnt(7)
	v_pk_mul_f32 v[72:73], v[100:101], v[0:1] op_sel_hi:[1,0]
	s_waitcnt vmcnt(6)
	v_pk_mul_f32 v[80:81], v[104:105], v[0:1] op_sel_hi:[1,0]
	v_pk_mul_f32 v[100:101], v[102:103], v[0:1] op_sel_hi:[1,0]
	v_pk_mul_f32 v[102:103], v[106:107], v[0:1] op_sel_hi:[1,0]
	s_waitcnt vmcnt(5)
	v_pk_mul_f32 v[104:105], v[108:109], v[0:1] op_sel_hi:[1,0]
	v_pk_mul_f32 v[108:109], v[110:111], v[0:1] op_sel_hi:[1,0]
	s_waitcnt vmcnt(4)
	v_pk_mul_f32 v[110:111], v[114:115], v[0:1] op_sel_hi:[1,0]
	s_waitcnt vmcnt(1)
	v_mul_f32_e32 v194, v188, v0
	s_waitcnt vmcnt(0)
	v_mov_b32_e32 v188, v129
	v_pk_mul_f32 v[106:107], v[112:113], v[0:1] op_sel_hi:[1,0]
	v_pk_mul_f32 v[112:113], v[118:119], v[0:1] op_sel_hi:[1,0]
	v_pk_mul_f32 v[114:115], v[122:123], v[0:1] op_sel_hi:[1,0]
	v_pk_mul_f32 v[178:179], v[120:121], v[0:1] op_sel_hi:[1,0]
	v_pk_mul_f32 v[190:191], v[124:125], v[0:1] op_sel_hi:[1,0]
	v_pk_mul_f32 v[186:187], v[186:187], v[0:1] op_sel_hi:[1,0]
	v_pk_mul_f32 v[192:193], v[126:127], v[0:1] op_sel_hi:[1,0]
	v_mul_f32_e32 v195, v128, v0
	v_pk_mul_f32 v[118:119], v[82:83], v[72:73]
	v_pk_mul_f32 v[72:73], v[66:67], v[80:81]
	v_pk_mul_f32 v[80:81], v[68:69], v[102:103]
	v_pk_mul_f32 v[102:103], v[116:117], v[110:111]
	v_mul_f32_e32 v110, v96, v194
	v_pk_mul_f32 v[66:67], v[188:189], v[0:1] op_sel_hi:[1,0]
	v_mov_b32_e32 v96, v181
	v_pk_mul_f32 v[120:121], v[84:85], v[100:101]
	v_pk_mul_f32 v[122:123], v[86:87], v[104:105]
	v_pk_mul_f32 v[100:101], v[70:71], v[106:107]
	v_pk_mul_f32 v[124:125], v[88:89], v[108:109]
	v_pk_mul_f32 v[126:127], v[90:91], v[112:113]
	v_pk_mul_f32 v[104:105], v[74:75], v[114:115]
	v_pk_mul_f32 v[128:129], v[92:93], v[178:179]
	v_pk_mul_f32 v[106:107], v[76:77], v[190:191]
	v_pk_mul_f32 v[178:179], v[94:95], v[186:187]
	v_pk_mul_f32 v[108:109], v[78:79], v[192:193]
	v_mul_f32_e32 v112, v180, v195
	v_pk_mul_f32 v[114:115], v[96:97], v[66:67]
	s_cbranch_scc0 .LBB0_561
; DI void head_store(f32x16 v0, f32x16 v1, float rs, int mode, const float* gain, const Params& p, int pos, bf16_t* obase, int ldo, char* stg_wg) {
;     ...
;     } else if (mode == 3) {
;       const int row = pos >> 6, col = pos & 63;
; #pragma unroll
;       for (int g4 = 0; g4 < 2; ++g4) {
;         const f32x4 c0 = *(const f32x4*)(p.tabac + row * 16 + 8 * g4 + 4 * h), s0 = *(const f32x4*)(p.tabas + row * 16 + 8 * g4 + 4 * h);
;         const f32x4 c1 = *(const f32x4*)(p.tabac + col * 16 + 8 * g4 + 4 * h), s1 = *(const f32x4*)(p.tabas + col * 16 + 8 * g4 + 4 * h);
; #pragma unroll
;         for (int j = 0; j < 4; ++j) { const int i = 4 * g4 + j;
;           float x1 = v0[i], x2 = v0[i + 8]; v0[i] = x1 * c0[j] - x2 * s0[j]; v0[i + 8] = x2 * c0[j] + x1 * s0[j];
;           x1 = v1[i]; x2 = v1[i + 8]; v1[i] = x1 * c1[j] - x2 * s1[j]; v1[i + 8] = x2 * c1[j] + x1 * s1[j]; }
;       }
	v_and_b32_e32 v0, 0x1fc0, v182
	v_lshl_add_u64 v[66:67], s[80:81], 0, v[0:1]
	v_lshlrev_b32_e32 v68, 2, v185
	v_mov_b32_e32 v69, v1
	v_lshl_add_u64 v[70:71], v[66:67], 0, v[68:69]
	v_lshl_add_u64 v[66:67], s[82:83], 0, v[0:1]
	v_lshlrev_b32_e32 v0, 6, v182
	v_and_b32_e32 v0, 0xfc0, v0
	v_lshl_add_u64 v[78:79], v[66:67], 0, v[68:69]
	v_lshl_add_u64 v[66:67], s[80:81], 0, v[0:1]
	v_lshl_add_u64 v[88:89], v[66:67], 0, v[68:69]
	v_lshl_add_u64 v[66:67], s[82:83], 0, v[0:1]
	v_lshl_add_u64 v[116:117], v[66:67], 0, v[68:69]
	global_load_dwordx4 v[66:69], v[70:71], off
	global_load_dwordx4 v[74:77], v[78:79], off
	global_load_dwordx4 v[84:87], v[88:89], off
	global_load_dwordx4 v[92:95], v[116:117], off
	v_mov_b32_e32 v111, v115
	v_mov_b32_e32 v113, v114
	s_mov_b64 s[0:1], 0
	s_waitcnt vmcnt(2)
	v_pk_mul_f32 v[82:83], v[126:127], v[74:75]
	v_pk_mul_f32 v[74:75], v[118:119], v[74:75]
	v_pk_fma_f32 v[82:83], v[118:119], v[66:67], v[82:83] neg_lo:[0,0,1] neg_hi:[0,0,1]
	v_pk_fma_f32 v[90:91], v[126:127], v[66:67], v[74:75]
	s_waitcnt vmcnt(0)
	v_pk_mul_f32 v[66:67], v[104:105], v[92:93]
	v_pk_mul_f32 v[74:75], v[72:73], v[92:93]
	v_pk_fma_f32 v[66:67], v[72:73], v[84:85], v[66:67] neg_lo:[0,0,1] neg_hi:[0,0,1]
	v_pk_fma_f32 v[74:75], v[104:105], v[84:85], v[74:75]
	v_pk_mul_f32 v[84:85], v[128:129], v[76:77]
	v_pk_mul_f32 v[76:77], v[120:121], v[76:77]
	v_pk_fma_f32 v[84:85], v[120:121], v[68:69], v[84:85] neg_lo:[0,0,1] neg_hi:[0,0,1]
	v_pk_fma_f32 v[92:93], v[128:129], v[68:69], v[76:77]
	v_pk_mul_f32 v[68:69], v[106:107], v[94:95]
	v_pk_mul_f32 v[76:77], v[80:81], v[94:95]
	global_load_dwordx4 v[94:97], v[70:71], off offset:32
	global_load_dwordx4 v[186:189], v[78:79], off offset:32
	global_load_dwordx4 v[190:193], v[88:89], off offset:32
	global_load_dwordx4 v[194:197], v[116:117], off offset:32
	v_pk_fma_f32 v[68:69], v[80:81], v[86:87], v[68:69] neg_lo:[0,0,1] neg_hi:[0,0,1]
	v_pk_fma_f32 v[76:77], v[106:107], v[86:87], v[76:77]
	s_waitcnt vmcnt(3)
	v_mul_f32_e32 v116, v110, v96
	s_waitcnt vmcnt(2)
	v_pk_mul_f32 v[70:71], v[178:179], v[186:187]
	v_mul_f32_e32 v180, v124, v188
	v_pk_fma_f32 v[86:87], v[122:123], v[94:95], v[70:71] neg_lo:[0,0,1] neg_hi:[0,0,1]
	v_pk_mul_f32 v[70:71], v[122:123], v[186:187]
	s_waitcnt vmcnt(0)
	v_pk_mul_f32 v[78:79], v[100:101], v[194:195]
	v_pk_fma_f32 v[94:95], v[178:179], v[94:95], v[70:71]
	v_pk_mul_f32 v[70:71], v[108:109], v[194:195]
	v_pk_mul_f32 v[88:89], v[110:111], v[188:189]
	v_mov_b32_e32 v194, v115
	v_mov_b32_e32 v195, v125
	v_mov_b32_e32 v188, v97
	v_pk_fma_f32 v[88:89], v[124:125], v[96:97], v[88:89] neg_lo:[0,0,1] neg_hi:[0,0,1]
	v_pk_mul_f32 v[96:97], v[194:195], v[188:189]
	v_pk_fma_f32 v[70:71], v[100:101], v[190:191], v[70:71] neg_lo:[0,0,1] neg_hi:[0,0,1]
	v_mov_b32_e32 v117, v96
	v_mov_b32_e32 v181, v97
	v_pk_fma_f32 v[78:79], v[108:109], v[190:191], v[78:79]
	v_mul_f32_e32 v190, v102, v196
	v_pk_add_f32 v[96:97], v[116:117], v[180:181]
	v_pk_mul_f32 v[116:117], v[112:113], v[196:197]
	v_mov_b32_e32 v180, v114
	v_mov_b32_e32 v181, v103
	v_mov_b32_e32 v196, v193
	v_pk_mul_f32 v[180:181], v[180:181], v[196:197]
	v_mul_f32_e32 v186, v112, v192
	v_mov_b32_e32 v187, v180
	v_mov_b32_e32 v191, v181
	v_pk_fma_f32 v[116:117], v[102:103], v[192:193], v[116:117] neg_lo:[0,0,1] neg_hi:[0,0,1]
	v_pk_add_f32 v[180:181], v[186:187], v[190:191]

; DI float swapsum(float v) { auto rr = __builtin_amdgcn_permlane32_swap(__float_as_uint(v), __float_as_uint(v), false, false); return __uint_as_float(rr[0]) + __uint_as_float(rr[1]); }
; DI void head_store(f32x16 v0, f32x16 v1, float rs, int mode, const float* gain, const Params& p, int pos, bf16_t* obase, int ldo, char* stg_wg) {
;     ...
;   v0 *= rs; v1 *= rs;
;   if (mode) {
;     float ss = 0.f;
; #pragma unroll
;     for (int i = 0; i < 16; ++i) ss += v0[i] * v0[i] + v1[i] * v1[i];
;     ss = swapsum(ss);
;     const float inv = rsqrtf(ss * (1.f / 64.f) + EPSF);
; #pragma unroll
;     for (int g4 = 0; g4 < 4; ++g4) {
;       const f32x4 ga = *(const f32x4*)(gain + 8 * g4 + 4 * h), gb = *(const f32x4*)(gain + 32 + 8 * g4 + 4 * h);
; #pragma unroll
;       for (int j = 0; j < 4; ++j) { v0[4 * g4 + j] *= inv * ga[j]; v1[4 * g4 + j] *= inv * gb[j]; }
;     }
; template <int EPI>
; DI void gemm_phase(char* lds, const Params& p, const GemmDesc g, int layer) {
;     ...
;           const float rs = rsqrtf(p.rstd[(layer & 1) * NTOK + t] * (1.f / DM) + EPSF);
.LBB0_577:
	v_mov_b32_e32 v0, v166
	v_mov_b32 v102, v212
	s_waitcnt vmcnt(4)
	v_fmamk_f32 v0, v0, 0x3a800000, v213
	v_cmp_gt_f32_e32 vcc, s37, v0
	v_mul_f32_e32 v66, 0x4b800000, v0
	v_bfe_u32 v103, v102, 5, 1
	v_cndmask_b32_e32 v0, v0, v66, vcc
	v_rsq_f32_e32 v0, v0
	s_nop 0
	v_mul_f32_e32 v66, 0x45800000, v0
	v_cndmask_b32_e32 v0, v0, v66, vcc
	v_pk_mul_f32 v[64:65], v[64:65], v[0:1] op_sel_hi:[1,0]
	v_pk_mul_f32 v[62:63], v[62:63], v[0:1] op_sel_hi:[1,0]
	v_pk_mul_f32 v[60:61], v[60:61], v[0:1] op_sel_hi:[1,0]
	v_pk_mul_f32 v[58:59], v[58:59], v[0:1] op_sel_hi:[1,0]
	v_pk_mul_f32 v[70:71], v[56:57], v[0:1] op_sel_hi:[1,0]
	v_pk_mul_f32 v[54:55], v[54:55], v[0:1] op_sel_hi:[1,0]
	v_pk_mul_f32 v[52:53], v[52:53], v[0:1] op_sel_hi:[1,0]
	v_pk_mul_f32 v[50:51], v[50:51], v[0:1] op_sel_hi:[1,0]
	v_pk_mul_f32 v[100:101], v[48:49], v[0:1] op_sel_hi:[1,0]
	v_pk_mul_f32 v[46:47], v[46:47], v[0:1] op_sel_hi:[1,0]
	v_pk_mul_f32 v[44:45], v[44:45], v[0:1] op_sel_hi:[1,0]
	v_pk_mul_f32 v[42:43], v[42:43], v[0:1] op_sel_hi:[1,0]
	v_pk_mul_f32 v[96:97], v[40:41], v[0:1] op_sel_hi:[1,0]
	v_pk_mul_f32 v[88:89], v[38:39], v[0:1] op_sel_hi:[1,0]
	v_pk_mul_f32 v[72:73], v[36:37], v[0:1] op_sel_hi:[1,0]
	v_pk_mul_f32 v[74:75], v[34:35], v[0:1] op_sel_hi:[1,0]
	s_and_b64 vcc, exec, s[88:89]
	s_cbranch_vccnz .LBB0_585
	v_mul_f32_e32 v0, v74, v74
	v_mul_f32_e32 v34, v75, v75
	v_fmac_f32_e32 v0, v50, v50
	v_fmac_f32_e32 v34, v51, v51
	v_add_f32_e32 v0, v0, v34
	v_mul_f32_e32 v34, v72, v72
	v_fmac_f32_e32 v34, v52, v52
	v_add_f32_e32 v0, v34, v0
	v_mul_f32_e32 v34, v73, v73
	v_fmac_f32_e32 v34, v53, v53
	v_add_f32_e32 v0, v34, v0
	v_mul_f32_e32 v34, v88, v88
	v_fmac_f32_e32 v34, v54, v54
	v_add_f32_e32 v0, v34, v0
	v_mul_f32_e32 v34, v89, v89
	v_fmac_f32_e32 v34, v55, v55
	v_add_f32_e32 v0, v34, v0
	v_mul_f32_e32 v34, v96, v96
	v_fmac_f32_e32 v34, v70, v70
	v_add_f32_e32 v0, v34, v0
	v_mul_f32_e32 v34, v97, v97
	v_fmac_f32_e32 v34, v71, v71
	v_add_f32_e32 v0, v34, v0
	v_mul_f32_e32 v34, v42, v42
	v_fmac_f32_e32 v34, v58, v58
	v_add_f32_e32 v0, v34, v0
	v_mul_f32_e32 v34, v43, v43
	v_fmac_f32_e32 v34, v59, v59
	v_add_f32_e32 v0, v34, v0
	v_pk_mul_f32 v[34:35], v[44:45], v[44:45]
	v_pk_mul_f32 v[36:37], v[46:47], v[46:47]
	v_pk_fma_f32 v[34:35], v[60:61], v[60:61], v[34:35]
	v_pk_fma_f32 v[36:37], v[62:63], v[62:63], v[36:37]
	v_add_f32_e32 v0, v34, v0
	v_add_f32_e32 v0, v35, v0
	v_pk_mul_f32 v[38:39], v[100:101], v[100:101]
	v_add_f32_e32 v0, v36, v0
	v_pk_fma_f32 v[38:39], v[64:65], v[64:65], v[38:39]
	v_add_f32_e32 v0, v37, v0
	v_add_f32_e32 v0, v38, v0
	v_add_f32_e32 v0, v39, v0
	v_mov_b32_e32 v34, v0
	s_nop 1
	v_permlane32_swap_b32_e32 v0, v34
	v_add_f32_e32 v0, v0, v34
	v_fmamk_f32 v0, v0, 0x3c800000, v213
	v_cmp_gt_f32_e32 vcc, s37, v0
	v_mul_f32_e32 v34, 0x4b800000, v0
	v_lshlrev_b32_e32 v76, 4, v103
	v_cndmask_b32_e32 v0, v0, v34, vcc
	v_rsq_f32_e32 v0, v0
	v_lshlrev_b32_e32 v104, 2, v103
	s_mov_b64 s[68:69], -1
	s_cmp_gt_i32 s97, 2
	v_mul_f32_e32 v34, 0x45800000, v0
	v_cndmask_b32_e32 v0, v0, v34, vcc
	global_load_dwordx4 v[34:37], v76, s[16:17]
	global_load_dwordx4 v[38:41], v76, s[16:17] offset:128
	s_waitcnt vmcnt(1)
	v_pk_mul_f32 v[34:35], v[34:35], v[0:1] op_sel_hi:[1,0]
	v_pk_mul_f32 v[36:37], v[36:37], v[0:1] op_sel_hi:[1,0]
	v_pk_mul_f32 v[56:57], v[50:51], v[34:35]
	s_waitcnt vmcnt(0)
	v_pk_mul_f32 v[34:35], v[38:39], v[0:1] op_sel_hi:[1,0]
	v_pk_mul_f32 v[68:69], v[52:53], v[36:37]
	v_pk_mul_f32 v[36:37], v[40:41], v[0:1] op_sel_hi:[1,0]
	global_load_dwordx4 v[38:41], v76, s[16:17] offset:32
	global_load_dwordx4 v[48:51], v76, s[16:17] offset:160
	v_pk_mul_f32 v[34:35], v[74:75], v[34:35]
	v_pk_mul_f32 v[36:37], v[72:73], v[36:37]
	s_waitcnt vmcnt(1)
	v_pk_mul_f32 v[38:39], v[38:39], v[0:1] op_sel_hi:[1,0]
	v_pk_mul_f32 v[40:41], v[40:41], v[0:1] op_sel_hi:[1,0]
	v_pk_mul_f32 v[78:79], v[54:55], v[38:39]
	s_waitcnt vmcnt(0)
	v_pk_mul_f32 v[38:39], v[48:49], v[0:1] op_sel_hi:[1,0]
	v_pk_mul_f32 v[80:81], v[70:71], v[40:41]
	v_pk_mul_f32 v[40:41], v[50:51], v[0:1] op_sel_hi:[1,0]
	global_load_dwordx4 v[48:51], v76, s[16:17] offset:64
	global_load_dwordx4 v[52:55], v76, s[16:17] offset:192
	v_pk_mul_f32 v[38:39], v[88:89], v[38:39]
	v_pk_mul_f32 v[40:41], v[96:97], v[40:41]
	s_waitcnt vmcnt(1)
	v_pk_mul_f32 v[48:49], v[48:49], v[0:1] op_sel_hi:[1,0]
	s_nop 0
	v_pk_mul_f32 v[90:91], v[58:59], v[48:49]
	s_waitcnt vmcnt(0)
	v_pk_mul_f32 v[48:49], v[52:53], v[0:1] op_sel_hi:[1,0]
	s_nop 0
	v_pk_mul_f32 v[48:49], v[42:43], v[48:49]
	v_pk_mul_f32 v[42:43], v[50:51], v[0:1] op_sel_hi:[1,0]
	s_nop 0
	v_pk_mul_f32 v[92:93], v[60:61], v[42:43]
	v_pk_mul_f32 v[42:43], v[54:55], v[0:1] op_sel_hi:[1,0]
	s_nop 0
	v_pk_mul_f32 v[66:67], v[44:45], v[42:43]
	global_load_dwordx4 v[42:45], v76, s[16:17] offset:96
	global_load_dwordx4 v[50:53], v76, s[16:17] offset:224
	s_waitcnt vmcnt(1)
	v_pk_mul_f32 v[42:43], v[42:43], v[0:1] op_sel_hi:[1,0]
	s_nop 0
	v_pk_mul_f32 v[94:95], v[62:63], v[42:43]
	s_waitcnt vmcnt(0)
	v_pk_mul_f32 v[42:43], v[50:51], v[0:1] op_sel_hi:[1,0]
	s_nop 0
	v_pk_mul_f32 v[76:77], v[46:47], v[42:43]
	v_mul_f32_e32 v42, v44, v0
	v_mul_f32_e32 v82, v64, v42
	v_mul_f32_e32 v42, v52, v0
	v_mov_b32_e32 v44, v53
	v_mul_f32_e32 v84, v100, v42
	v_pk_mul_f32 v[42:43], v[44:45], v[0:1] op_sel_hi:[1,0]
	v_mov_b32_e32 v64, v101
	v_pk_mul_f32 v[86:87], v[64:65], v[42:43]
	s_cbranch_scc0 .LBB0_580
; DI void head_store(f32x16 v0, f32x16 v1, float rs, int mode, const float* gain, const Params& p, int pos, bf16_t* obase, int ldo, char* stg_wg) {
;     ...
;     } else if (mode == 3) {
;       const int row = pos >> 6, col = pos & 63;
; #pragma unroll
;       for (int g4 = 0; g4 < 2; ++g4) {
;         const f32x4 c0 = *(const f32x4*)(p.tabac + row * 16 + 8 * g4 + 4 * h), s0 = *(const f32x4*)(p.tabas + row * 16 + 8 * g4 + 4 * h);
;         const f32x4 c1 = *(const f32x4*)(p.tabac + col * 16 + 8 * g4 + 4 * h), s1 = *(const f32x4*)(p.tabas + col * 16 + 8 * g4 + 4 * h);
; #pragma unroll
;         for (int j = 0; j < 4; ++j) { const int i = 4 * g4 + j;
;           float x1 = v0[i], x2 = v0[i + 8]; v0[i] = x1 * c0[j] - x2 * s0[j]; v0[i + 8] = x2 * c0[j] + x1 * s0[j];
;           x1 = v1[i]; x2 = v1[i + 8]; v1[i] = x1 * c1[j] - x2 * s1[j]; v1[i + 8] = x2 * c1[j] + x1 * s1[j]; }
;       }
	v_and_b32_e32 v0, 0x1fc0, v163
	v_lshl_add_u64 v[42:43], s[80:81], 0, v[0:1]
	v_lshlrev_b32_e32 v44, 2, v104
	v_mov_b32_e32 v45, v1
	v_lshl_add_u64 v[46:47], v[42:43], 0, v[44:45]
	v_lshl_add_u64 v[42:43], s[82:83], 0, v[0:1]
	v_lshlrev_b32_e32 v0, 6, v163
	v_and_b32_e32 v0, 0x7c0, v0
	v_lshl_add_u64 v[70:71], v[42:43], 0, v[44:45]
	v_lshl_add_u64 v[42:43], s[80:81], 0, v[0:1]
	v_lshl_add_u64 v[88:89], v[42:43], 0, v[44:45]
	v_lshl_add_u64 v[42:43], s[82:83], 0, v[0:1]
	v_lshl_add_u64 v[96:97], v[42:43], 0, v[44:45]
	global_load_dwordx4 v[42:45], v[46:47], off
	global_load_dwordx4 v[52:55], v[70:71], off
	global_load_dwordx4 v[60:63], v[88:89], off
	global_load_dwordx4 v[106:109], v[96:97], off
	v_mov_b32_e32 v83, v87
	v_mov_b32_e32 v85, v86
	s_mov_b64 s[68:69], 0
	s_waitcnt vmcnt(2)
	v_pk_mul_f32 v[50:51], v[90:91], v[52:53]
	v_pk_mul_f32 v[52:53], v[56:57], v[52:53]
	v_pk_fma_f32 v[50:51], v[56:57], v[42:43], v[50:51] neg_lo:[0,0,1] neg_hi:[0,0,1]
	v_pk_fma_f32 v[58:59], v[90:91], v[42:43], v[52:53]
	s_waitcnt vmcnt(0)
	v_pk_mul_f32 v[42:43], v[48:49], v[106:107]
	v_pk_mul_f32 v[52:53], v[92:93], v[54:55]
	v_pk_fma_f32 v[74:75], v[34:35], v[60:61], v[42:43] neg_lo:[0,0,1] neg_hi:[0,0,1]
	v_pk_mul_f32 v[42:43], v[34:35], v[106:107]
	v_pk_mul_f32 v[54:55], v[68:69], v[54:55]
	v_pk_fma_f32 v[42:43], v[48:49], v[60:61], v[42:43]
	v_pk_fma_f32 v[52:53], v[68:69], v[44:45], v[52:53] neg_lo:[0,0,1] neg_hi:[0,0,1]
	v_pk_fma_f32 v[60:61], v[92:93], v[44:45], v[54:55]
	v_pk_mul_f32 v[44:45], v[66:67], v[108:109]
	s_nop 0
	v_pk_fma_f32 v[72:73], v[36:37], v[62:63], v[44:45] neg_lo:[0,0,1] neg_hi:[0,0,1]
	v_pk_mul_f32 v[44:45], v[36:37], v[108:109]
	s_nop 0
	v_pk_fma_f32 v[44:45], v[66:67], v[62:63], v[44:45]
	global_load_dwordx4 v[62:65], v[46:47], off offset:32
	global_load_dwordx4 v[106:109], v[70:71], off offset:32
	global_load_dwordx4 v[110:113], v[88:89], off offset:32
	global_load_dwordx4 v[114:117], v[96:97], off offset:32
	s_waitcnt vmcnt(3)
	v_mul_f32_e32 v96, v82, v64
	s_waitcnt vmcnt(2)
	v_pk_mul_f32 v[46:47], v[94:95], v[106:107]
	v_mul_f32_e32 v100, v80, v108
	v_pk_fma_f32 v[54:55], v[78:79], v[62:63], v[46:47] neg_lo:[0,0,1] neg_hi:[0,0,1]
	v_pk_mul_f32 v[46:47], v[78:79], v[106:107]
	v_pk_mul_f32 v[70:71], v[82:83], v[108:109]
	v_pk_fma_f32 v[62:63], v[94:95], v[62:63], v[46:47]
	s_waitcnt vmcnt(0)
	v_pk_mul_f32 v[46:47], v[76:77], v[114:115]
	v_mov_b32_e32 v108, v65
	v_pk_fma_f32 v[88:89], v[38:39], v[110:111], v[46:47] neg_lo:[0,0,1] neg_hi:[0,0,1]
	v_pk_mul_f32 v[46:47], v[38:39], v[114:115]
	v_mov_b32_e32 v114, v87
	v_mov_b32_e32 v115, v81
	v_pk_fma_f32 v[70:71], v[80:81], v[64:65], v[70:71] neg_lo:[0,0,1] neg_hi:[0,0,1]
	v_pk_mul_f32 v[64:65], v[114:115], v[108:109]
	v_pk_fma_f32 v[46:47], v[76:77], v[110:111], v[46:47]
	v_mov_b32_e32 v97, v64
	v_mov_b32_e32 v101, v65
	v_mul_f32_e32 v110, v40, v116
	v_pk_add_f32 v[64:65], v[96:97], v[100:101]
	v_pk_mul_f32 v[96:97], v[84:85], v[116:117]
	v_mov_b32_e32 v100, v86
	v_mov_b32_e32 v101, v41
	v_mov_b32_e32 v116, v113
	v_pk_mul_f32 v[100:101], v[100:101], v[116:117]
	v_mul_f32_e32 v106, v84, v112
	v_mov_b32_e32 v107, v100
	v_mov_b32_e32 v111, v101
	v_pk_fma_f32 v[96:97], v[40:41], v[112:113], v[96:97] neg_lo:[0,0,1] neg_hi:[0,0,1]
	v_pk_add_f32 v[100:101], v[106:107], v[110:111]

; DI unsigned cvtpk(float lo, float hi) { f32x2 v = {lo, hi}; bf16x2_t b = __builtin_convertvector(v, bf16x2_t); return __builtin_bit_cast(unsigned, b); }
; DI float swapsum(float v) { auto rr = __builtin_amdgcn_permlane32_swap(__float_as_uint(v), __float_as_uint(v), false, false); return __uint_as_float(rr[0]) + __uint_as_float(rr[1]); }
; DI void head_store(f32x16 v0, f32x16 v1, float rs, int mode, const float* gain, const Params& p, int pos, bf16_t* obase, int ldo, char* stg_wg) {
;     ...
;   v0 *= rs; v1 *= rs;
;   if (mode) {
;     float ss = 0.f;
; #pragma unroll
;     for (int i = 0; i < 16; ++i) ss += v0[i] * v0[i] + v1[i] * v1[i];
;     ss = swapsum(ss);
;     const float inv = rsqrtf(ss * (1.f / 64.f) + EPSF);
;     ...
; #pragma unroll
;   for (int g4 = 0; g4 < 4; ++g4) {
;     u32x2 w0, w1; w0.x = cvtpk(v0[4 * g4], v0[4 * g4 + 1]); w0.y = cvtpk(v0[4 * g4 + 2], v0[4 * g4 + 3]);
;     w1.x = cvtpk(v1[4 * g4], v1[4 * g4 + 1]); w1.y = cvtpk(v1[4 * g4 + 2], v1[4 * g4 + 3]);
;     *(u32x2*)(stg + r * 128 + ((g4 ^ (r & 7)) << 4) + h * 8) = w0;
;     *(u32x2*)(stg + r * 128 + (((4 + g4) ^ (r & 7)) << 4) + h * 8) = w1;
;   }
; #pragma unroll
;   for (int j = 0; j < 4; ++j) {
;     const int row = (lane >> 3) + 8 * j, ch = lane & 7;
;     const u32x4 w = *(const u32x4*)(stg + row * 128 + ((ch ^ (row & 7)) << 4));
;     *(u32x4*)(obase + (size_t)row * ldo + ch * 8) = w;
;   }
.LBB0_585:
	v_lshlrev_b32_e32 v0, 6, v102
	v_and_b32_e32 v0, 0xfffff000, v0
	v_add_u32_e32 v35, 0x20000, v0
	v_lshlrev_b32_e32 v0, 7, v102
	v_and_b32_e32 v0, 0xf80, v0
	v_and_b32_e32 v40, 7, v102
	v_lshlrev_b32_e32 v36, 3, v103
	v_or3_b32 v41, v35, v0, v36
	v_lshlrev_b32_e32 v0, 4, v40
	v_cvt_pk_bf16_f32 v36, v50, v51
	v_cvt_pk_bf16_f32 v37, v52, v53
	v_or_b32_e32 v40, v41, v0
	ds_write_b64 v40, v[36:37]
	v_xor_b32_e32 v36, 64, v0
	v_cvt_pk_bf16_f32 v38, v74, v75
	v_cvt_pk_bf16_f32 v39, v72, v73
	v_or_b32_e32 v36, v41, v36
	v_xor_b32_e32 v40, 16, v0
	ds_write_b64 v36, v[38:39]
	v_cvt_pk_bf16_f32 v36, v54, v55
	v_cvt_pk_bf16_f32 v37, v70, v71
	v_or_b32_e32 v40, v41, v40
	ds_write_b64 v40, v[36:37]
	v_xor_b32_e32 v36, 0x50, v0
	v_cvt_pk_bf16_f32 v38, v88, v89
	v_cvt_pk_bf16_f32 v39, v96, v97
	v_or_b32_e32 v36, v41, v36
	v_xor_b32_e32 v40, 32, v0
	ds_write_b64 v36, v[38:39]
	v_cvt_pk_bf16_f32 v36, v58, v59
	v_cvt_pk_bf16_f32 v37, v60, v61
	v_or_b32_e32 v40, v41, v40
	ds_write_b64 v40, v[36:37]
	v_xor_b32_e32 v36, 0x60, v0
	v_cvt_pk_bf16_f32 v38, v42, v43
	v_cvt_pk_bf16_f32 v39, v44, v45
	v_or_b32_e32 v36, v41, v36
	v_xor_b32_e32 v40, 48, v0
	v_and_b32_e32 v34, 63, v102
	ds_write_b64 v36, v[38:39]
	v_cvt_pk_bf16_f32 v36, v62, v63
	v_cvt_pk_bf16_f32 v37, v64, v65
	v_or_b32_e32 v40, v41, v40
	ds_write_b64 v40, v[36:37]
	v_xor_b32_e32 v36, 0x70, v0
	v_lshrrev_b32_e32 v40, 3, v34
	v_cvt_pk_bf16_f32 v38, v46, v47
	v_cvt_pk_bf16_f32 v39, v100, v101
	v_or_b32_e32 v36, v41, v36
	v_bitop3_b32 v34, v40, v102, 7 bitop3:0x78
	ds_write_b64 v36, v[38:39]
	v_lshlrev_b32_e32 v34, 4, v34
	v_lshl_add_u64 v[38:39], s[92:93], 0, v[0:1]
	v_lshlrev_b32_e32 v0, 7, v40
	v_or3_b32 v46, v35, v34, v0
	ds_read_b128 v[34:37], v46
	v_mul_u32_u24_e32 v0, 0xf00, v40
	v_lshlrev_b32_e32 v0, 1, v0
	v_lshl_add_u64 v[42:43], v[38:39], 0, v[0:1]
	ds_read_b128 v[38:41], v46 offset:1024
	s_mov_b32 s38, 0xf000
	s_waitcnt lgkmcnt(1)
	global_store_dwordx4 v[42:43], v[34:37], off offset:128
	s_xor_b64 s[68:69], s[88:89], -1
	s_nop 0
	v_add_co_u32_e32 v34, vcc, s38, v42
	s_mov_b32 s38, 0x1e000
	s_nop 0
	v_addc_co_u32_e32 v35, vcc, 0, v43, vcc
	s_waitcnt lgkmcnt(0)
	global_store_dwordx4 v[34:35], v[38:41], off offset:128
	ds_read_b128 v[34:37], v46 offset:2048
	ds_read_b128 v[38:41], v46 offset:3072
	v_add_co_u32_e32 v44, vcc, s38, v42
	s_mov_b32 s38, 0x2d000
	s_nop 0
	v_addc_co_u32_e32 v45, vcc, 0, v43, vcc
	s_waitcnt lgkmcnt(1)
	global_store_dwordx4 v[44:45], v[34:37], off offset:128
	s_nop 1
	v_add_co_u32_e32 v34, vcc, s38, v42
	s_nop 1
	v_addc_co_u32_e32 v35, vcc, 0, v43, vcc
	s_waitcnt lgkmcnt(0)
	global_store_dwordx4 v[34:35], v[38:41], off offset:128
	v_mov_b32_e32 v0, v214
	v_mov_b32 v68, v212
	s_waitcnt vmcnt(4)
	v_fmamk_f32 v0, v0, 0x3a800000, v213
	v_mul_f32_e32 v34, 0x4b800000, v0
	v_cmp_gt_f32_e32 vcc, s37, v0
	v_bfe_u32 v69, v68, 5, 1
	s_nop 0
	v_cndmask_b32_e32 v0, v0, v34, vcc
	v_rsq_f32_e32 v0, v0
	s_nop 0
	v_mul_f32_e32 v34, 0x45800000, v0
	v_cndmask_b32_e32 v0, v0, v34, vcc
	v_pk_mul_f32 v[32:33], v[32:33], v[0:1] op_sel_hi:[1,0]
	v_pk_mul_f32 v[30:31], v[30:31], v[0:1] op_sel_hi:[1,0]
	v_pk_mul_f32 v[28:29], v[28:29], v[0:1] op_sel_hi:[1,0]
	v_pk_mul_f32 v[26:27], v[26:27], v[0:1] op_sel_hi:[1,0]
	v_pk_mul_f32 v[54:55], v[24:25], v[0:1] op_sel_hi:[1,0]
	v_pk_mul_f32 v[46:47], v[22:23], v[0:1] op_sel_hi:[1,0]
	v_pk_mul_f32 v[20:21], v[20:21], v[0:1] op_sel_hi:[1,0]
	v_pk_mul_f32 v[18:19], v[18:19], v[0:1] op_sel_hi:[1,0]
	v_pk_mul_f32 v[66:67], v[16:17], v[0:1] op_sel_hi:[1,0]
	v_pk_mul_f32 v[50:51], v[14:15], v[0:1] op_sel_hi:[1,0]
	v_pk_mul_f32 v[24:25], v[12:13], v[0:1] op_sel_hi:[1,0]
	v_pk_mul_f32 v[36:37], v[10:11], v[0:1] op_sel_hi:[1,0]
	v_pk_mul_f32 v[64:65], v[8:9], v[0:1] op_sel_hi:[1,0]
	v_pk_mul_f32 v[62:63], v[6:7], v[0:1] op_sel_hi:[1,0]
	v_pk_mul_f32 v[58:59], v[4:5], v[0:1] op_sel_hi:[1,0]
	s_andn2_b64 vcc, exec, s[68:69]
	v_pk_mul_f32 v[60:61], v[2:3], v[0:1] op_sel_hi:[1,0]
	s_cbranch_vccnz .LBB0_515
	v_mul_f32_e32 v0, v60, v60
	v_mul_f32_e32 v2, v61, v61
	v_fmac_f32_e32 v0, v18, v18
	v_fmac_f32_e32 v2, v19, v19
	v_add_f32_e32 v0, v0, v2
	v_mul_f32_e32 v2, v58, v58
	v_fmac_f32_e32 v2, v20, v20
	v_add_f32_e32 v0, v2, v0
	v_mul_f32_e32 v2, v59, v59
	v_fmac_f32_e32 v2, v21, v21
	v_add_f32_e32 v0, v2, v0
	v_mul_f32_e32 v2, v62, v62
	v_fmac_f32_e32 v2, v46, v46
	v_add_f32_e32 v0, v2, v0
	v_mul_f32_e32 v2, v63, v63
	v_fmac_f32_e32 v2, v47, v47
	v_add_f32_e32 v0, v2, v0
	v_mul_f32_e32 v2, v64, v64
	v_fmac_f32_e32 v2, v54, v54
	v_add_f32_e32 v0, v2, v0
	v_mul_f32_e32 v2, v65, v65
	v_fmac_f32_e32 v2, v55, v55
	v_add_f32_e32 v0, v2, v0
	v_mul_f32_e32 v2, v36, v36
	v_fmac_f32_e32 v2, v26, v26
	v_add_f32_e32 v0, v2, v0
	v_mul_f32_e32 v2, v37, v37
	v_fmac_f32_e32 v2, v27, v27
	v_add_f32_e32 v0, v2, v0
	v_pk_mul_f32 v[2:3], v[24:25], v[24:25]
	v_pk_mul_f32 v[4:5], v[50:51], v[50:51]
	v_pk_fma_f32 v[2:3], v[28:29], v[28:29], v[2:3]
	v_pk_fma_f32 v[4:5], v[30:31], v[30:31], v[4:5]
	v_add_f32_e32 v0, v2, v0
	v_add_f32_e32 v0, v3, v0
	v_pk_mul_f32 v[6:7], v[66:67], v[66:67]
	v_add_f32_e32 v0, v4, v0
	v_pk_fma_f32 v[6:7], v[32:33], v[32:33], v[6:7]
	v_add_f32_e32 v0, v5, v0
	v_add_f32_e32 v0, v6, v0
	v_add_f32_e32 v0, v7, v0
	v_mov_b32_e32 v2, v0
	s_nop 1
	v_permlane32_swap_b32_e32 v0, v2
	v_add_f32_e32 v0, v0, v2
	v_fmamk_f32 v0, v0, 0x3c800000, v213
	v_cmp_gt_f32_e32 vcc, s37, v0
	v_mul_f32_e32 v2, 0x4b800000, v0
	v_lshlrev_b32_e32 v22, 4, v69
	v_cndmask_b32_e32 v0, v0, v2, vcc
	v_rsq_f32_e32 v0, v0
	v_lshlrev_b32_e32 v70, 2, v69
	s_cmp_gt_i32 s97, 2
	v_mul_f32_e32 v2, 0x45800000, v0
	v_cndmask_b32_e32 v0, v0, v2, vcc
	global_load_dwordx4 v[2:5], v22, s[16:17]
	global_load_dwordx4 v[6:9], v22, s[16:17] offset:128
	s_waitcnt vmcnt(1)
; DI void head_store(f32x16 v0, f32x16 v1, float rs, int mode, const float* gain, const Params& p, int pos, bf16_t* obase, int ldo, char* stg_wg) {
;     ...
;     for (int g4 = 0; g4 < 4; ++g4) {
;       const f32x4 ga = *(const f32x4*)(gain + 8 * g4 + 4 * h), gb = *(const f32x4*)(gain + 32 + 8 * g4 + 4 * h);
; #pragma unroll
;       for (int j = 0; j < 4; ++j) { v0[4 * g4 + j] *= inv * ga[j]; v1[4 * g4 + j] *= inv * gb[j]; }
;     }
;     if (mode == 2) {
; #pragma unroll
;       for (int g4 = 0; g4 < 4; ++g4) {
;         const f32x4 c = *(const f32x4*)(p.tab1c + pos * 32 + 8 * g4 + 4 * h), s = *(const f32x4*)(p.tab1s + pos * 32 + 8 * g4 + 4 * h);
; #pragma unroll
;         for (int j = 0; j < 4; ++j) { const int i = 4 * g4 + j; const float x1 = v0[i], x2 = v1[i]; v0[i] = x1 * c[j] - x2 * s[j]; v1[i] = x2 * c[j] + x1 * s[j]; }
;       }
;     } else if (mode == 3) {
;       const int row = pos >> 6, col = pos & 63;
; #pragma unroll
;       for (int g4 = 0; g4 < 2; ++g4) {
;         const f32x4 c0 = *(const f32x4*)(p.tabac + row * 16 + 8 * g4 + 4 * h), s0 = *(const f32x4*)(p.tabas + row * 16 + 8 * g4 + 4 * h);
;         const f32x4 c1 = *(const f32x4*)(p.tabac + col * 16 + 8 * g4 + 4 * h), s1 = *(const f32x4*)(p.tabas + col * 16 + 8 * g4 + 4 * h);
; #pragma unroll
;         for (int j = 0; j < 4; ++j) { const int i = 4 * g4 + j;
;           float x1 = v0[i], x2 = v0[i + 8]; v0[i] = x1 * c0[j] - x2 * s0[j]; v0[i + 8] = x2 * c0[j] + x1 * s0[j];
;           x1 = v1[i]; x2 = v1[i + 8]; v1[i] = x1 * c1[j] - x2 * s1[j]; v1[i + 8] = x2 * c1[j] + x1 * s1[j]; }
;       }
	v_pk_mul_f32 v[2:3], v[2:3], v[0:1] op_sel_hi:[1,0]
	v_pk_mul_f32 v[4:5], v[4:5], v[0:1] op_sel_hi:[1,0]
	v_pk_mul_f32 v[12:13], v[18:19], v[2:3]
	s_waitcnt vmcnt(0)
	v_pk_mul_f32 v[2:3], v[6:7], v[0:1] op_sel_hi:[1,0]
	v_pk_mul_f32 v[16:17], v[20:21], v[4:5]
	v_pk_mul_f32 v[4:5], v[8:9], v[0:1] op_sel_hi:[1,0]
	global_load_dwordx4 v[6:9], v22, s[16:17] offset:32
	global_load_dwordx4 v[18:21], v22, s[16:17] offset:160
	v_pk_mul_f32 v[2:3], v[60:61], v[2:3]
	v_pk_mul_f32 v[4:5], v[58:59], v[4:5]
	s_waitcnt vmcnt(1)
	v_pk_mul_f32 v[6:7], v[6:7], v[0:1] op_sel_hi:[1,0]
	v_pk_mul_f32 v[8:9], v[8:9], v[0:1] op_sel_hi:[1,0]
	v_pk_mul_f32 v[34:35], v[46:47], v[6:7]
	s_waitcnt vmcnt(0)
	v_pk_mul_f32 v[6:7], v[18:19], v[0:1] op_sel_hi:[1,0]
	v_pk_mul_f32 v[38:39], v[54:55], v[8:9]
	v_pk_mul_f32 v[8:9], v[20:21], v[0:1] op_sel_hi:[1,0]
	global_load_dwordx4 v[18:21], v22, s[16:17] offset:64
	global_load_dwordx4 v[40:43], v22, s[16:17] offset:192
	v_pk_mul_f32 v[6:7], v[62:63], v[6:7]
	v_pk_mul_f32 v[8:9], v[64:65], v[8:9]
	s_waitcnt vmcnt(1)
	v_pk_mul_f32 v[14:15], v[20:21], v[0:1] op_sel_hi:[1,0]
	s_nop 0
	v_pk_mul_f32 v[52:53], v[28:29], v[14:15]
	s_waitcnt vmcnt(0)
	v_pk_mul_f32 v[14:15], v[42:43], v[0:1] op_sel_hi:[1,0]
	v_pk_mul_f32 v[10:11], v[18:19], v[0:1] op_sel_hi:[1,0]
	v_pk_mul_f32 v[14:15], v[24:25], v[14:15]
	global_load_dwordx4 v[18:21], v22, s[16:17] offset:96
	s_nop 0
	global_load_dwordx4 v[22:25], v22, s[16:17] offset:224
	v_pk_mul_f32 v[48:49], v[26:27], v[10:11]
	v_pk_mul_f32 v[10:11], v[40:41], v[0:1] op_sel_hi:[1,0]
	s_mov_b64 s[16:17], -1
	v_pk_mul_f32 v[10:11], v[36:37], v[10:11]
	s_waitcnt vmcnt(1)
	v_pk_mul_f32 v[18:19], v[18:19], v[0:1] op_sel_hi:[1,0]
	s_nop 0
	v_pk_mul_f32 v[56:57], v[30:31], v[18:19]
	s_waitcnt vmcnt(0)
	v_pk_mul_f32 v[18:19], v[22:23], v[0:1] op_sel_hi:[1,0]
	s_nop 0
	v_pk_mul_f32 v[22:23], v[50:51], v[18:19]
	v_mul_f32_e32 v18, v20, v0
	v_mul_f32_e32 v40, v32, v18
	v_mul_f32_e32 v18, v24, v0
	v_mov_b32_e32 v20, v25
	v_mul_f32_e32 v42, v66, v18
	v_pk_mul_f32 v[18:19], v[20:21], v[0:1] op_sel_hi:[1,0]
	v_mov_b32_e32 v32, v67
	v_pk_mul_f32 v[44:45], v[32:33], v[18:19]
	s_cbranch_scc0 .LBB0_588
	v_and_b32_e32 v0, 0x1fc0, v182
	v_lshl_add_u64 v[18:19], s[80:81], 0, v[0:1]
	v_lshlrev_b32_e32 v20, 2, v70
	v_mov_b32_e32 v21, v1
	v_lshl_add_u64 v[46:47], v[18:19], 0, v[20:21]
	v_lshl_add_u64 v[18:19], s[82:83], 0, v[0:1]
	v_lshlrev_b32_e32 v0, 6, v182
	v_and_b32_e32 v0, 0xfc0, v0
	v_lshl_add_u64 v[50:51], v[18:19], 0, v[20:21]
	v_lshl_add_u64 v[18:19], s[80:81], 0, v[0:1]
	v_lshl_add_u64 v[54:55], v[18:19], 0, v[20:21]
	v_lshl_add_u64 v[18:19], s[82:83], 0, v[0:1]
	v_lshl_add_u64 v[66:67], v[18:19], 0, v[20:21]
	global_load_dwordx4 v[26:29], v[46:47], off
	global_load_dwordx4 v[30:33], v[50:51], off
	global_load_dwordx4 v[62:65], v[54:55], off
	global_load_dwordx4 v[72:75], v[66:67], off
	v_mov_b32_e32 v41, v45
	v_mov_b32_e32 v82, v45
	v_mov_b32_e32 v83, v39
	v_mov_b32_e32 v43, v44
	s_mov_b64 s[16:17], 0
	s_waitcnt vmcnt(2)
	v_pk_mul_f32 v[18:19], v[48:49], v[30:31]
	v_pk_mul_f32 v[20:21], v[12:13], v[30:31]
	v_pk_fma_f32 v[18:19], v[12:13], v[26:27], v[18:19] neg_lo:[0,0,1] neg_hi:[0,0,1]
	v_pk_fma_f32 v[26:27], v[48:49], v[26:27], v[20:21]
	s_waitcnt vmcnt(0)
	v_pk_mul_f32 v[20:21], v[10:11], v[72:73]
	v_pk_mul_f32 v[24:25], v[16:17], v[32:33]
	v_pk_fma_f32 v[60:61], v[2:3], v[62:63], v[20:21] neg_lo:[0,0,1] neg_hi:[0,0,1]
	v_pk_mul_f32 v[20:21], v[2:3], v[72:73]
	s_nop 0
	v_pk_fma_f32 v[36:37], v[10:11], v[62:63], v[20:21]
	v_pk_mul_f32 v[20:21], v[52:53], v[32:33]
	s_nop 0
	v_pk_fma_f32 v[20:21], v[16:17], v[28:29], v[20:21] neg_lo:[0,0,1] neg_hi:[0,0,1]
	v_pk_fma_f32 v[28:29], v[52:53], v[28:29], v[24:25]
	v_pk_mul_f32 v[24:25], v[14:15], v[74:75]
	s_nop 0
	v_pk_fma_f32 v[58:59], v[4:5], v[64:65], v[24:25] neg_lo:[0,0,1] neg_hi:[0,0,1]
	v_pk_mul_f32 v[24:25], v[4:5], v[74:75]
	s_nop 0
	v_pk_fma_f32 v[24:25], v[14:15], v[64:65], v[24:25]
	global_load_dwordx4 v[30:33], v[46:47], off offset:32
	global_load_dwordx4 v[62:65], v[50:51], off offset:32
	global_load_dwordx4 v[72:75], v[54:55], off offset:32
	global_load_dwordx4 v[76:79], v[66:67], off offset:32
	s_waitcnt vmcnt(3)
	v_mul_f32_e32 v66, v40, v32
	s_waitcnt vmcnt(2)
	v_pk_mul_f32 v[46:47], v[56:57], v[62:63]
	v_pk_mul_f32 v[50:51], v[34:35], v[62:63]
	v_pk_fma_f32 v[46:47], v[34:35], v[30:31], v[46:47] neg_lo:[0,0,1] neg_hi:[0,0,1]
	v_pk_fma_f32 v[30:31], v[56:57], v[30:31], v[50:51]
	s_waitcnt vmcnt(0)
	v_pk_mul_f32 v[50:51], v[22:23], v[76:77]
	v_pk_mul_f32 v[54:55], v[40:41], v[64:65]
	v_pk_fma_f32 v[62:63], v[6:7], v[72:73], v[50:51] neg_lo:[0,0,1] neg_hi:[0,0,1]
	v_pk_mul_f32 v[50:51], v[6:7], v[76:77]
	v_pk_fma_f32 v[54:55], v[38:39], v[32:33], v[54:55] neg_lo:[0,0,1] neg_hi:[0,0,1]
	v_pk_fma_f32 v[50:51], v[22:23], v[72:73], v[50:51]
	v_mul_f32_e32 v72, v38, v64
	v_mov_b32_e32 v64, v33
	v_pk_mul_f32 v[32:33], v[82:83], v[64:65]
	v_mul_f32_e32 v80, v8, v78
	v_mov_b32_e32 v67, v32
	v_mov_b32_e32 v73, v33
	v_pk_add_f32 v[32:33], v[66:67], v[72:73]
	v_pk_mul_f32 v[64:65], v[42:43], v[78:79]
	v_mov_b32_e32 v66, v44
	v_mov_b32_e32 v67, v9
	v_mov_b32_e32 v78, v75
	v_pk_mul_f32 v[66:67], v[66:67], v[78:79]
	v_mul_f32_e32 v76, v42, v74
	v_mov_b32_e32 v77, v66
	v_mov_b32_e32 v81, v67
	v_pk_fma_f32 v[64:65], v[8:9], v[74:75], v[64:65] neg_lo:[0,0,1] neg_hi:[0,0,1]
	v_pk_add_f32 v[66:67], v[76:77], v[80:81]
